# scan: decay factored over groups of 4 steps (producer pre-scales kk/r/kka/kd by the in-group cumulative decay, consumer rescales state once per 4 steps); producer fully hand-written with thread = 4 co
# speedup vs baseline: 1.0331x; 1.0171x over previous
.LBB0_56:
	s_and_b64 s[4:5], s[42:43], exec
	s_mov_b32 s4, 0x1caf0000
	s_cselect_b32 s4, s4, 0x14af0000
	s_add_u32 s4, s30, s4
	s_addc_u32 s5, s31, 0
	s_lshl_b32 s6, s37, 1
	v_lshl_add_u32 v0, s64, 4, v58
	s_add_u32 s4, s4, s6
	s_addc_u32 s5, s5, 0
	v_ashrrev_i32_e32 v1, 31, v0
	s_waitcnt lgkmcnt(0)
	s_barrier
	v_lshl_add_u64 v[0:1], v[0:1], 1, s[4:5]
	s_and_b64 s[4:5], s[42:43], exec
	s_movk_i32 s4, 0x4000
	s_mov_b32 s28, 0
	s_cselect_b32 s85, 0, -1
	s_cselect_b32 s84, s4, 0xffffc000
	s_waitcnt vmcnt(0)
	v_mov_b32_e32 v6, 0
	v_mov_b32_e32 v4, v78
	v_mov_b32_e32 v5, v15
	v_mov_b32_e32 v7, 0
	v_mov_b32_e32 v8, 0
	v_mov_b32_e32 v9, 0
	v_lshlrev_b32_e32 v74, 4, v58
	v_add_u32_e32 v74, 0x22000, v74
	v_mov_b32_e32 v10, v59
	v_mov_b32_e32 v11, v74
	ds_read_b128 v[66:69], v11 offset:0
	ds_read_b128 v[20:23], v10 offset:256
	ds_read_b128 v[28:31], v10 offset:768
	ds_read_b128 v[24:27], v10 offset:512
	ds_read_b128 v[36:39], v10 offset:1280
	ds_read_b128 v[44:47], v10 offset:1792
	ds_read_b128 v[40:43], v10 offset:1536
.Lscan_cons_chunk:
	v_cndmask_b32_e64 v2, v4, v5, s[42:43]
	v_add_lshl_u32 v2, v2, s80, 10
	v_mov_b32_e32 v3, v180
	s_add_i32 s28, s28, 0x10000
	v_lshl_add_u64 v[2:3], v[0:1], 0, v[2:3]
	v_add_u32_e32 v5, 64, v5
	v_subrev_u32_e32 v4, 64, v4
	s_waitcnt lgkmcnt(3)
	v_fma_mix_f32 v12, v6, v20, v180 op_sel_hi:[0,1,0]
	v_fma_mix_f32 v12, v7, v20, v12 op_sel:[0,1,0] op_sel_hi:[0,1,0]
	v_fma_mix_f32 v12, v8, v21, v12 op_sel_hi:[0,1,0]
	v_fma_mix_f32 v12, v9, v21, v12 op_sel:[0,1,0] op_sel_hi:[0,1,0]
	s_nop 1
	v_add_f32_dpp v12, v12, v12 row_ror:1 row_mask:0xf bank_mask:0xf bound_ctrl:1
	s_nop 1
	v_add_f32_dpp v12, v12, v12 row_ror:2 row_mask:0xf bank_mask:0xf bound_ctrl:1
	v_pk_fma_f32 v[48:49], v[28:29], v[66:67], v[6:7] op_sel_hi:[1,0,1]
	v_pk_fma_f32 v[50:51], v[30:31], v[66:67], v[8:9] op_sel_hi:[1,0,1]
	v_add_f32_dpp v12, v12, v12 row_ror:4 row_mask:0xf bank_mask:0xf bound_ctrl:1
	s_nop 1
	v_add_f32_dpp v12, v12, v12 row_ror:8 row_mask:0xf bank_mask:0xf bound_ctrl:1
	v_pk_fma_f32 v[6:7], v[24:25], v[12:13], v[48:49] op_sel_hi:[1,0,1] neg_lo:[1,0,0] neg_hi:[1,0,0]
	v_pk_fma_f32 v[8:9], v[26:27], v[12:13], v[50:51] op_sel_hi:[1,0,1] neg_lo:[1,0,0] neg_hi:[1,0,0]
	ds_read_b128 v[88:91], v10 offset:2304
	ds_read_b128 v[96:99], v10 offset:2816
	ds_read_b128 v[92:95], v10 offset:2560
	s_waitcnt lgkmcnt(3)
	v_fma_mix_f32 v12, v6, v36, v180 op_sel_hi:[0,1,0]
	v_fma_mix_f32 v12, v7, v36, v12 op_sel:[0,1,0] op_sel_hi:[0,1,0]
	v_fma_mix_f32 v12, v8, v37, v12 op_sel_hi:[0,1,0]
	v_fma_mix_f32 v12, v9, v37, v12 op_sel:[0,1,0] op_sel_hi:[0,1,0]
	v_fma_mix_f32 v52, v6, v22, v180 op_sel_hi:[0,1,0]
	v_fma_mix_f32 v52, v7, v22, v52 op_sel:[0,1,0] op_sel_hi:[0,1,0]
	v_add_f32_dpp v12, v12, v12 row_ror:1 row_mask:0xf bank_mask:0xf bound_ctrl:1
	v_fma_mix_f32 v52, v8, v23, v52 op_sel_hi:[0,1,0]
	v_fma_mix_f32 v52, v9, v23, v52 op_sel:[0,1,0] op_sel_hi:[0,1,0]
	v_add_f32_dpp v12, v12, v12 row_ror:2 row_mask:0xf bank_mask:0xf bound_ctrl:1
	v_pk_fma_f32 v[48:49], v[44:45], v[66:67], v[6:7] op_sel:[0,1,0]
	v_pk_fma_f32 v[50:51], v[46:47], v[66:67], v[8:9] op_sel:[0,1,0]
	v_add_f32_dpp v12, v12, v12 row_ror:4 row_mask:0xf bank_mask:0xf bound_ctrl:1
	s_nop 1
	v_add_f32_dpp v12, v12, v12 row_ror:8 row_mask:0xf bank_mask:0xf bound_ctrl:1
	v_pk_fma_f32 v[6:7], v[40:41], v[12:13], v[48:49] op_sel_hi:[1,0,1] neg_lo:[1,0,0] neg_hi:[1,0,0]
	v_pk_fma_f32 v[8:9], v[42:43], v[12:13], v[50:51] op_sel_hi:[1,0,1] neg_lo:[1,0,0] neg_hi:[1,0,0]
	ds_read_b128 v[110:113], v10 offset:3328
	ds_read_b128 v[106:109], v10 offset:3072
	ds_read_b128 v[118:121], v10 offset:3840
	ds_read_b128 v[114:117], v10 offset:3584
	ds_read_b128 v[70:73], v11 offset:256
	s_waitcnt lgkmcnt(5)
	v_fma_mix_f32 v12, v6, v88, v180 op_sel_hi:[0,1,0]
	v_fma_mix_f32 v12, v7, v88, v12 op_sel:[0,1,0] op_sel_hi:[0,1,0]
	v_fma_mix_f32 v12, v8, v89, v12 op_sel_hi:[0,1,0]
	v_fma_mix_f32 v12, v9, v89, v12 op_sel:[0,1,0] op_sel_hi:[0,1,0]
	v_fma_mix_f32 v53, v6, v38, v180 op_sel_hi:[0,1,0]
	v_fma_mix_f32 v53, v7, v38, v53 op_sel:[0,1,0] op_sel_hi:[0,1,0]
	v_add_f32_dpp v12, v12, v12 row_ror:1 row_mask:0xf bank_mask:0xf bound_ctrl:1
	v_fma_mix_f32 v53, v8, v39, v53 op_sel_hi:[0,1,0]
	v_fma_mix_f32 v53, v9, v39, v53 op_sel:[0,1,0] op_sel_hi:[0,1,0]
	v_add_f32_dpp v12, v12, v12 row_ror:2 row_mask:0xf bank_mask:0xf bound_ctrl:1
	v_pk_fma_f32 v[48:49], v[96:97], v[68:69], v[6:7] op_sel_hi:[1,0,1]
	v_pk_fma_f32 v[50:51], v[98:99], v[68:69], v[8:9] op_sel_hi:[1,0,1]
	v_add_f32_dpp v12, v12, v12 row_ror:4 row_mask:0xf bank_mask:0xf bound_ctrl:1
	s_nop 1
	v_add_f32_dpp v12, v12, v12 row_ror:8 row_mask:0xf bank_mask:0xf bound_ctrl:1
	v_pk_fma_f32 v[6:7], v[92:93], v[12:13], v[48:49] op_sel_hi:[1,0,1] neg_lo:[1,0,0] neg_hi:[1,0,0]
	v_pk_fma_f32 v[8:9], v[94:95], v[12:13], v[50:51] op_sel_hi:[1,0,1] neg_lo:[1,0,0] neg_hi:[1,0,0]
	ds_read_b128 v[20:23], v10 offset:4352
	ds_read_b128 v[28:31], v10 offset:4864
	ds_read_b128 v[24:27], v10 offset:4608
	s_waitcnt lgkmcnt(4)
	v_fma_mix_f32 v12, v6, v110, v180 op_sel_hi:[0,1,0]
	v_fma_mix_f32 v12, v7, v110, v12 op_sel:[0,1,0] op_sel_hi:[0,1,0]
	v_fma_mix_f32 v12, v8, v111, v12 op_sel_hi:[0,1,0]
	v_fma_mix_f32 v12, v9, v111, v12 op_sel:[0,1,0] op_sel_hi:[0,1,0]
	v_fma_mix_f32 v54, v6, v90, v180 op_sel_hi:[0,1,0]
	v_fma_mix_f32 v54, v7, v90, v54 op_sel:[0,1,0] op_sel_hi:[0,1,0]
	v_add_f32_dpp v12, v12, v12 row_ror:1 row_mask:0xf bank_mask:0xf bound_ctrl:1
	v_fma_mix_f32 v54, v8, v91, v54 op_sel_hi:[0,1,0]
	v_fma_mix_f32 v54, v9, v91, v54 op_sel:[0,1,0] op_sel_hi:[0,1,0]
	v_add_f32_dpp v12, v12, v12 row_ror:2 row_mask:0xf bank_mask:0xf bound_ctrl:1
	v_pk_fma_f32 v[48:49], v[118:119], v[68:69], v[6:7] op_sel:[0,1,0]
	v_pk_fma_f32 v[50:51], v[120:121], v[68:69], v[8:9] op_sel:[0,1,0]
	v_add_f32_dpp v12, v12, v12 row_ror:4 row_mask:0xf bank_mask:0xf bound_ctrl:1
	s_nop 1
	v_add_f32_dpp v12, v12, v12 row_ror:8 row_mask:0xf bank_mask:0xf bound_ctrl:1
	v_pk_fma_f32 v[6:7], v[114:115], v[12:13], v[48:49] op_sel_hi:[1,0,1] neg_lo:[1,0,0] neg_hi:[1,0,0]
	v_pk_fma_f32 v[8:9], v[116:117], v[12:13], v[50:51] op_sel_hi:[1,0,1] neg_lo:[1,0,0] neg_hi:[1,0,0]
	v_pk_mul_f32 v[6:7], v[6:7], v[106:107]
	v_pk_mul_f32 v[8:9], v[8:9], v[108:109]
	ds_read_b128 v[36:39], v10 offset:5376
	ds_read_b128 v[44:47], v10 offset:5888
	ds_read_b128 v[40:43], v10 offset:5632
	s_waitcnt lgkmcnt(3)
	v_fma_mix_f32 v12, v6, v20, v180 op_sel_hi:[0,1,0]
	v_fma_mix_f32 v12, v7, v20, v12 op_sel:[0,1,0] op_sel_hi:[0,1,0]
	v_fma_mix_f32 v12, v8, v21, v12 op_sel_hi:[0,1,0]
	v_fma_mix_f32 v12, v9, v21, v12 op_sel:[0,1,0] op_sel_hi:[0,1,0]
	v_fma_mix_f32 v55, v6, v112, v180 op_sel_hi:[0,1,0]
	v_fma_mix_f32 v55, v7, v112, v55 op_sel:[0,1,0] op_sel_hi:[0,1,0]
	v_add_f32_dpp v12, v12, v12 row_ror:1 row_mask:0xf bank_mask:0xf bound_ctrl:1
	v_fma_mix_f32 v55, v8, v113, v55 op_sel_hi:[0,1,0]
	v_fma_mix_f32 v55, v9, v113, v55 op_sel:[0,1,0] op_sel_hi:[0,1,0]
	v_add_f32_dpp v12, v12, v12 row_ror:2 row_mask:0xf bank_mask:0xf bound_ctrl:1
	v_pk_fma_f32 v[48:49], v[28:29], v[70:71], v[6:7] op_sel_hi:[1,0,1]
	v_pk_fma_f32 v[50:51], v[30:31], v[70:71], v[8:9] op_sel_hi:[1,0,1]
	v_add_f32_dpp v12, v12, v12 row_ror:4 row_mask:0xf bank_mask:0xf bound_ctrl:1
	s_nop 1
	v_add_f32_dpp v12, v12, v12 row_ror:8 row_mask:0xf bank_mask:0xf bound_ctrl:1
	v_pk_fma_f32 v[6:7], v[24:25], v[12:13], v[48:49] op_sel_hi:[1,0,1] neg_lo:[1,0,0] neg_hi:[1,0,0]
	v_pk_fma_f32 v[8:9], v[26:27], v[12:13], v[50:51] op_sel_hi:[1,0,1] neg_lo:[1,0,0] neg_hi:[1,0,0]
	ds_read_b128 v[88:91], v10 offset:6400
	ds_read_b128 v[96:99], v10 offset:6912
	ds_read_b128 v[92:95], v10 offset:6656
	s_waitcnt lgkmcnt(3)
	v_fma_mix_f32 v12, v6, v36, v180 op_sel_hi:[0,1,0]
	v_fma_mix_f32 v12, v7, v36, v12 op_sel:[0,1,0] op_sel_hi:[0,1,0]
	v_fma_mix_f32 v12, v8, v37, v12 op_sel_hi:[0,1,0]
	v_fma_mix_f32 v12, v9, v37, v12 op_sel:[0,1,0] op_sel_hi:[0,1,0]
	v_fma_mix_f32 v56, v6, v22, v180 op_sel_hi:[0,1,0]
	v_fma_mix_f32 v56, v7, v22, v56 op_sel:[0,1,0] op_sel_hi:[0,1,0]
	v_add_f32_dpp v12, v12, v12 row_ror:1 row_mask:0xf bank_mask:0xf bound_ctrl:1
	v_fma_mix_f32 v56, v8, v23, v56 op_sel_hi:[0,1,0]
	v_fma_mix_f32 v56, v9, v23, v56 op_sel:[0,1,0] op_sel_hi:[0,1,0]
	v_add_f32_dpp v12, v12, v12 row_ror:2 row_mask:0xf bank_mask:0xf bound_ctrl:1
	v_pk_fma_f32 v[48:49], v[44:45], v[70:71], v[6:7] op_sel:[0,1,0]
	v_pk_fma_f32 v[50:51], v[46:47], v[70:71], v[8:9] op_sel:[0,1,0]
	v_add_f32_dpp v12, v12, v12 row_ror:4 row_mask:0xf bank_mask:0xf bound_ctrl:1
	s_nop 1
	v_add_f32_dpp v12, v12, v12 row_ror:8 row_mask:0xf bank_mask:0xf bound_ctrl:1
	v_pk_fma_f32 v[6:7], v[40:41], v[12:13], v[48:49] op_sel_hi:[1,0,1] neg_lo:[1,0,0] neg_hi:[1,0,0]
	v_pk_fma_f32 v[8:9], v[42:43], v[12:13], v[50:51] op_sel_hi:[1,0,1] neg_lo:[1,0,0] neg_hi:[1,0,0]
	ds_read_b128 v[110:113], v10 offset:7424
	ds_read_b128 v[106:109], v10 offset:7168
	ds_read_b128 v[118:121], v10 offset:7936
	ds_read_b128 v[114:117], v10 offset:7680
	ds_read_b128 v[66:69], v11 offset:512
	s_waitcnt lgkmcnt(5)
	v_fma_mix_f32 v12, v6, v88, v180 op_sel_hi:[0,1,0]
	v_fma_mix_f32 v12, v7, v88, v12 op_sel:[0,1,0] op_sel_hi:[0,1,0]
	v_fma_mix_f32 v12, v8, v89, v12 op_sel_hi:[0,1,0]
	v_fma_mix_f32 v12, v9, v89, v12 op_sel:[0,1,0] op_sel_hi:[0,1,0]
	v_fma_mix_f32 v57, v6, v38, v180 op_sel_hi:[0,1,0]
	v_fma_mix_f32 v57, v7, v38, v57 op_sel:[0,1,0] op_sel_hi:[0,1,0]
	v_add_f32_dpp v12, v12, v12 row_ror:1 row_mask:0xf bank_mask:0xf bound_ctrl:1
	v_fma_mix_f32 v57, v8, v39, v57 op_sel_hi:[0,1,0]
	v_fma_mix_f32 v57, v9, v39, v57 op_sel:[0,1,0] op_sel_hi:[0,1,0]
	v_add_f32_dpp v12, v12, v12 row_ror:2 row_mask:0xf bank_mask:0xf bound_ctrl:1
	v_pk_fma_f32 v[48:49], v[96:97], v[72:73], v[6:7] op_sel_hi:[1,0,1]
	v_pk_fma_f32 v[50:51], v[98:99], v[72:73], v[8:9] op_sel_hi:[1,0,1]
	v_add_f32_dpp v12, v12, v12 row_ror:4 row_mask:0xf bank_mask:0xf bound_ctrl:1
	s_nop 1
	v_add_f32_dpp v12, v12, v12 row_ror:8 row_mask:0xf bank_mask:0xf bound_ctrl:1
	v_pk_fma_f32 v[6:7], v[92:93], v[12:13], v[48:49] op_sel_hi:[1,0,1] neg_lo:[1,0,0] neg_hi:[1,0,0]
	v_pk_fma_f32 v[8:9], v[94:95], v[12:13], v[50:51] op_sel_hi:[1,0,1] neg_lo:[1,0,0] neg_hi:[1,0,0]
	ds_read_b128 v[20:23], v10 offset:8448
	ds_read_b128 v[28:31], v10 offset:8960
	ds_read_b128 v[24:27], v10 offset:8704
	s_waitcnt lgkmcnt(4)
	v_fma_mix_f32 v12, v6, v110, v180 op_sel_hi:[0,1,0]
	v_fma_mix_f32 v12, v7, v110, v12 op_sel:[0,1,0] op_sel_hi:[0,1,0]
	v_fma_mix_f32 v12, v8, v111, v12 op_sel_hi:[0,1,0]
	v_fma_mix_f32 v12, v9, v111, v12 op_sel:[0,1,0] op_sel_hi:[0,1,0]
	v_fma_mix_f32 v81, v6, v90, v180 op_sel_hi:[0,1,0]
	v_fma_mix_f32 v81, v7, v90, v81 op_sel:[0,1,0] op_sel_hi:[0,1,0]
	v_add_f32_dpp v12, v12, v12 row_ror:1 row_mask:0xf bank_mask:0xf bound_ctrl:1
	v_fma_mix_f32 v81, v8, v91, v81 op_sel_hi:[0,1,0]
	v_fma_mix_f32 v81, v9, v91, v81 op_sel:[0,1,0] op_sel_hi:[0,1,0]
	v_add_f32_dpp v12, v12, v12 row_ror:2 row_mask:0xf bank_mask:0xf bound_ctrl:1
	v_pk_fma_f32 v[48:49], v[118:119], v[72:73], v[6:7] op_sel:[0,1,0]
	v_pk_fma_f32 v[50:51], v[120:121], v[72:73], v[8:9] op_sel:[0,1,0]
	v_add_f32_dpp v12, v12, v12 row_ror:4 row_mask:0xf bank_mask:0xf bound_ctrl:1
	s_nop 1
	v_add_f32_dpp v12, v12, v12 row_ror:8 row_mask:0xf bank_mask:0xf bound_ctrl:1
	v_pk_fma_f32 v[6:7], v[114:115], v[12:13], v[48:49] op_sel_hi:[1,0,1] neg_lo:[1,0,0] neg_hi:[1,0,0]
	v_pk_fma_f32 v[8:9], v[116:117], v[12:13], v[50:51] op_sel_hi:[1,0,1] neg_lo:[1,0,0] neg_hi:[1,0,0]
	v_pk_mul_f32 v[6:7], v[6:7], v[106:107]
	v_pk_mul_f32 v[8:9], v[8:9], v[108:109]
	ds_read_b128 v[36:39], v10 offset:9472
	ds_read_b128 v[44:47], v10 offset:9984
	ds_read_b128 v[40:43], v10 offset:9728
	s_waitcnt lgkmcnt(3)
	v_fma_mix_f32 v12, v6, v20, v180 op_sel_hi:[0,1,0]
	v_fma_mix_f32 v12, v7, v20, v12 op_sel:[0,1,0] op_sel_hi:[0,1,0]
	v_fma_mix_f32 v12, v8, v21, v12 op_sel_hi:[0,1,0]
	v_fma_mix_f32 v12, v9, v21, v12 op_sel:[0,1,0] op_sel_hi:[0,1,0]
	v_fma_mix_f32 v82, v6, v112, v180 op_sel_hi:[0,1,0]
	v_fma_mix_f32 v82, v7, v112, v82 op_sel:[0,1,0] op_sel_hi:[0,1,0]
	v_add_f32_dpp v12, v12, v12 row_ror:1 row_mask:0xf bank_mask:0xf bound_ctrl:1
	v_fma_mix_f32 v82, v8, v113, v82 op_sel_hi:[0,1,0]
	v_fma_mix_f32 v82, v9, v113, v82 op_sel:[0,1,0] op_sel_hi:[0,1,0]
	v_add_f32_dpp v12, v12, v12 row_ror:2 row_mask:0xf bank_mask:0xf bound_ctrl:1
	v_pk_fma_f32 v[48:49], v[28:29], v[66:67], v[6:7] op_sel_hi:[1,0,1]
	v_pk_fma_f32 v[50:51], v[30:31], v[66:67], v[8:9] op_sel_hi:[1,0,1]
	v_add_f32_dpp v12, v12, v12 row_ror:4 row_mask:0xf bank_mask:0xf bound_ctrl:1
	s_nop 1
	v_add_f32_dpp v12, v12, v12 row_ror:8 row_mask:0xf bank_mask:0xf bound_ctrl:1
	v_pk_fma_f32 v[6:7], v[24:25], v[12:13], v[48:49] op_sel_hi:[1,0,1] neg_lo:[1,0,0] neg_hi:[1,0,0]
	v_pk_fma_f32 v[8:9], v[26:27], v[12:13], v[50:51] op_sel_hi:[1,0,1] neg_lo:[1,0,0] neg_hi:[1,0,0]
	ds_read_b128 v[88:91], v10 offset:10496
	ds_read_b128 v[96:99], v10 offset:11008
	ds_read_b128 v[92:95], v10 offset:10752
	s_waitcnt lgkmcnt(3)
	v_fma_mix_f32 v12, v6, v36, v180 op_sel_hi:[0,1,0]
	v_fma_mix_f32 v12, v7, v36, v12 op_sel:[0,1,0] op_sel_hi:[0,1,0]
	v_fma_mix_f32 v12, v8, v37, v12 op_sel_hi:[0,1,0]
	v_fma_mix_f32 v12, v9, v37, v12 op_sel:[0,1,0] op_sel_hi:[0,1,0]
	v_fma_mix_f32 v83, v6, v22, v180 op_sel_hi:[0,1,0]
	v_fma_mix_f32 v83, v7, v22, v83 op_sel:[0,1,0] op_sel_hi:[0,1,0]
	v_add_f32_dpp v12, v12, v12 row_ror:1 row_mask:0xf bank_mask:0xf bound_ctrl:1
	v_fma_mix_f32 v83, v8, v23, v83 op_sel_hi:[0,1,0]
	v_fma_mix_f32 v83, v9, v23, v83 op_sel:[0,1,0] op_sel_hi:[0,1,0]
	v_add_f32_dpp v12, v12, v12 row_ror:2 row_mask:0xf bank_mask:0xf bound_ctrl:1
	v_pk_fma_f32 v[48:49], v[44:45], v[66:67], v[6:7] op_sel:[0,1,0]
	v_pk_fma_f32 v[50:51], v[46:47], v[66:67], v[8:9] op_sel:[0,1,0]
	v_add_f32_dpp v12, v12, v12 row_ror:4 row_mask:0xf bank_mask:0xf bound_ctrl:1
	s_nop 1
	v_add_f32_dpp v12, v12, v12 row_ror:8 row_mask:0xf bank_mask:0xf bound_ctrl:1
	v_pk_fma_f32 v[6:7], v[40:41], v[12:13], v[48:49] op_sel_hi:[1,0,1] neg_lo:[1,0,0] neg_hi:[1,0,0]
	v_pk_fma_f32 v[8:9], v[42:43], v[12:13], v[50:51] op_sel_hi:[1,0,1] neg_lo:[1,0,0] neg_hi:[1,0,0]
	ds_read_b128 v[110:113], v10 offset:11520
	ds_read_b128 v[106:109], v10 offset:11264
	ds_read_b128 v[118:121], v10 offset:12032
	ds_read_b128 v[114:117], v10 offset:11776
	ds_read_b128 v[70:73], v11 offset:768
	s_waitcnt lgkmcnt(5)
	v_fma_mix_f32 v12, v6, v88, v180 op_sel_hi:[0,1,0]
	v_fma_mix_f32 v12, v7, v88, v12 op_sel:[0,1,0] op_sel_hi:[0,1,0]
	v_fma_mix_f32 v12, v8, v89, v12 op_sel_hi:[0,1,0]
	v_fma_mix_f32 v12, v9, v89, v12 op_sel:[0,1,0] op_sel_hi:[0,1,0]
	v_fma_mix_f32 v100, v6, v38, v180 op_sel_hi:[0,1,0]
	v_fma_mix_f32 v100, v7, v38, v100 op_sel:[0,1,0] op_sel_hi:[0,1,0]
	v_add_f32_dpp v12, v12, v12 row_ror:1 row_mask:0xf bank_mask:0xf bound_ctrl:1
	v_fma_mix_f32 v100, v8, v39, v100 op_sel_hi:[0,1,0]
	v_fma_mix_f32 v100, v9, v39, v100 op_sel:[0,1,0] op_sel_hi:[0,1,0]
	v_add_f32_dpp v12, v12, v12 row_ror:2 row_mask:0xf bank_mask:0xf bound_ctrl:1
	v_pk_fma_f32 v[48:49], v[96:97], v[68:69], v[6:7] op_sel_hi:[1,0,1]
	v_pk_fma_f32 v[50:51], v[98:99], v[68:69], v[8:9] op_sel_hi:[1,0,1]
	v_add_f32_dpp v12, v12, v12 row_ror:4 row_mask:0xf bank_mask:0xf bound_ctrl:1
	s_nop 1
	v_add_f32_dpp v12, v12, v12 row_ror:8 row_mask:0xf bank_mask:0xf bound_ctrl:1
	v_pk_fma_f32 v[6:7], v[92:93], v[12:13], v[48:49] op_sel_hi:[1,0,1] neg_lo:[1,0,0] neg_hi:[1,0,0]
	v_pk_fma_f32 v[8:9], v[94:95], v[12:13], v[50:51] op_sel_hi:[1,0,1] neg_lo:[1,0,0] neg_hi:[1,0,0]
	ds_read_b128 v[20:23], v10 offset:12544
	ds_read_b128 v[28:31], v10 offset:13056
	ds_read_b128 v[24:27], v10 offset:12800
	s_waitcnt lgkmcnt(4)
	v_fma_mix_f32 v12, v6, v110, v180 op_sel_hi:[0,1,0]
	v_fma_mix_f32 v12, v7, v110, v12 op_sel:[0,1,0] op_sel_hi:[0,1,0]
	v_fma_mix_f32 v12, v8, v111, v12 op_sel_hi:[0,1,0]
	v_fma_mix_f32 v12, v9, v111, v12 op_sel:[0,1,0] op_sel_hi:[0,1,0]
	v_fma_mix_f32 v101, v6, v90, v180 op_sel_hi:[0,1,0]
	v_fma_mix_f32 v101, v7, v90, v101 op_sel:[0,1,0] op_sel_hi:[0,1,0]
	v_add_f32_dpp v12, v12, v12 row_ror:1 row_mask:0xf bank_mask:0xf bound_ctrl:1
	v_fma_mix_f32 v101, v8, v91, v101 op_sel_hi:[0,1,0]
	v_fma_mix_f32 v101, v9, v91, v101 op_sel:[0,1,0] op_sel_hi:[0,1,0]
	v_add_f32_dpp v12, v12, v12 row_ror:2 row_mask:0xf bank_mask:0xf bound_ctrl:1
	v_pk_fma_f32 v[48:49], v[118:119], v[68:69], v[6:7] op_sel:[0,1,0]
	v_pk_fma_f32 v[50:51], v[120:121], v[68:69], v[8:9] op_sel:[0,1,0]
	v_add_f32_dpp v12, v12, v12 row_ror:4 row_mask:0xf bank_mask:0xf bound_ctrl:1
	s_nop 1
	v_add_f32_dpp v12, v12, v12 row_ror:8 row_mask:0xf bank_mask:0xf bound_ctrl:1
	v_pk_fma_f32 v[6:7], v[114:115], v[12:13], v[48:49] op_sel_hi:[1,0,1] neg_lo:[1,0,0] neg_hi:[1,0,0]
	v_pk_fma_f32 v[8:9], v[116:117], v[12:13], v[50:51] op_sel_hi:[1,0,1] neg_lo:[1,0,0] neg_hi:[1,0,0]
	v_pk_mul_f32 v[6:7], v[6:7], v[106:107]
	v_pk_mul_f32 v[8:9], v[8:9], v[108:109]
	ds_read_b128 v[36:39], v10 offset:13568
	ds_read_b128 v[44:47], v10 offset:14080
	ds_read_b128 v[40:43], v10 offset:13824
	s_waitcnt lgkmcnt(3)
	v_fma_mix_f32 v12, v6, v20, v180 op_sel_hi:[0,1,0]
	v_fma_mix_f32 v12, v7, v20, v12 op_sel:[0,1,0] op_sel_hi:[0,1,0]
	v_fma_mix_f32 v12, v8, v21, v12 op_sel_hi:[0,1,0]
	v_fma_mix_f32 v12, v9, v21, v12 op_sel:[0,1,0] op_sel_hi:[0,1,0]
	v_fma_mix_f32 v102, v6, v112, v180 op_sel_hi:[0,1,0]
	v_fma_mix_f32 v102, v7, v112, v102 op_sel:[0,1,0] op_sel_hi:[0,1,0]
	v_add_f32_dpp v12, v12, v12 row_ror:1 row_mask:0xf bank_mask:0xf bound_ctrl:1
	v_fma_mix_f32 v102, v8, v113, v102 op_sel_hi:[0,1,0]
	v_fma_mix_f32 v102, v9, v113, v102 op_sel:[0,1,0] op_sel_hi:[0,1,0]
	v_add_f32_dpp v12, v12, v12 row_ror:2 row_mask:0xf bank_mask:0xf bound_ctrl:1
	v_pk_fma_f32 v[48:49], v[28:29], v[70:71], v[6:7] op_sel_hi:[1,0,1]
	v_pk_fma_f32 v[50:51], v[30:31], v[70:71], v[8:9] op_sel_hi:[1,0,1]
	v_add_f32_dpp v12, v12, v12 row_ror:4 row_mask:0xf bank_mask:0xf bound_ctrl:1
	s_nop 1
	v_add_f32_dpp v12, v12, v12 row_ror:8 row_mask:0xf bank_mask:0xf bound_ctrl:1
	v_pk_fma_f32 v[6:7], v[24:25], v[12:13], v[48:49] op_sel_hi:[1,0,1] neg_lo:[1,0,0] neg_hi:[1,0,0]
	v_pk_fma_f32 v[8:9], v[26:27], v[12:13], v[50:51] op_sel_hi:[1,0,1] neg_lo:[1,0,0] neg_hi:[1,0,0]
	ds_read_b128 v[88:91], v10 offset:14592
	ds_read_b128 v[96:99], v10 offset:15104
	ds_read_b128 v[92:95], v10 offset:14848
	s_waitcnt lgkmcnt(3)
	v_fma_mix_f32 v12, v6, v36, v180 op_sel_hi:[0,1,0]
	v_fma_mix_f32 v12, v7, v36, v12 op_sel:[0,1,0] op_sel_hi:[0,1,0]
	v_fma_mix_f32 v12, v8, v37, v12 op_sel_hi:[0,1,0]
	v_fma_mix_f32 v12, v9, v37, v12 op_sel:[0,1,0] op_sel_hi:[0,1,0]
	v_fma_mix_f32 v103, v6, v22, v180 op_sel_hi:[0,1,0]
	v_fma_mix_f32 v103, v7, v22, v103 op_sel:[0,1,0] op_sel_hi:[0,1,0]
	v_add_f32_dpp v12, v12, v12 row_ror:1 row_mask:0xf bank_mask:0xf bound_ctrl:1
	v_fma_mix_f32 v103, v8, v23, v103 op_sel_hi:[0,1,0]
	v_fma_mix_f32 v103, v9, v23, v103 op_sel:[0,1,0] op_sel_hi:[0,1,0]
	v_add_f32_dpp v12, v12, v12 row_ror:2 row_mask:0xf bank_mask:0xf bound_ctrl:1
	v_pk_fma_f32 v[48:49], v[44:45], v[70:71], v[6:7] op_sel:[0,1,0]
	v_pk_fma_f32 v[50:51], v[46:47], v[70:71], v[8:9] op_sel:[0,1,0]
	v_add_f32_dpp v12, v12, v12 row_ror:4 row_mask:0xf bank_mask:0xf bound_ctrl:1
	s_nop 1
	v_add_f32_dpp v12, v12, v12 row_ror:8 row_mask:0xf bank_mask:0xf bound_ctrl:1
	v_pk_fma_f32 v[6:7], v[40:41], v[12:13], v[48:49] op_sel_hi:[1,0,1] neg_lo:[1,0,0] neg_hi:[1,0,0]
	v_pk_fma_f32 v[8:9], v[42:43], v[12:13], v[50:51] op_sel_hi:[1,0,1] neg_lo:[1,0,0] neg_hi:[1,0,0]
	ds_read_b128 v[110:113], v10 offset:15616
	ds_read_b128 v[106:109], v10 offset:15360
	ds_read_b128 v[118:121], v10 offset:16128
	ds_read_b128 v[114:117], v10 offset:15872
	ds_read_b128 v[66:69], v11 offset:1024
	s_waitcnt lgkmcnt(5)
	v_fma_mix_f32 v12, v6, v88, v180 op_sel_hi:[0,1,0]
	v_fma_mix_f32 v12, v7, v88, v12 op_sel:[0,1,0] op_sel_hi:[0,1,0]
	v_fma_mix_f32 v12, v8, v89, v12 op_sel_hi:[0,1,0]
	v_fma_mix_f32 v12, v9, v89, v12 op_sel:[0,1,0] op_sel_hi:[0,1,0]
	v_fma_mix_f32 v104, v6, v38, v180 op_sel_hi:[0,1,0]
	v_fma_mix_f32 v104, v7, v38, v104 op_sel:[0,1,0] op_sel_hi:[0,1,0]
	v_add_f32_dpp v12, v12, v12 row_ror:1 row_mask:0xf bank_mask:0xf bound_ctrl:1
	v_fma_mix_f32 v104, v8, v39, v104 op_sel_hi:[0,1,0]
	v_fma_mix_f32 v104, v9, v39, v104 op_sel:[0,1,0] op_sel_hi:[0,1,0]
	v_add_f32_dpp v12, v12, v12 row_ror:2 row_mask:0xf bank_mask:0xf bound_ctrl:1
	v_pk_fma_f32 v[48:49], v[96:97], v[72:73], v[6:7] op_sel_hi:[1,0,1]
	v_pk_fma_f32 v[50:51], v[98:99], v[72:73], v[8:9] op_sel_hi:[1,0,1]
	v_add_f32_dpp v12, v12, v12 row_ror:4 row_mask:0xf bank_mask:0xf bound_ctrl:1
	s_nop 1
	v_add_f32_dpp v12, v12, v12 row_ror:8 row_mask:0xf bank_mask:0xf bound_ctrl:1
	v_pk_fma_f32 v[6:7], v[92:93], v[12:13], v[48:49] op_sel_hi:[1,0,1] neg_lo:[1,0,0] neg_hi:[1,0,0]
	v_pk_fma_f32 v[8:9], v[94:95], v[12:13], v[50:51] op_sel_hi:[1,0,1] neg_lo:[1,0,0] neg_hi:[1,0,0]
	ds_read_b128 v[20:23], v10 offset:16640
	ds_read_b128 v[28:31], v10 offset:17152
	ds_read_b128 v[24:27], v10 offset:16896
	s_waitcnt lgkmcnt(4)
	v_fma_mix_f32 v12, v6, v110, v180 op_sel_hi:[0,1,0]
	v_fma_mix_f32 v12, v7, v110, v12 op_sel:[0,1,0] op_sel_hi:[0,1,0]
	v_fma_mix_f32 v12, v8, v111, v12 op_sel_hi:[0,1,0]
	v_fma_mix_f32 v12, v9, v111, v12 op_sel:[0,1,0] op_sel_hi:[0,1,0]
	v_fma_mix_f32 v105, v6, v90, v180 op_sel_hi:[0,1,0]
	v_fma_mix_f32 v105, v7, v90, v105 op_sel:[0,1,0] op_sel_hi:[0,1,0]
	v_add_f32_dpp v12, v12, v12 row_ror:1 row_mask:0xf bank_mask:0xf bound_ctrl:1
	v_fma_mix_f32 v105, v8, v91, v105 op_sel_hi:[0,1,0]
	v_fma_mix_f32 v105, v9, v91, v105 op_sel:[0,1,0] op_sel_hi:[0,1,0]
	v_add_f32_dpp v12, v12, v12 row_ror:2 row_mask:0xf bank_mask:0xf bound_ctrl:1
	v_pk_fma_f32 v[48:49], v[118:119], v[72:73], v[6:7] op_sel:[0,1,0]
	v_pk_fma_f32 v[50:51], v[120:121], v[72:73], v[8:9] op_sel:[0,1,0]
	v_add_f32_dpp v12, v12, v12 row_ror:4 row_mask:0xf bank_mask:0xf bound_ctrl:1
	s_nop 1
	v_add_f32_dpp v12, v12, v12 row_ror:8 row_mask:0xf bank_mask:0xf bound_ctrl:1
	v_pk_fma_f32 v[6:7], v[114:115], v[12:13], v[48:49] op_sel_hi:[1,0,1] neg_lo:[1,0,0] neg_hi:[1,0,0]
	v_pk_fma_f32 v[8:9], v[116:117], v[12:13], v[50:51] op_sel_hi:[1,0,1] neg_lo:[1,0,0] neg_hi:[1,0,0]
	v_pk_mul_f32 v[6:7], v[6:7], v[106:107]
	v_pk_mul_f32 v[8:9], v[8:9], v[108:109]
	ds_read_b128 v[36:39], v10 offset:17664
	ds_read_b128 v[44:47], v10 offset:18176
	ds_read_b128 v[40:43], v10 offset:17920
	s_waitcnt lgkmcnt(3)
	v_fma_mix_f32 v12, v6, v20, v180 op_sel_hi:[0,1,0]
	v_fma_mix_f32 v12, v7, v20, v12 op_sel:[0,1,0] op_sel_hi:[0,1,0]
	v_fma_mix_f32 v12, v8, v21, v12 op_sel_hi:[0,1,0]
	v_fma_mix_f32 v12, v9, v21, v12 op_sel:[0,1,0] op_sel_hi:[0,1,0]
	v_fma_mix_f32 v61, v6, v112, v180 op_sel_hi:[0,1,0]
	v_fma_mix_f32 v61, v7, v112, v61 op_sel:[0,1,0] op_sel_hi:[0,1,0]
	v_add_f32_dpp v12, v12, v12 row_ror:1 row_mask:0xf bank_mask:0xf bound_ctrl:1
	v_fma_mix_f32 v61, v8, v113, v61 op_sel_hi:[0,1,0]
	v_fma_mix_f32 v61, v9, v113, v61 op_sel:[0,1,0] op_sel_hi:[0,1,0]
	v_add_f32_dpp v12, v12, v12 row_ror:2 row_mask:0xf bank_mask:0xf bound_ctrl:1
	v_pk_fma_f32 v[48:49], v[28:29], v[66:67], v[6:7] op_sel_hi:[1,0,1]
	v_pk_fma_f32 v[50:51], v[30:31], v[66:67], v[8:9] op_sel_hi:[1,0,1]
	v_add_f32_dpp v12, v12, v12 row_ror:4 row_mask:0xf bank_mask:0xf bound_ctrl:1
	s_nop 1
	v_add_f32_dpp v12, v12, v12 row_ror:8 row_mask:0xf bank_mask:0xf bound_ctrl:1
	v_pk_fma_f32 v[6:7], v[24:25], v[12:13], v[48:49] op_sel_hi:[1,0,1] neg_lo:[1,0,0] neg_hi:[1,0,0]
	v_pk_fma_f32 v[8:9], v[26:27], v[12:13], v[50:51] op_sel_hi:[1,0,1] neg_lo:[1,0,0] neg_hi:[1,0,0]
	ds_read_b128 v[88:91], v10 offset:18688
	ds_read_b128 v[96:99], v10 offset:19200
	ds_read_b128 v[92:95], v10 offset:18944
	v_add_f32_dpp v83, v83, v83 row_ror:8 row_mask:0xf bank_mask:0xc
	v_add_f32_dpp v83, v52, v52 row_ror:8 row_mask:0xf bank_mask:0x3
	v_add_f32_dpp v100, v100, v100 row_ror:8 row_mask:0xf bank_mask:0xc
	v_add_f32_dpp v100, v53, v53 row_ror:8 row_mask:0xf bank_mask:0x3
	v_add_f32_dpp v101, v101, v101 row_ror:8 row_mask:0xf bank_mask:0xc
	v_add_f32_dpp v101, v54, v54 row_ror:8 row_mask:0xf bank_mask:0x3
	v_add_f32_dpp v102, v102, v102 row_ror:8 row_mask:0xf bank_mask:0xc
	v_add_f32_dpp v102, v55, v55 row_ror:8 row_mask:0xf bank_mask:0x3
	v_add_f32_dpp v103, v103, v103 row_ror:8 row_mask:0xf bank_mask:0xc
	v_add_f32_dpp v103, v56, v56 row_ror:8 row_mask:0xf bank_mask:0x3
	v_add_f32_dpp v104, v104, v104 row_ror:8 row_mask:0xf bank_mask:0xc
	v_add_f32_dpp v104, v57, v57 row_ror:8 row_mask:0xf bank_mask:0x3
	v_add_f32_dpp v105, v105, v105 row_ror:8 row_mask:0xf bank_mask:0xc
	v_add_f32_dpp v105, v81, v81 row_ror:8 row_mask:0xf bank_mask:0x3
	v_add_f32_dpp v61, v61, v61 row_ror:8 row_mask:0xf bank_mask:0xc
	v_add_f32_dpp v61, v82, v82 row_ror:8 row_mask:0xf bank_mask:0x3
	v_add_f32_dpp v103, v103, v103 row_ror:4 row_mask:0xf bank_mask:0xa
	v_add_f32_dpp v103, v83, v83 row_ror:12 row_mask:0xf bank_mask:0x5
	v_add_f32_dpp v104, v104, v104 row_ror:4 row_mask:0xf bank_mask:0xa
	v_add_f32_dpp v104, v100, v100 row_ror:12 row_mask:0xf bank_mask:0x5
	v_add_f32_dpp v105, v105, v105 row_ror:4 row_mask:0xf bank_mask:0xa
	v_add_f32_dpp v105, v101, v101 row_ror:12 row_mask:0xf bank_mask:0x5
	v_add_f32_dpp v61, v61, v61 row_ror:4 row_mask:0xf bank_mask:0xa
	v_add_f32_dpp v61, v102, v102 row_ror:12 row_mask:0xf bank_mask:0x5
	v_cndmask_b32_e64 v62, v105, v103, s[38:39]
	v_cndmask_b32_e64 v63, v103, v105, s[38:39]
	v_cndmask_b32_e64 v64, v61, v104, s[38:39]
	v_cndmask_b32_e64 v65, v104, v61, s[38:39]
	v_add_f32_dpp v62, v63, v62 quad_perm:[2,3,0,1] row_mask:0xf bank_mask:0xf bound_ctrl:1
	s_nop 0
	v_add_f32_dpp v63, v65, v64 quad_perm:[2,3,0,1] row_mask:0xf bank_mask:0xf bound_ctrl:1
	v_cndmask_b32_e64 v65, v63, v62, s[40:41]
	v_cndmask_b32_e64 v62, v62, v63, s[40:41]
	s_nop 1
	v_add_f32_dpp v62, v62, v65 quad_perm:[1,0,3,2] row_mask:0xf bank_mask:0xf bound_ctrl:1
	v_cvt_pk_bf16_f32 v62, v62, v62
	global_store_short v[2:3], v62, off
	v_lshl_add_u64 v[2:3], v[2:3], 0, s[84:85]
	s_waitcnt lgkmcnt(3)
	v_fma_mix_f32 v12, v6, v36, v180 op_sel_hi:[0,1,0]
	v_fma_mix_f32 v12, v7, v36, v12 op_sel:[0,1,0] op_sel_hi:[0,1,0]
	v_fma_mix_f32 v12, v8, v37, v12 op_sel_hi:[0,1,0]
	v_fma_mix_f32 v12, v9, v37, v12 op_sel:[0,1,0] op_sel_hi:[0,1,0]
	v_fma_mix_f32 v52, v6, v22, v180 op_sel_hi:[0,1,0]
	v_fma_mix_f32 v52, v7, v22, v52 op_sel:[0,1,0] op_sel_hi:[0,1,0]
	v_add_f32_dpp v12, v12, v12 row_ror:1 row_mask:0xf bank_mask:0xf bound_ctrl:1
	v_fma_mix_f32 v52, v8, v23, v52 op_sel_hi:[0,1,0]
	v_fma_mix_f32 v52, v9, v23, v52 op_sel:[0,1,0] op_sel_hi:[0,1,0]
	v_add_f32_dpp v12, v12, v12 row_ror:2 row_mask:0xf bank_mask:0xf bound_ctrl:1
	v_pk_fma_f32 v[48:49], v[44:45], v[66:67], v[6:7] op_sel:[0,1,0]
	v_pk_fma_f32 v[50:51], v[46:47], v[66:67], v[8:9] op_sel:[0,1,0]
	v_add_f32_dpp v12, v12, v12 row_ror:4 row_mask:0xf bank_mask:0xf bound_ctrl:1
	s_nop 1
	v_add_f32_dpp v12, v12, v12 row_ror:8 row_mask:0xf bank_mask:0xf bound_ctrl:1
	v_pk_fma_f32 v[6:7], v[40:41], v[12:13], v[48:49] op_sel_hi:[1,0,1] neg_lo:[1,0,0] neg_hi:[1,0,0]
	v_pk_fma_f32 v[8:9], v[42:43], v[12:13], v[50:51] op_sel_hi:[1,0,1] neg_lo:[1,0,0] neg_hi:[1,0,0]
	ds_read_b128 v[110:113], v10 offset:19712
	ds_read_b128 v[106:109], v10 offset:19456
	ds_read_b128 v[118:121], v10 offset:20224
	ds_read_b128 v[114:117], v10 offset:19968
	ds_read_b128 v[70:73], v11 offset:1280
	s_waitcnt lgkmcnt(5)
	v_fma_mix_f32 v12, v6, v88, v180 op_sel_hi:[0,1,0]
	v_fma_mix_f32 v12, v7, v88, v12 op_sel:[0,1,0] op_sel_hi:[0,1,0]
	v_fma_mix_f32 v12, v8, v89, v12 op_sel_hi:[0,1,0]
	v_fma_mix_f32 v12, v9, v89, v12 op_sel:[0,1,0] op_sel_hi:[0,1,0]
	v_fma_mix_f32 v53, v6, v38, v180 op_sel_hi:[0,1,0]
	v_fma_mix_f32 v53, v7, v38, v53 op_sel:[0,1,0] op_sel_hi:[0,1,0]
	v_add_f32_dpp v12, v12, v12 row_ror:1 row_mask:0xf bank_mask:0xf bound_ctrl:1
	v_fma_mix_f32 v53, v8, v39, v53 op_sel_hi:[0,1,0]
	v_fma_mix_f32 v53, v9, v39, v53 op_sel:[0,1,0] op_sel_hi:[0,1,0]
	v_add_f32_dpp v12, v12, v12 row_ror:2 row_mask:0xf bank_mask:0xf bound_ctrl:1
	v_pk_fma_f32 v[48:49], v[96:97], v[68:69], v[6:7] op_sel_hi:[1,0,1]
	v_pk_fma_f32 v[50:51], v[98:99], v[68:69], v[8:9] op_sel_hi:[1,0,1]
	v_add_f32_dpp v12, v12, v12 row_ror:4 row_mask:0xf bank_mask:0xf bound_ctrl:1
	s_nop 1
	v_add_f32_dpp v12, v12, v12 row_ror:8 row_mask:0xf bank_mask:0xf bound_ctrl:1
	v_pk_fma_f32 v[6:7], v[92:93], v[12:13], v[48:49] op_sel_hi:[1,0,1] neg_lo:[1,0,0] neg_hi:[1,0,0]
	v_pk_fma_f32 v[8:9], v[94:95], v[12:13], v[50:51] op_sel_hi:[1,0,1] neg_lo:[1,0,0] neg_hi:[1,0,0]
	ds_read_b128 v[20:23], v10 offset:20736
	ds_read_b128 v[28:31], v10 offset:21248
	ds_read_b128 v[24:27], v10 offset:20992
	s_waitcnt lgkmcnt(4)
	v_fma_mix_f32 v12, v6, v110, v180 op_sel_hi:[0,1,0]
	v_fma_mix_f32 v12, v7, v110, v12 op_sel:[0,1,0] op_sel_hi:[0,1,0]
	v_fma_mix_f32 v12, v8, v111, v12 op_sel_hi:[0,1,0]
	v_fma_mix_f32 v12, v9, v111, v12 op_sel:[0,1,0] op_sel_hi:[0,1,0]
	v_fma_mix_f32 v54, v6, v90, v180 op_sel_hi:[0,1,0]
	v_fma_mix_f32 v54, v7, v90, v54 op_sel:[0,1,0] op_sel_hi:[0,1,0]
	v_add_f32_dpp v12, v12, v12 row_ror:1 row_mask:0xf bank_mask:0xf bound_ctrl:1
	v_fma_mix_f32 v54, v8, v91, v54 op_sel_hi:[0,1,0]
	v_fma_mix_f32 v54, v9, v91, v54 op_sel:[0,1,0] op_sel_hi:[0,1,0]
	v_add_f32_dpp v12, v12, v12 row_ror:2 row_mask:0xf bank_mask:0xf bound_ctrl:1
	v_pk_fma_f32 v[48:49], v[118:119], v[68:69], v[6:7] op_sel:[0,1,0]
	v_pk_fma_f32 v[50:51], v[120:121], v[68:69], v[8:9] op_sel:[0,1,0]
	v_add_f32_dpp v12, v12, v12 row_ror:4 row_mask:0xf bank_mask:0xf bound_ctrl:1
	s_nop 1
	v_add_f32_dpp v12, v12, v12 row_ror:8 row_mask:0xf bank_mask:0xf bound_ctrl:1
	v_pk_fma_f32 v[6:7], v[114:115], v[12:13], v[48:49] op_sel_hi:[1,0,1] neg_lo:[1,0,0] neg_hi:[1,0,0]
	v_pk_fma_f32 v[8:9], v[116:117], v[12:13], v[50:51] op_sel_hi:[1,0,1] neg_lo:[1,0,0] neg_hi:[1,0,0]
	v_pk_mul_f32 v[6:7], v[6:7], v[106:107]
	v_pk_mul_f32 v[8:9], v[8:9], v[108:109]
	ds_read_b128 v[36:39], v10 offset:21760
	ds_read_b128 v[44:47], v10 offset:22272
	ds_read_b128 v[40:43], v10 offset:22016
	s_waitcnt lgkmcnt(3)
	v_fma_mix_f32 v12, v6, v20, v180 op_sel_hi:[0,1,0]
	v_fma_mix_f32 v12, v7, v20, v12 op_sel:[0,1,0] op_sel_hi:[0,1,0]
	v_fma_mix_f32 v12, v8, v21, v12 op_sel_hi:[0,1,0]
	v_fma_mix_f32 v12, v9, v21, v12 op_sel:[0,1,0] op_sel_hi:[0,1,0]
	v_fma_mix_f32 v55, v6, v112, v180 op_sel_hi:[0,1,0]
	v_fma_mix_f32 v55, v7, v112, v55 op_sel:[0,1,0] op_sel_hi:[0,1,0]
	v_add_f32_dpp v12, v12, v12 row_ror:1 row_mask:0xf bank_mask:0xf bound_ctrl:1
	v_fma_mix_f32 v55, v8, v113, v55 op_sel_hi:[0,1,0]
	v_fma_mix_f32 v55, v9, v113, v55 op_sel:[0,1,0] op_sel_hi:[0,1,0]
	v_add_f32_dpp v12, v12, v12 row_ror:2 row_mask:0xf bank_mask:0xf bound_ctrl:1
	v_pk_fma_f32 v[48:49], v[28:29], v[70:71], v[6:7] op_sel_hi:[1,0,1]
	v_pk_fma_f32 v[50:51], v[30:31], v[70:71], v[8:9] op_sel_hi:[1,0,1]
	v_add_f32_dpp v12, v12, v12 row_ror:4 row_mask:0xf bank_mask:0xf bound_ctrl:1
	s_nop 1
	v_add_f32_dpp v12, v12, v12 row_ror:8 row_mask:0xf bank_mask:0xf bound_ctrl:1
	v_pk_fma_f32 v[6:7], v[24:25], v[12:13], v[48:49] op_sel_hi:[1,0,1] neg_lo:[1,0,0] neg_hi:[1,0,0]
	v_pk_fma_f32 v[8:9], v[26:27], v[12:13], v[50:51] op_sel_hi:[1,0,1] neg_lo:[1,0,0] neg_hi:[1,0,0]
	ds_read_b128 v[88:91], v10 offset:22784
	ds_read_b128 v[96:99], v10 offset:23296
	ds_read_b128 v[92:95], v10 offset:23040
	s_waitcnt lgkmcnt(3)
	v_fma_mix_f32 v12, v6, v36, v180 op_sel_hi:[0,1,0]
	v_fma_mix_f32 v12, v7, v36, v12 op_sel:[0,1,0] op_sel_hi:[0,1,0]
	v_fma_mix_f32 v12, v8, v37, v12 op_sel_hi:[0,1,0]
	v_fma_mix_f32 v12, v9, v37, v12 op_sel:[0,1,0] op_sel_hi:[0,1,0]
	v_fma_mix_f32 v56, v6, v22, v180 op_sel_hi:[0,1,0]
	v_fma_mix_f32 v56, v7, v22, v56 op_sel:[0,1,0] op_sel_hi:[0,1,0]
	v_add_f32_dpp v12, v12, v12 row_ror:1 row_mask:0xf bank_mask:0xf bound_ctrl:1
	v_fma_mix_f32 v56, v8, v23, v56 op_sel_hi:[0,1,0]
	v_fma_mix_f32 v56, v9, v23, v56 op_sel:[0,1,0] op_sel_hi:[0,1,0]
	v_add_f32_dpp v12, v12, v12 row_ror:2 row_mask:0xf bank_mask:0xf bound_ctrl:1
	v_pk_fma_f32 v[48:49], v[44:45], v[70:71], v[6:7] op_sel:[0,1,0]
	v_pk_fma_f32 v[50:51], v[46:47], v[70:71], v[8:9] op_sel:[0,1,0]
	v_add_f32_dpp v12, v12, v12 row_ror:4 row_mask:0xf bank_mask:0xf bound_ctrl:1
	s_nop 1
	v_add_f32_dpp v12, v12, v12 row_ror:8 row_mask:0xf bank_mask:0xf bound_ctrl:1
	v_pk_fma_f32 v[6:7], v[40:41], v[12:13], v[48:49] op_sel_hi:[1,0,1] neg_lo:[1,0,0] neg_hi:[1,0,0]
	v_pk_fma_f32 v[8:9], v[42:43], v[12:13], v[50:51] op_sel_hi:[1,0,1] neg_lo:[1,0,0] neg_hi:[1,0,0]
	ds_read_b128 v[110:113], v10 offset:23808
	ds_read_b128 v[106:109], v10 offset:23552
	ds_read_b128 v[118:121], v10 offset:24320
	ds_read_b128 v[114:117], v10 offset:24064
	ds_read_b128 v[66:69], v11 offset:1536
	s_waitcnt lgkmcnt(5)
	v_fma_mix_f32 v12, v6, v88, v180 op_sel_hi:[0,1,0]
	v_fma_mix_f32 v12, v7, v88, v12 op_sel:[0,1,0] op_sel_hi:[0,1,0]
	v_fma_mix_f32 v12, v8, v89, v12 op_sel_hi:[0,1,0]
	v_fma_mix_f32 v12, v9, v89, v12 op_sel:[0,1,0] op_sel_hi:[0,1,0]
	v_fma_mix_f32 v57, v6, v38, v180 op_sel_hi:[0,1,0]
	v_fma_mix_f32 v57, v7, v38, v57 op_sel:[0,1,0] op_sel_hi:[0,1,0]
	v_add_f32_dpp v12, v12, v12 row_ror:1 row_mask:0xf bank_mask:0xf bound_ctrl:1
	v_fma_mix_f32 v57, v8, v39, v57 op_sel_hi:[0,1,0]
	v_fma_mix_f32 v57, v9, v39, v57 op_sel:[0,1,0] op_sel_hi:[0,1,0]
	v_add_f32_dpp v12, v12, v12 row_ror:2 row_mask:0xf bank_mask:0xf bound_ctrl:1
	v_pk_fma_f32 v[48:49], v[96:97], v[72:73], v[6:7] op_sel_hi:[1,0,1]
	v_pk_fma_f32 v[50:51], v[98:99], v[72:73], v[8:9] op_sel_hi:[1,0,1]
	v_add_f32_dpp v12, v12, v12 row_ror:4 row_mask:0xf bank_mask:0xf bound_ctrl:1
	s_nop 1
	v_add_f32_dpp v12, v12, v12 row_ror:8 row_mask:0xf bank_mask:0xf bound_ctrl:1
	v_pk_fma_f32 v[6:7], v[92:93], v[12:13], v[48:49] op_sel_hi:[1,0,1] neg_lo:[1,0,0] neg_hi:[1,0,0]
	v_pk_fma_f32 v[8:9], v[94:95], v[12:13], v[50:51] op_sel_hi:[1,0,1] neg_lo:[1,0,0] neg_hi:[1,0,0]
	ds_read_b128 v[20:23], v10 offset:24832
	ds_read_b128 v[28:31], v10 offset:25344
	ds_read_b128 v[24:27], v10 offset:25088
	s_waitcnt lgkmcnt(4)
	v_fma_mix_f32 v12, v6, v110, v180 op_sel_hi:[0,1,0]
	v_fma_mix_f32 v12, v7, v110, v12 op_sel:[0,1,0] op_sel_hi:[0,1,0]
	v_fma_mix_f32 v12, v8, v111, v12 op_sel_hi:[0,1,0]
	v_fma_mix_f32 v12, v9, v111, v12 op_sel:[0,1,0] op_sel_hi:[0,1,0]
	v_fma_mix_f32 v81, v6, v90, v180 op_sel_hi:[0,1,0]
	v_fma_mix_f32 v81, v7, v90, v81 op_sel:[0,1,0] op_sel_hi:[0,1,0]
	v_add_f32_dpp v12, v12, v12 row_ror:1 row_mask:0xf bank_mask:0xf bound_ctrl:1
	v_fma_mix_f32 v81, v8, v91, v81 op_sel_hi:[0,1,0]
	v_fma_mix_f32 v81, v9, v91, v81 op_sel:[0,1,0] op_sel_hi:[0,1,0]
	v_add_f32_dpp v12, v12, v12 row_ror:2 row_mask:0xf bank_mask:0xf bound_ctrl:1
	v_pk_fma_f32 v[48:49], v[118:119], v[72:73], v[6:7] op_sel:[0,1,0]
	v_pk_fma_f32 v[50:51], v[120:121], v[72:73], v[8:9] op_sel:[0,1,0]
	v_add_f32_dpp v12, v12, v12 row_ror:4 row_mask:0xf bank_mask:0xf bound_ctrl:1
	s_nop 1
	v_add_f32_dpp v12, v12, v12 row_ror:8 row_mask:0xf bank_mask:0xf bound_ctrl:1
	v_pk_fma_f32 v[6:7], v[114:115], v[12:13], v[48:49] op_sel_hi:[1,0,1] neg_lo:[1,0,0] neg_hi:[1,0,0]
	v_pk_fma_f32 v[8:9], v[116:117], v[12:13], v[50:51] op_sel_hi:[1,0,1] neg_lo:[1,0,0] neg_hi:[1,0,0]
	v_pk_mul_f32 v[6:7], v[6:7], v[106:107]
	v_pk_mul_f32 v[8:9], v[8:9], v[108:109]
	ds_read_b128 v[36:39], v10 offset:25856
	ds_read_b128 v[44:47], v10 offset:26368
	ds_read_b128 v[40:43], v10 offset:26112
	s_waitcnt lgkmcnt(3)
	v_fma_mix_f32 v12, v6, v20, v180 op_sel_hi:[0,1,0]
	v_fma_mix_f32 v12, v7, v20, v12 op_sel:[0,1,0] op_sel_hi:[0,1,0]
	v_fma_mix_f32 v12, v8, v21, v12 op_sel_hi:[0,1,0]
	v_fma_mix_f32 v12, v9, v21, v12 op_sel:[0,1,0] op_sel_hi:[0,1,0]
	v_fma_mix_f32 v82, v6, v112, v180 op_sel_hi:[0,1,0]
	v_fma_mix_f32 v82, v7, v112, v82 op_sel:[0,1,0] op_sel_hi:[0,1,0]
	v_add_f32_dpp v12, v12, v12 row_ror:1 row_mask:0xf bank_mask:0xf bound_ctrl:1
	v_fma_mix_f32 v82, v8, v113, v82 op_sel_hi:[0,1,0]
	v_fma_mix_f32 v82, v9, v113, v82 op_sel:[0,1,0] op_sel_hi:[0,1,0]
	v_add_f32_dpp v12, v12, v12 row_ror:2 row_mask:0xf bank_mask:0xf bound_ctrl:1
	v_pk_fma_f32 v[48:49], v[28:29], v[66:67], v[6:7] op_sel_hi:[1,0,1]
	v_pk_fma_f32 v[50:51], v[30:31], v[66:67], v[8:9] op_sel_hi:[1,0,1]
	v_add_f32_dpp v12, v12, v12 row_ror:4 row_mask:0xf bank_mask:0xf bound_ctrl:1
	s_nop 1
	v_add_f32_dpp v12, v12, v12 row_ror:8 row_mask:0xf bank_mask:0xf bound_ctrl:1
	v_pk_fma_f32 v[6:7], v[24:25], v[12:13], v[48:49] op_sel_hi:[1,0,1] neg_lo:[1,0,0] neg_hi:[1,0,0]
	v_pk_fma_f32 v[8:9], v[26:27], v[12:13], v[50:51] op_sel_hi:[1,0,1] neg_lo:[1,0,0] neg_hi:[1,0,0]
	ds_read_b128 v[88:91], v10 offset:26880
	ds_read_b128 v[96:99], v10 offset:27392
	ds_read_b128 v[92:95], v10 offset:27136
	s_waitcnt lgkmcnt(3)
	v_fma_mix_f32 v12, v6, v36, v180 op_sel_hi:[0,1,0]
	v_fma_mix_f32 v12, v7, v36, v12 op_sel:[0,1,0] op_sel_hi:[0,1,0]
	v_fma_mix_f32 v12, v8, v37, v12 op_sel_hi:[0,1,0]
	v_fma_mix_f32 v12, v9, v37, v12 op_sel:[0,1,0] op_sel_hi:[0,1,0]
	v_fma_mix_f32 v83, v6, v22, v180 op_sel_hi:[0,1,0]
	v_fma_mix_f32 v83, v7, v22, v83 op_sel:[0,1,0] op_sel_hi:[0,1,0]
	v_add_f32_dpp v12, v12, v12 row_ror:1 row_mask:0xf bank_mask:0xf bound_ctrl:1
	v_fma_mix_f32 v83, v8, v23, v83 op_sel_hi:[0,1,0]
	v_fma_mix_f32 v83, v9, v23, v83 op_sel:[0,1,0] op_sel_hi:[0,1,0]
	v_add_f32_dpp v12, v12, v12 row_ror:2 row_mask:0xf bank_mask:0xf bound_ctrl:1
	v_pk_fma_f32 v[48:49], v[44:45], v[66:67], v[6:7] op_sel:[0,1,0]
	v_pk_fma_f32 v[50:51], v[46:47], v[66:67], v[8:9] op_sel:[0,1,0]
	v_add_f32_dpp v12, v12, v12 row_ror:4 row_mask:0xf bank_mask:0xf bound_ctrl:1
	s_nop 1
	v_add_f32_dpp v12, v12, v12 row_ror:8 row_mask:0xf bank_mask:0xf bound_ctrl:1
	v_pk_fma_f32 v[6:7], v[40:41], v[12:13], v[48:49] op_sel_hi:[1,0,1] neg_lo:[1,0,0] neg_hi:[1,0,0]
	v_pk_fma_f32 v[8:9], v[42:43], v[12:13], v[50:51] op_sel_hi:[1,0,1] neg_lo:[1,0,0] neg_hi:[1,0,0]
	ds_read_b128 v[110:113], v10 offset:27904
	ds_read_b128 v[106:109], v10 offset:27648
	ds_read_b128 v[118:121], v10 offset:28416
	ds_read_b128 v[114:117], v10 offset:28160
	ds_read_b128 v[70:73], v11 offset:1792
	s_waitcnt lgkmcnt(5)
	v_fma_mix_f32 v12, v6, v88, v180 op_sel_hi:[0,1,0]
	v_fma_mix_f32 v12, v7, v88, v12 op_sel:[0,1,0] op_sel_hi:[0,1,0]
	v_fma_mix_f32 v12, v8, v89, v12 op_sel_hi:[0,1,0]
	v_fma_mix_f32 v12, v9, v89, v12 op_sel:[0,1,0] op_sel_hi:[0,1,0]
	v_fma_mix_f32 v100, v6, v38, v180 op_sel_hi:[0,1,0]
	v_fma_mix_f32 v100, v7, v38, v100 op_sel:[0,1,0] op_sel_hi:[0,1,0]
	v_add_f32_dpp v12, v12, v12 row_ror:1 row_mask:0xf bank_mask:0xf bound_ctrl:1
	v_fma_mix_f32 v100, v8, v39, v100 op_sel_hi:[0,1,0]
	v_fma_mix_f32 v100, v9, v39, v100 op_sel:[0,1,0] op_sel_hi:[0,1,0]
	v_add_f32_dpp v12, v12, v12 row_ror:2 row_mask:0xf bank_mask:0xf bound_ctrl:1
	v_pk_fma_f32 v[48:49], v[96:97], v[68:69], v[6:7] op_sel_hi:[1,0,1]
	v_pk_fma_f32 v[50:51], v[98:99], v[68:69], v[8:9] op_sel_hi:[1,0,1]
	v_add_f32_dpp v12, v12, v12 row_ror:4 row_mask:0xf bank_mask:0xf bound_ctrl:1
	s_nop 1
	v_add_f32_dpp v12, v12, v12 row_ror:8 row_mask:0xf bank_mask:0xf bound_ctrl:1
	v_pk_fma_f32 v[6:7], v[92:93], v[12:13], v[48:49] op_sel_hi:[1,0,1] neg_lo:[1,0,0] neg_hi:[1,0,0]
	v_pk_fma_f32 v[8:9], v[94:95], v[12:13], v[50:51] op_sel_hi:[1,0,1] neg_lo:[1,0,0] neg_hi:[1,0,0]
	ds_read_b128 v[20:23], v10 offset:28928
	ds_read_b128 v[28:31], v10 offset:29440
	ds_read_b128 v[24:27], v10 offset:29184
	s_waitcnt lgkmcnt(4)
	v_fma_mix_f32 v12, v6, v110, v180 op_sel_hi:[0,1,0]
	v_fma_mix_f32 v12, v7, v110, v12 op_sel:[0,1,0] op_sel_hi:[0,1,0]
	v_fma_mix_f32 v12, v8, v111, v12 op_sel_hi:[0,1,0]
	v_fma_mix_f32 v12, v9, v111, v12 op_sel:[0,1,0] op_sel_hi:[0,1,0]
	v_fma_mix_f32 v101, v6, v90, v180 op_sel_hi:[0,1,0]
	v_fma_mix_f32 v101, v7, v90, v101 op_sel:[0,1,0] op_sel_hi:[0,1,0]
	v_add_f32_dpp v12, v12, v12 row_ror:1 row_mask:0xf bank_mask:0xf bound_ctrl:1
	v_fma_mix_f32 v101, v8, v91, v101 op_sel_hi:[0,1,0]
	v_fma_mix_f32 v101, v9, v91, v101 op_sel:[0,1,0] op_sel_hi:[0,1,0]
	v_add_f32_dpp v12, v12, v12 row_ror:2 row_mask:0xf bank_mask:0xf bound_ctrl:1
	v_pk_fma_f32 v[48:49], v[118:119], v[68:69], v[6:7] op_sel:[0,1,0]
	v_pk_fma_f32 v[50:51], v[120:121], v[68:69], v[8:9] op_sel:[0,1,0]
	v_add_f32_dpp v12, v12, v12 row_ror:4 row_mask:0xf bank_mask:0xf bound_ctrl:1
	s_nop 1
	v_add_f32_dpp v12, v12, v12 row_ror:8 row_mask:0xf bank_mask:0xf bound_ctrl:1
	v_pk_fma_f32 v[6:7], v[114:115], v[12:13], v[48:49] op_sel_hi:[1,0,1] neg_lo:[1,0,0] neg_hi:[1,0,0]
	v_pk_fma_f32 v[8:9], v[116:117], v[12:13], v[50:51] op_sel_hi:[1,0,1] neg_lo:[1,0,0] neg_hi:[1,0,0]
	v_pk_mul_f32 v[6:7], v[6:7], v[106:107]
	v_pk_mul_f32 v[8:9], v[8:9], v[108:109]
	ds_read_b128 v[36:39], v10 offset:29952
	ds_read_b128 v[44:47], v10 offset:30464
	ds_read_b128 v[40:43], v10 offset:30208
	s_waitcnt lgkmcnt(3)
	v_fma_mix_f32 v12, v6, v20, v180 op_sel_hi:[0,1,0]
	v_fma_mix_f32 v12, v7, v20, v12 op_sel:[0,1,0] op_sel_hi:[0,1,0]
	v_fma_mix_f32 v12, v8, v21, v12 op_sel_hi:[0,1,0]
	v_fma_mix_f32 v12, v9, v21, v12 op_sel:[0,1,0] op_sel_hi:[0,1,0]
	v_fma_mix_f32 v102, v6, v112, v180 op_sel_hi:[0,1,0]
	v_fma_mix_f32 v102, v7, v112, v102 op_sel:[0,1,0] op_sel_hi:[0,1,0]
	v_add_f32_dpp v12, v12, v12 row_ror:1 row_mask:0xf bank_mask:0xf bound_ctrl:1
	v_fma_mix_f32 v102, v8, v113, v102 op_sel_hi:[0,1,0]
	v_fma_mix_f32 v102, v9, v113, v102 op_sel:[0,1,0] op_sel_hi:[0,1,0]
	v_add_f32_dpp v12, v12, v12 row_ror:2 row_mask:0xf bank_mask:0xf bound_ctrl:1
	v_pk_fma_f32 v[48:49], v[28:29], v[70:71], v[6:7] op_sel_hi:[1,0,1]
	v_pk_fma_f32 v[50:51], v[30:31], v[70:71], v[8:9] op_sel_hi:[1,0,1]
	v_add_f32_dpp v12, v12, v12 row_ror:4 row_mask:0xf bank_mask:0xf bound_ctrl:1
	s_nop 1
	v_add_f32_dpp v12, v12, v12 row_ror:8 row_mask:0xf bank_mask:0xf bound_ctrl:1
	v_pk_fma_f32 v[6:7], v[24:25], v[12:13], v[48:49] op_sel_hi:[1,0,1] neg_lo:[1,0,0] neg_hi:[1,0,0]
	v_pk_fma_f32 v[8:9], v[26:27], v[12:13], v[50:51] op_sel_hi:[1,0,1] neg_lo:[1,0,0] neg_hi:[1,0,0]
	ds_read_b128 v[88:91], v10 offset:30976
	ds_read_b128 v[96:99], v10 offset:31488
	ds_read_b128 v[92:95], v10 offset:31232
	s_waitcnt lgkmcnt(3)
	v_fma_mix_f32 v12, v6, v36, v180 op_sel_hi:[0,1,0]
	v_fma_mix_f32 v12, v7, v36, v12 op_sel:[0,1,0] op_sel_hi:[0,1,0]
	v_fma_mix_f32 v12, v8, v37, v12 op_sel_hi:[0,1,0]
	v_fma_mix_f32 v12, v9, v37, v12 op_sel:[0,1,0] op_sel_hi:[0,1,0]
	v_fma_mix_f32 v103, v6, v22, v180 op_sel_hi:[0,1,0]
	v_fma_mix_f32 v103, v7, v22, v103 op_sel:[0,1,0] op_sel_hi:[0,1,0]
	v_add_f32_dpp v12, v12, v12 row_ror:1 row_mask:0xf bank_mask:0xf bound_ctrl:1
	v_fma_mix_f32 v103, v8, v23, v103 op_sel_hi:[0,1,0]
	v_fma_mix_f32 v103, v9, v23, v103 op_sel:[0,1,0] op_sel_hi:[0,1,0]
	v_add_f32_dpp v12, v12, v12 row_ror:2 row_mask:0xf bank_mask:0xf bound_ctrl:1
	v_pk_fma_f32 v[48:49], v[44:45], v[70:71], v[6:7] op_sel:[0,1,0]
	v_pk_fma_f32 v[50:51], v[46:47], v[70:71], v[8:9] op_sel:[0,1,0]
	v_add_f32_dpp v12, v12, v12 row_ror:4 row_mask:0xf bank_mask:0xf bound_ctrl:1
	s_nop 1
	v_add_f32_dpp v12, v12, v12 row_ror:8 row_mask:0xf bank_mask:0xf bound_ctrl:1
	v_pk_fma_f32 v[6:7], v[40:41], v[12:13], v[48:49] op_sel_hi:[1,0,1] neg_lo:[1,0,0] neg_hi:[1,0,0]
	v_pk_fma_f32 v[8:9], v[42:43], v[12:13], v[50:51] op_sel_hi:[1,0,1] neg_lo:[1,0,0] neg_hi:[1,0,0]
	ds_read_b128 v[110:113], v10 offset:32000
	ds_read_b128 v[106:109], v10 offset:31744
	ds_read_b128 v[118:121], v10 offset:32512
	ds_read_b128 v[114:117], v10 offset:32256
	ds_read_b128 v[66:69], v11 offset:2048
	s_waitcnt lgkmcnt(5)
	v_fma_mix_f32 v12, v6, v88, v180 op_sel_hi:[0,1,0]
	v_fma_mix_f32 v12, v7, v88, v12 op_sel:[0,1,0] op_sel_hi:[0,1,0]
	v_fma_mix_f32 v12, v8, v89, v12 op_sel_hi:[0,1,0]
	v_fma_mix_f32 v12, v9, v89, v12 op_sel:[0,1,0] op_sel_hi:[0,1,0]
	v_fma_mix_f32 v104, v6, v38, v180 op_sel_hi:[0,1,0]
	v_fma_mix_f32 v104, v7, v38, v104 op_sel:[0,1,0] op_sel_hi:[0,1,0]
	v_add_f32_dpp v12, v12, v12 row_ror:1 row_mask:0xf bank_mask:0xf bound_ctrl:1
	v_fma_mix_f32 v104, v8, v39, v104 op_sel_hi:[0,1,0]
	v_fma_mix_f32 v104, v9, v39, v104 op_sel:[0,1,0] op_sel_hi:[0,1,0]
	v_add_f32_dpp v12, v12, v12 row_ror:2 row_mask:0xf bank_mask:0xf bound_ctrl:1
	v_pk_fma_f32 v[48:49], v[96:97], v[72:73], v[6:7] op_sel_hi:[1,0,1]
	v_pk_fma_f32 v[50:51], v[98:99], v[72:73], v[8:9] op_sel_hi:[1,0,1]
	v_add_f32_dpp v12, v12, v12 row_ror:4 row_mask:0xf bank_mask:0xf bound_ctrl:1
	s_nop 1
	v_add_f32_dpp v12, v12, v12 row_ror:8 row_mask:0xf bank_mask:0xf bound_ctrl:1
	v_pk_fma_f32 v[6:7], v[92:93], v[12:13], v[48:49] op_sel_hi:[1,0,1] neg_lo:[1,0,0] neg_hi:[1,0,0]
	v_pk_fma_f32 v[8:9], v[94:95], v[12:13], v[50:51] op_sel_hi:[1,0,1] neg_lo:[1,0,0] neg_hi:[1,0,0]
	ds_read_b128 v[20:23], v10 offset:33024
	ds_read_b128 v[28:31], v10 offset:33536
	ds_read_b128 v[24:27], v10 offset:33280
	s_waitcnt lgkmcnt(4)
	v_fma_mix_f32 v12, v6, v110, v180 op_sel_hi:[0,1,0]
	v_fma_mix_f32 v12, v7, v110, v12 op_sel:[0,1,0] op_sel_hi:[0,1,0]
	v_fma_mix_f32 v12, v8, v111, v12 op_sel_hi:[0,1,0]
	v_fma_mix_f32 v12, v9, v111, v12 op_sel:[0,1,0] op_sel_hi:[0,1,0]
	v_fma_mix_f32 v105, v6, v90, v180 op_sel_hi:[0,1,0]
	v_fma_mix_f32 v105, v7, v90, v105 op_sel:[0,1,0] op_sel_hi:[0,1,0]
	v_add_f32_dpp v12, v12, v12 row_ror:1 row_mask:0xf bank_mask:0xf bound_ctrl:1
	v_fma_mix_f32 v105, v8, v91, v105 op_sel_hi:[0,1,0]
	v_fma_mix_f32 v105, v9, v91, v105 op_sel:[0,1,0] op_sel_hi:[0,1,0]
	v_add_f32_dpp v12, v12, v12 row_ror:2 row_mask:0xf bank_mask:0xf bound_ctrl:1
	v_pk_fma_f32 v[48:49], v[118:119], v[72:73], v[6:7] op_sel:[0,1,0]
	v_pk_fma_f32 v[50:51], v[120:121], v[72:73], v[8:9] op_sel:[0,1,0]
	v_add_f32_dpp v12, v12, v12 row_ror:4 row_mask:0xf bank_mask:0xf bound_ctrl:1
	s_nop 1
	v_add_f32_dpp v12, v12, v12 row_ror:8 row_mask:0xf bank_mask:0xf bound_ctrl:1
	v_pk_fma_f32 v[6:7], v[114:115], v[12:13], v[48:49] op_sel_hi:[1,0,1] neg_lo:[1,0,0] neg_hi:[1,0,0]
	v_pk_fma_f32 v[8:9], v[116:117], v[12:13], v[50:51] op_sel_hi:[1,0,1] neg_lo:[1,0,0] neg_hi:[1,0,0]
	v_pk_mul_f32 v[6:7], v[6:7], v[106:107]
	v_pk_mul_f32 v[8:9], v[8:9], v[108:109]
	ds_read_b128 v[36:39], v10 offset:34048
	ds_read_b128 v[44:47], v10 offset:34560
	ds_read_b128 v[40:43], v10 offset:34304
	s_waitcnt lgkmcnt(3)
	v_fma_mix_f32 v12, v6, v20, v180 op_sel_hi:[0,1,0]
	v_fma_mix_f32 v12, v7, v20, v12 op_sel:[0,1,0] op_sel_hi:[0,1,0]
	v_fma_mix_f32 v12, v8, v21, v12 op_sel_hi:[0,1,0]
	v_fma_mix_f32 v12, v9, v21, v12 op_sel:[0,1,0] op_sel_hi:[0,1,0]
	v_fma_mix_f32 v61, v6, v112, v180 op_sel_hi:[0,1,0]
	v_fma_mix_f32 v61, v7, v112, v61 op_sel:[0,1,0] op_sel_hi:[0,1,0]
	v_add_f32_dpp v12, v12, v12 row_ror:1 row_mask:0xf bank_mask:0xf bound_ctrl:1
	v_fma_mix_f32 v61, v8, v113, v61 op_sel_hi:[0,1,0]
	v_fma_mix_f32 v61, v9, v113, v61 op_sel:[0,1,0] op_sel_hi:[0,1,0]
	v_add_f32_dpp v12, v12, v12 row_ror:2 row_mask:0xf bank_mask:0xf bound_ctrl:1
	v_pk_fma_f32 v[48:49], v[28:29], v[66:67], v[6:7] op_sel_hi:[1,0,1]
	v_pk_fma_f32 v[50:51], v[30:31], v[66:67], v[8:9] op_sel_hi:[1,0,1]
	v_add_f32_dpp v12, v12, v12 row_ror:4 row_mask:0xf bank_mask:0xf bound_ctrl:1
	s_nop 1
	v_add_f32_dpp v12, v12, v12 row_ror:8 row_mask:0xf bank_mask:0xf bound_ctrl:1
	v_pk_fma_f32 v[6:7], v[24:25], v[12:13], v[48:49] op_sel_hi:[1,0,1] neg_lo:[1,0,0] neg_hi:[1,0,0]
	v_pk_fma_f32 v[8:9], v[26:27], v[12:13], v[50:51] op_sel_hi:[1,0,1] neg_lo:[1,0,0] neg_hi:[1,0,0]
	ds_read_b128 v[88:91], v10 offset:35072
	ds_read_b128 v[96:99], v10 offset:35584
	ds_read_b128 v[92:95], v10 offset:35328
	v_add_f32_dpp v83, v83, v83 row_ror:8 row_mask:0xf bank_mask:0xc
	v_add_f32_dpp v83, v52, v52 row_ror:8 row_mask:0xf bank_mask:0x3
	v_add_f32_dpp v100, v100, v100 row_ror:8 row_mask:0xf bank_mask:0xc
	v_add_f32_dpp v100, v53, v53 row_ror:8 row_mask:0xf bank_mask:0x3
	v_add_f32_dpp v101, v101, v101 row_ror:8 row_mask:0xf bank_mask:0xc
	v_add_f32_dpp v101, v54, v54 row_ror:8 row_mask:0xf bank_mask:0x3
	v_add_f32_dpp v102, v102, v102 row_ror:8 row_mask:0xf bank_mask:0xc
	v_add_f32_dpp v102, v55, v55 row_ror:8 row_mask:0xf bank_mask:0x3
	v_add_f32_dpp v103, v103, v103 row_ror:8 row_mask:0xf bank_mask:0xc
	v_add_f32_dpp v103, v56, v56 row_ror:8 row_mask:0xf bank_mask:0x3
	v_add_f32_dpp v104, v104, v104 row_ror:8 row_mask:0xf bank_mask:0xc
	v_add_f32_dpp v104, v57, v57 row_ror:8 row_mask:0xf bank_mask:0x3
	v_add_f32_dpp v105, v105, v105 row_ror:8 row_mask:0xf bank_mask:0xc
	v_add_f32_dpp v105, v81, v81 row_ror:8 row_mask:0xf bank_mask:0x3
	v_add_f32_dpp v61, v61, v61 row_ror:8 row_mask:0xf bank_mask:0xc
	v_add_f32_dpp v61, v82, v82 row_ror:8 row_mask:0xf bank_mask:0x3
	v_add_f32_dpp v103, v103, v103 row_ror:4 row_mask:0xf bank_mask:0xa
	v_add_f32_dpp v103, v83, v83 row_ror:12 row_mask:0xf bank_mask:0x5
	v_add_f32_dpp v104, v104, v104 row_ror:4 row_mask:0xf bank_mask:0xa
	v_add_f32_dpp v104, v100, v100 row_ror:12 row_mask:0xf bank_mask:0x5
	v_add_f32_dpp v105, v105, v105 row_ror:4 row_mask:0xf bank_mask:0xa
	v_add_f32_dpp v105, v101, v101 row_ror:12 row_mask:0xf bank_mask:0x5
	v_add_f32_dpp v61, v61, v61 row_ror:4 row_mask:0xf bank_mask:0xa
	v_add_f32_dpp v61, v102, v102 row_ror:12 row_mask:0xf bank_mask:0x5
	v_cndmask_b32_e64 v62, v105, v103, s[38:39]
	v_cndmask_b32_e64 v63, v103, v105, s[38:39]
	v_cndmask_b32_e64 v64, v61, v104, s[38:39]
	v_cndmask_b32_e64 v65, v104, v61, s[38:39]
	v_add_f32_dpp v62, v63, v62 quad_perm:[2,3,0,1] row_mask:0xf bank_mask:0xf bound_ctrl:1
	s_nop 0
	v_add_f32_dpp v63, v65, v64 quad_perm:[2,3,0,1] row_mask:0xf bank_mask:0xf bound_ctrl:1
	v_cndmask_b32_e64 v65, v63, v62, s[40:41]
	v_cndmask_b32_e64 v62, v62, v63, s[40:41]
	s_nop 1
	v_add_f32_dpp v62, v62, v65 quad_perm:[1,0,3,2] row_mask:0xf bank_mask:0xf bound_ctrl:1
	v_cvt_pk_bf16_f32 v62, v62, v62
	global_store_short v[2:3], v62, off
	v_lshl_add_u64 v[2:3], v[2:3], 0, s[84:85]
	s_waitcnt lgkmcnt(3)
	v_fma_mix_f32 v12, v6, v36, v180 op_sel_hi:[0,1,0]
	v_fma_mix_f32 v12, v7, v36, v12 op_sel:[0,1,0] op_sel_hi:[0,1,0]
	v_fma_mix_f32 v12, v8, v37, v12 op_sel_hi:[0,1,0]
	v_fma_mix_f32 v12, v9, v37, v12 op_sel:[0,1,0] op_sel_hi:[0,1,0]
	v_fma_mix_f32 v52, v6, v22, v180 op_sel_hi:[0,1,0]
	v_fma_mix_f32 v52, v7, v22, v52 op_sel:[0,1,0] op_sel_hi:[0,1,0]
	v_add_f32_dpp v12, v12, v12 row_ror:1 row_mask:0xf bank_mask:0xf bound_ctrl:1
	v_fma_mix_f32 v52, v8, v23, v52 op_sel_hi:[0,1,0]
	v_fma_mix_f32 v52, v9, v23, v52 op_sel:[0,1,0] op_sel_hi:[0,1,0]
	v_add_f32_dpp v12, v12, v12 row_ror:2 row_mask:0xf bank_mask:0xf bound_ctrl:1
	v_pk_fma_f32 v[48:49], v[44:45], v[66:67], v[6:7] op_sel:[0,1,0]
	v_pk_fma_f32 v[50:51], v[46:47], v[66:67], v[8:9] op_sel:[0,1,0]
	v_add_f32_dpp v12, v12, v12 row_ror:4 row_mask:0xf bank_mask:0xf bound_ctrl:1
	s_nop 1
	v_add_f32_dpp v12, v12, v12 row_ror:8 row_mask:0xf bank_mask:0xf bound_ctrl:1
	v_pk_fma_f32 v[6:7], v[40:41], v[12:13], v[48:49] op_sel_hi:[1,0,1] neg_lo:[1,0,0] neg_hi:[1,0,0]
	v_pk_fma_f32 v[8:9], v[42:43], v[12:13], v[50:51] op_sel_hi:[1,0,1] neg_lo:[1,0,0] neg_hi:[1,0,0]
	ds_read_b128 v[110:113], v10 offset:36096
	ds_read_b128 v[106:109], v10 offset:35840
	ds_read_b128 v[118:121], v10 offset:36608
	ds_read_b128 v[114:117], v10 offset:36352
	ds_read_b128 v[70:73], v11 offset:2304
	s_waitcnt lgkmcnt(5)
	v_fma_mix_f32 v12, v6, v88, v180 op_sel_hi:[0,1,0]
	v_fma_mix_f32 v12, v7, v88, v12 op_sel:[0,1,0] op_sel_hi:[0,1,0]
	v_fma_mix_f32 v12, v8, v89, v12 op_sel_hi:[0,1,0]
	v_fma_mix_f32 v12, v9, v89, v12 op_sel:[0,1,0] op_sel_hi:[0,1,0]
	v_fma_mix_f32 v53, v6, v38, v180 op_sel_hi:[0,1,0]
	v_fma_mix_f32 v53, v7, v38, v53 op_sel:[0,1,0] op_sel_hi:[0,1,0]
	v_add_f32_dpp v12, v12, v12 row_ror:1 row_mask:0xf bank_mask:0xf bound_ctrl:1
	v_fma_mix_f32 v53, v8, v39, v53 op_sel_hi:[0,1,0]
	v_fma_mix_f32 v53, v9, v39, v53 op_sel:[0,1,0] op_sel_hi:[0,1,0]
	v_add_f32_dpp v12, v12, v12 row_ror:2 row_mask:0xf bank_mask:0xf bound_ctrl:1
	v_pk_fma_f32 v[48:49], v[96:97], v[68:69], v[6:7] op_sel_hi:[1,0,1]
	v_pk_fma_f32 v[50:51], v[98:99], v[68:69], v[8:9] op_sel_hi:[1,0,1]
	v_add_f32_dpp v12, v12, v12 row_ror:4 row_mask:0xf bank_mask:0xf bound_ctrl:1
	s_nop 1
	v_add_f32_dpp v12, v12, v12 row_ror:8 row_mask:0xf bank_mask:0xf bound_ctrl:1
	v_pk_fma_f32 v[6:7], v[92:93], v[12:13], v[48:49] op_sel_hi:[1,0,1] neg_lo:[1,0,0] neg_hi:[1,0,0]
	v_pk_fma_f32 v[8:9], v[94:95], v[12:13], v[50:51] op_sel_hi:[1,0,1] neg_lo:[1,0,0] neg_hi:[1,0,0]
	ds_read_b128 v[20:23], v10 offset:37120
	ds_read_b128 v[28:31], v10 offset:37632
	ds_read_b128 v[24:27], v10 offset:37376
	s_waitcnt lgkmcnt(4)
	v_fma_mix_f32 v12, v6, v110, v180 op_sel_hi:[0,1,0]
	v_fma_mix_f32 v12, v7, v110, v12 op_sel:[0,1,0] op_sel_hi:[0,1,0]
	v_fma_mix_f32 v12, v8, v111, v12 op_sel_hi:[0,1,0]
	v_fma_mix_f32 v12, v9, v111, v12 op_sel:[0,1,0] op_sel_hi:[0,1,0]
	v_fma_mix_f32 v54, v6, v90, v180 op_sel_hi:[0,1,0]
	v_fma_mix_f32 v54, v7, v90, v54 op_sel:[0,1,0] op_sel_hi:[0,1,0]
	v_add_f32_dpp v12, v12, v12 row_ror:1 row_mask:0xf bank_mask:0xf bound_ctrl:1
	v_fma_mix_f32 v54, v8, v91, v54 op_sel_hi:[0,1,0]
	v_fma_mix_f32 v54, v9, v91, v54 op_sel:[0,1,0] op_sel_hi:[0,1,0]
	v_add_f32_dpp v12, v12, v12 row_ror:2 row_mask:0xf bank_mask:0xf bound_ctrl:1
	v_pk_fma_f32 v[48:49], v[118:119], v[68:69], v[6:7] op_sel:[0,1,0]
	v_pk_fma_f32 v[50:51], v[120:121], v[68:69], v[8:9] op_sel:[0,1,0]
	v_add_f32_dpp v12, v12, v12 row_ror:4 row_mask:0xf bank_mask:0xf bound_ctrl:1
	s_nop 1
	v_add_f32_dpp v12, v12, v12 row_ror:8 row_mask:0xf bank_mask:0xf bound_ctrl:1
	v_pk_fma_f32 v[6:7], v[114:115], v[12:13], v[48:49] op_sel_hi:[1,0,1] neg_lo:[1,0,0] neg_hi:[1,0,0]
	v_pk_fma_f32 v[8:9], v[116:117], v[12:13], v[50:51] op_sel_hi:[1,0,1] neg_lo:[1,0,0] neg_hi:[1,0,0]
	v_pk_mul_f32 v[6:7], v[6:7], v[106:107]
	v_pk_mul_f32 v[8:9], v[8:9], v[108:109]
	ds_read_b128 v[36:39], v10 offset:38144
	ds_read_b128 v[44:47], v10 offset:38656
	ds_read_b128 v[40:43], v10 offset:38400
	s_waitcnt lgkmcnt(3)
	v_fma_mix_f32 v12, v6, v20, v180 op_sel_hi:[0,1,0]
	v_fma_mix_f32 v12, v7, v20, v12 op_sel:[0,1,0] op_sel_hi:[0,1,0]
	v_fma_mix_f32 v12, v8, v21, v12 op_sel_hi:[0,1,0]
	v_fma_mix_f32 v12, v9, v21, v12 op_sel:[0,1,0] op_sel_hi:[0,1,0]
	v_fma_mix_f32 v55, v6, v112, v180 op_sel_hi:[0,1,0]
	v_fma_mix_f32 v55, v7, v112, v55 op_sel:[0,1,0] op_sel_hi:[0,1,0]
	v_add_f32_dpp v12, v12, v12 row_ror:1 row_mask:0xf bank_mask:0xf bound_ctrl:1
	v_fma_mix_f32 v55, v8, v113, v55 op_sel_hi:[0,1,0]
	v_fma_mix_f32 v55, v9, v113, v55 op_sel:[0,1,0] op_sel_hi:[0,1,0]
	v_add_f32_dpp v12, v12, v12 row_ror:2 row_mask:0xf bank_mask:0xf bound_ctrl:1
	v_pk_fma_f32 v[48:49], v[28:29], v[70:71], v[6:7] op_sel_hi:[1,0,1]
	v_pk_fma_f32 v[50:51], v[30:31], v[70:71], v[8:9] op_sel_hi:[1,0,1]
	v_add_f32_dpp v12, v12, v12 row_ror:4 row_mask:0xf bank_mask:0xf bound_ctrl:1
	s_nop 1
	v_add_f32_dpp v12, v12, v12 row_ror:8 row_mask:0xf bank_mask:0xf bound_ctrl:1
	v_pk_fma_f32 v[6:7], v[24:25], v[12:13], v[48:49] op_sel_hi:[1,0,1] neg_lo:[1,0,0] neg_hi:[1,0,0]
	v_pk_fma_f32 v[8:9], v[26:27], v[12:13], v[50:51] op_sel_hi:[1,0,1] neg_lo:[1,0,0] neg_hi:[1,0,0]
	ds_read_b128 v[88:91], v10 offset:39168
	ds_read_b128 v[96:99], v10 offset:39680
	ds_read_b128 v[92:95], v10 offset:39424
	s_waitcnt lgkmcnt(3)
	v_fma_mix_f32 v12, v6, v36, v180 op_sel_hi:[0,1,0]
	v_fma_mix_f32 v12, v7, v36, v12 op_sel:[0,1,0] op_sel_hi:[0,1,0]
	v_fma_mix_f32 v12, v8, v37, v12 op_sel_hi:[0,1,0]
	v_fma_mix_f32 v12, v9, v37, v12 op_sel:[0,1,0] op_sel_hi:[0,1,0]
	v_fma_mix_f32 v56, v6, v22, v180 op_sel_hi:[0,1,0]
	v_fma_mix_f32 v56, v7, v22, v56 op_sel:[0,1,0] op_sel_hi:[0,1,0]
	v_add_f32_dpp v12, v12, v12 row_ror:1 row_mask:0xf bank_mask:0xf bound_ctrl:1
	v_fma_mix_f32 v56, v8, v23, v56 op_sel_hi:[0,1,0]
	v_fma_mix_f32 v56, v9, v23, v56 op_sel:[0,1,0] op_sel_hi:[0,1,0]
	v_add_f32_dpp v12, v12, v12 row_ror:2 row_mask:0xf bank_mask:0xf bound_ctrl:1
	v_pk_fma_f32 v[48:49], v[44:45], v[70:71], v[6:7] op_sel:[0,1,0]
	v_pk_fma_f32 v[50:51], v[46:47], v[70:71], v[8:9] op_sel:[0,1,0]
	v_add_f32_dpp v12, v12, v12 row_ror:4 row_mask:0xf bank_mask:0xf bound_ctrl:1
	s_nop 1
	v_add_f32_dpp v12, v12, v12 row_ror:8 row_mask:0xf bank_mask:0xf bound_ctrl:1
	v_pk_fma_f32 v[6:7], v[40:41], v[12:13], v[48:49] op_sel_hi:[1,0,1] neg_lo:[1,0,0] neg_hi:[1,0,0]
	v_pk_fma_f32 v[8:9], v[42:43], v[12:13], v[50:51] op_sel_hi:[1,0,1] neg_lo:[1,0,0] neg_hi:[1,0,0]
	ds_read_b128 v[110:113], v10 offset:40192
	ds_read_b128 v[106:109], v10 offset:39936
	ds_read_b128 v[118:121], v10 offset:40704
	ds_read_b128 v[114:117], v10 offset:40448
	ds_read_b128 v[66:69], v11 offset:2560
	s_waitcnt lgkmcnt(5)
	v_fma_mix_f32 v12, v6, v88, v180 op_sel_hi:[0,1,0]
	v_fma_mix_f32 v12, v7, v88, v12 op_sel:[0,1,0] op_sel_hi:[0,1,0]
	v_fma_mix_f32 v12, v8, v89, v12 op_sel_hi:[0,1,0]
	v_fma_mix_f32 v12, v9, v89, v12 op_sel:[0,1,0] op_sel_hi:[0,1,0]
	v_fma_mix_f32 v57, v6, v38, v180 op_sel_hi:[0,1,0]
	v_fma_mix_f32 v57, v7, v38, v57 op_sel:[0,1,0] op_sel_hi:[0,1,0]
	v_add_f32_dpp v12, v12, v12 row_ror:1 row_mask:0xf bank_mask:0xf bound_ctrl:1
	v_fma_mix_f32 v57, v8, v39, v57 op_sel_hi:[0,1,0]
	v_fma_mix_f32 v57, v9, v39, v57 op_sel:[0,1,0] op_sel_hi:[0,1,0]
	v_add_f32_dpp v12, v12, v12 row_ror:2 row_mask:0xf bank_mask:0xf bound_ctrl:1
	v_pk_fma_f32 v[48:49], v[96:97], v[72:73], v[6:7] op_sel_hi:[1,0,1]
	v_pk_fma_f32 v[50:51], v[98:99], v[72:73], v[8:9] op_sel_hi:[1,0,1]
	v_add_f32_dpp v12, v12, v12 row_ror:4 row_mask:0xf bank_mask:0xf bound_ctrl:1
	s_nop 1
	v_add_f32_dpp v12, v12, v12 row_ror:8 row_mask:0xf bank_mask:0xf bound_ctrl:1
	v_pk_fma_f32 v[6:7], v[92:93], v[12:13], v[48:49] op_sel_hi:[1,0,1] neg_lo:[1,0,0] neg_hi:[1,0,0]
	v_pk_fma_f32 v[8:9], v[94:95], v[12:13], v[50:51] op_sel_hi:[1,0,1] neg_lo:[1,0,0] neg_hi:[1,0,0]
	ds_read_b128 v[20:23], v10 offset:41216
	ds_read_b128 v[28:31], v10 offset:41728
	ds_read_b128 v[24:27], v10 offset:41472
	s_waitcnt lgkmcnt(4)
	v_fma_mix_f32 v12, v6, v110, v180 op_sel_hi:[0,1,0]
	v_fma_mix_f32 v12, v7, v110, v12 op_sel:[0,1,0] op_sel_hi:[0,1,0]
	v_fma_mix_f32 v12, v8, v111, v12 op_sel_hi:[0,1,0]
	v_fma_mix_f32 v12, v9, v111, v12 op_sel:[0,1,0] op_sel_hi:[0,1,0]
	v_fma_mix_f32 v81, v6, v90, v180 op_sel_hi:[0,1,0]
	v_fma_mix_f32 v81, v7, v90, v81 op_sel:[0,1,0] op_sel_hi:[0,1,0]
	v_add_f32_dpp v12, v12, v12 row_ror:1 row_mask:0xf bank_mask:0xf bound_ctrl:1
	v_fma_mix_f32 v81, v8, v91, v81 op_sel_hi:[0,1,0]
	v_fma_mix_f32 v81, v9, v91, v81 op_sel:[0,1,0] op_sel_hi:[0,1,0]
	v_add_f32_dpp v12, v12, v12 row_ror:2 row_mask:0xf bank_mask:0xf bound_ctrl:1
	v_pk_fma_f32 v[48:49], v[118:119], v[72:73], v[6:7] op_sel:[0,1,0]
	v_pk_fma_f32 v[50:51], v[120:121], v[72:73], v[8:9] op_sel:[0,1,0]
	v_add_f32_dpp v12, v12, v12 row_ror:4 row_mask:0xf bank_mask:0xf bound_ctrl:1
	s_nop 1
	v_add_f32_dpp v12, v12, v12 row_ror:8 row_mask:0xf bank_mask:0xf bound_ctrl:1
	v_pk_fma_f32 v[6:7], v[114:115], v[12:13], v[48:49] op_sel_hi:[1,0,1] neg_lo:[1,0,0] neg_hi:[1,0,0]
	v_pk_fma_f32 v[8:9], v[116:117], v[12:13], v[50:51] op_sel_hi:[1,0,1] neg_lo:[1,0,0] neg_hi:[1,0,0]
	v_pk_mul_f32 v[6:7], v[6:7], v[106:107]
	v_pk_mul_f32 v[8:9], v[8:9], v[108:109]
	ds_read_b128 v[36:39], v10 offset:42240
	ds_read_b128 v[44:47], v10 offset:42752
	ds_read_b128 v[40:43], v10 offset:42496
	s_waitcnt lgkmcnt(3)
	v_fma_mix_f32 v12, v6, v20, v180 op_sel_hi:[0,1,0]
	v_fma_mix_f32 v12, v7, v20, v12 op_sel:[0,1,0] op_sel_hi:[0,1,0]
	v_fma_mix_f32 v12, v8, v21, v12 op_sel_hi:[0,1,0]
	v_fma_mix_f32 v12, v9, v21, v12 op_sel:[0,1,0] op_sel_hi:[0,1,0]
	v_fma_mix_f32 v82, v6, v112, v180 op_sel_hi:[0,1,0]
	v_fma_mix_f32 v82, v7, v112, v82 op_sel:[0,1,0] op_sel_hi:[0,1,0]
	v_add_f32_dpp v12, v12, v12 row_ror:1 row_mask:0xf bank_mask:0xf bound_ctrl:1
	v_fma_mix_f32 v82, v8, v113, v82 op_sel_hi:[0,1,0]
	v_fma_mix_f32 v82, v9, v113, v82 op_sel:[0,1,0] op_sel_hi:[0,1,0]
	v_add_f32_dpp v12, v12, v12 row_ror:2 row_mask:0xf bank_mask:0xf bound_ctrl:1
	v_pk_fma_f32 v[48:49], v[28:29], v[66:67], v[6:7] op_sel_hi:[1,0,1]
	v_pk_fma_f32 v[50:51], v[30:31], v[66:67], v[8:9] op_sel_hi:[1,0,1]
	v_add_f32_dpp v12, v12, v12 row_ror:4 row_mask:0xf bank_mask:0xf bound_ctrl:1
	s_nop 1
	v_add_f32_dpp v12, v12, v12 row_ror:8 row_mask:0xf bank_mask:0xf bound_ctrl:1
	v_pk_fma_f32 v[6:7], v[24:25], v[12:13], v[48:49] op_sel_hi:[1,0,1] neg_lo:[1,0,0] neg_hi:[1,0,0]
	v_pk_fma_f32 v[8:9], v[26:27], v[12:13], v[50:51] op_sel_hi:[1,0,1] neg_lo:[1,0,0] neg_hi:[1,0,0]
	ds_read_b128 v[88:91], v10 offset:43264
	ds_read_b128 v[96:99], v10 offset:43776
	ds_read_b128 v[92:95], v10 offset:43520
	s_waitcnt lgkmcnt(3)
	v_fma_mix_f32 v12, v6, v36, v180 op_sel_hi:[0,1,0]
	v_fma_mix_f32 v12, v7, v36, v12 op_sel:[0,1,0] op_sel_hi:[0,1,0]
	v_fma_mix_f32 v12, v8, v37, v12 op_sel_hi:[0,1,0]
	v_fma_mix_f32 v12, v9, v37, v12 op_sel:[0,1,0] op_sel_hi:[0,1,0]
	v_fma_mix_f32 v83, v6, v22, v180 op_sel_hi:[0,1,0]
	v_fma_mix_f32 v83, v7, v22, v83 op_sel:[0,1,0] op_sel_hi:[0,1,0]
	v_add_f32_dpp v12, v12, v12 row_ror:1 row_mask:0xf bank_mask:0xf bound_ctrl:1
	v_fma_mix_f32 v83, v8, v23, v83 op_sel_hi:[0,1,0]
	v_fma_mix_f32 v83, v9, v23, v83 op_sel:[0,1,0] op_sel_hi:[0,1,0]
	v_add_f32_dpp v12, v12, v12 row_ror:2 row_mask:0xf bank_mask:0xf bound_ctrl:1
	v_pk_fma_f32 v[48:49], v[44:45], v[66:67], v[6:7] op_sel:[0,1,0]
	v_pk_fma_f32 v[50:51], v[46:47], v[66:67], v[8:9] op_sel:[0,1,0]
	v_add_f32_dpp v12, v12, v12 row_ror:4 row_mask:0xf bank_mask:0xf bound_ctrl:1
	s_nop 1
	v_add_f32_dpp v12, v12, v12 row_ror:8 row_mask:0xf bank_mask:0xf bound_ctrl:1
	v_pk_fma_f32 v[6:7], v[40:41], v[12:13], v[48:49] op_sel_hi:[1,0,1] neg_lo:[1,0,0] neg_hi:[1,0,0]
	v_pk_fma_f32 v[8:9], v[42:43], v[12:13], v[50:51] op_sel_hi:[1,0,1] neg_lo:[1,0,0] neg_hi:[1,0,0]
	ds_read_b128 v[110:113], v10 offset:44288
	ds_read_b128 v[106:109], v10 offset:44032
	ds_read_b128 v[118:121], v10 offset:44800
	ds_read_b128 v[114:117], v10 offset:44544
	ds_read_b128 v[70:73], v11 offset:2816
	s_waitcnt lgkmcnt(5)
	v_fma_mix_f32 v12, v6, v88, v180 op_sel_hi:[0,1,0]
	v_fma_mix_f32 v12, v7, v88, v12 op_sel:[0,1,0] op_sel_hi:[0,1,0]
	v_fma_mix_f32 v12, v8, v89, v12 op_sel_hi:[0,1,0]
	v_fma_mix_f32 v12, v9, v89, v12 op_sel:[0,1,0] op_sel_hi:[0,1,0]
	v_fma_mix_f32 v100, v6, v38, v180 op_sel_hi:[0,1,0]
	v_fma_mix_f32 v100, v7, v38, v100 op_sel:[0,1,0] op_sel_hi:[0,1,0]
	v_add_f32_dpp v12, v12, v12 row_ror:1 row_mask:0xf bank_mask:0xf bound_ctrl:1
	v_fma_mix_f32 v100, v8, v39, v100 op_sel_hi:[0,1,0]
	v_fma_mix_f32 v100, v9, v39, v100 op_sel:[0,1,0] op_sel_hi:[0,1,0]
	v_add_f32_dpp v12, v12, v12 row_ror:2 row_mask:0xf bank_mask:0xf bound_ctrl:1
	v_pk_fma_f32 v[48:49], v[96:97], v[68:69], v[6:7] op_sel_hi:[1,0,1]
	v_pk_fma_f32 v[50:51], v[98:99], v[68:69], v[8:9] op_sel_hi:[1,0,1]
	v_add_f32_dpp v12, v12, v12 row_ror:4 row_mask:0xf bank_mask:0xf bound_ctrl:1
	s_nop 1
	v_add_f32_dpp v12, v12, v12 row_ror:8 row_mask:0xf bank_mask:0xf bound_ctrl:1
	v_pk_fma_f32 v[6:7], v[92:93], v[12:13], v[48:49] op_sel_hi:[1,0,1] neg_lo:[1,0,0] neg_hi:[1,0,0]
	v_pk_fma_f32 v[8:9], v[94:95], v[12:13], v[50:51] op_sel_hi:[1,0,1] neg_lo:[1,0,0] neg_hi:[1,0,0]
	ds_read_b128 v[20:23], v10 offset:45312
	ds_read_b128 v[28:31], v10 offset:45824
	ds_read_b128 v[24:27], v10 offset:45568
	s_waitcnt lgkmcnt(4)
	v_fma_mix_f32 v12, v6, v110, v180 op_sel_hi:[0,1,0]
	v_fma_mix_f32 v12, v7, v110, v12 op_sel:[0,1,0] op_sel_hi:[0,1,0]
	v_fma_mix_f32 v12, v8, v111, v12 op_sel_hi:[0,1,0]
	v_fma_mix_f32 v12, v9, v111, v12 op_sel:[0,1,0] op_sel_hi:[0,1,0]
	v_fma_mix_f32 v101, v6, v90, v180 op_sel_hi:[0,1,0]
	v_fma_mix_f32 v101, v7, v90, v101 op_sel:[0,1,0] op_sel_hi:[0,1,0]
	v_add_f32_dpp v12, v12, v12 row_ror:1 row_mask:0xf bank_mask:0xf bound_ctrl:1
	v_fma_mix_f32 v101, v8, v91, v101 op_sel_hi:[0,1,0]
	v_fma_mix_f32 v101, v9, v91, v101 op_sel:[0,1,0] op_sel_hi:[0,1,0]
	v_add_f32_dpp v12, v12, v12 row_ror:2 row_mask:0xf bank_mask:0xf bound_ctrl:1
	v_pk_fma_f32 v[48:49], v[118:119], v[68:69], v[6:7] op_sel:[0,1,0]
	v_pk_fma_f32 v[50:51], v[120:121], v[68:69], v[8:9] op_sel:[0,1,0]
	v_add_f32_dpp v12, v12, v12 row_ror:4 row_mask:0xf bank_mask:0xf bound_ctrl:1
	s_nop 1
	v_add_f32_dpp v12, v12, v12 row_ror:8 row_mask:0xf bank_mask:0xf bound_ctrl:1
	v_pk_fma_f32 v[6:7], v[114:115], v[12:13], v[48:49] op_sel_hi:[1,0,1] neg_lo:[1,0,0] neg_hi:[1,0,0]
	v_pk_fma_f32 v[8:9], v[116:117], v[12:13], v[50:51] op_sel_hi:[1,0,1] neg_lo:[1,0,0] neg_hi:[1,0,0]
	v_pk_mul_f32 v[6:7], v[6:7], v[106:107]
	v_pk_mul_f32 v[8:9], v[8:9], v[108:109]
	ds_read_b128 v[36:39], v10 offset:46336
	ds_read_b128 v[44:47], v10 offset:46848
	ds_read_b128 v[40:43], v10 offset:46592
	s_waitcnt lgkmcnt(3)
	v_fma_mix_f32 v12, v6, v20, v180 op_sel_hi:[0,1,0]
	v_fma_mix_f32 v12, v7, v20, v12 op_sel:[0,1,0] op_sel_hi:[0,1,0]
	v_fma_mix_f32 v12, v8, v21, v12 op_sel_hi:[0,1,0]
	v_fma_mix_f32 v12, v9, v21, v12 op_sel:[0,1,0] op_sel_hi:[0,1,0]
	v_fma_mix_f32 v102, v6, v112, v180 op_sel_hi:[0,1,0]
	v_fma_mix_f32 v102, v7, v112, v102 op_sel:[0,1,0] op_sel_hi:[0,1,0]
	v_add_f32_dpp v12, v12, v12 row_ror:1 row_mask:0xf bank_mask:0xf bound_ctrl:1
	v_fma_mix_f32 v102, v8, v113, v102 op_sel_hi:[0,1,0]
	v_fma_mix_f32 v102, v9, v113, v102 op_sel:[0,1,0] op_sel_hi:[0,1,0]
	v_add_f32_dpp v12, v12, v12 row_ror:2 row_mask:0xf bank_mask:0xf bound_ctrl:1
	v_pk_fma_f32 v[48:49], v[28:29], v[70:71], v[6:7] op_sel_hi:[1,0,1]
	v_pk_fma_f32 v[50:51], v[30:31], v[70:71], v[8:9] op_sel_hi:[1,0,1]
	v_add_f32_dpp v12, v12, v12 row_ror:4 row_mask:0xf bank_mask:0xf bound_ctrl:1
	s_nop 1
	v_add_f32_dpp v12, v12, v12 row_ror:8 row_mask:0xf bank_mask:0xf bound_ctrl:1
	v_pk_fma_f32 v[6:7], v[24:25], v[12:13], v[48:49] op_sel_hi:[1,0,1] neg_lo:[1,0,0] neg_hi:[1,0,0]
	v_pk_fma_f32 v[8:9], v[26:27], v[12:13], v[50:51] op_sel_hi:[1,0,1] neg_lo:[1,0,0] neg_hi:[1,0,0]
	ds_read_b128 v[88:91], v10 offset:47360
	ds_read_b128 v[96:99], v10 offset:47872
	ds_read_b128 v[92:95], v10 offset:47616
	s_waitcnt lgkmcnt(3)
	v_fma_mix_f32 v12, v6, v36, v180 op_sel_hi:[0,1,0]
	v_fma_mix_f32 v12, v7, v36, v12 op_sel:[0,1,0] op_sel_hi:[0,1,0]
	v_fma_mix_f32 v12, v8, v37, v12 op_sel_hi:[0,1,0]
	v_fma_mix_f32 v12, v9, v37, v12 op_sel:[0,1,0] op_sel_hi:[0,1,0]
	v_fma_mix_f32 v103, v6, v22, v180 op_sel_hi:[0,1,0]
	v_fma_mix_f32 v103, v7, v22, v103 op_sel:[0,1,0] op_sel_hi:[0,1,0]
	v_add_f32_dpp v12, v12, v12 row_ror:1 row_mask:0xf bank_mask:0xf bound_ctrl:1
	v_fma_mix_f32 v103, v8, v23, v103 op_sel_hi:[0,1,0]
	v_fma_mix_f32 v103, v9, v23, v103 op_sel:[0,1,0] op_sel_hi:[0,1,0]
	v_add_f32_dpp v12, v12, v12 row_ror:2 row_mask:0xf bank_mask:0xf bound_ctrl:1
	v_pk_fma_f32 v[48:49], v[44:45], v[70:71], v[6:7] op_sel:[0,1,0]
	v_pk_fma_f32 v[50:51], v[46:47], v[70:71], v[8:9] op_sel:[0,1,0]
	v_add_f32_dpp v12, v12, v12 row_ror:4 row_mask:0xf bank_mask:0xf bound_ctrl:1
	s_nop 1
	v_add_f32_dpp v12, v12, v12 row_ror:8 row_mask:0xf bank_mask:0xf bound_ctrl:1
	v_pk_fma_f32 v[6:7], v[40:41], v[12:13], v[48:49] op_sel_hi:[1,0,1] neg_lo:[1,0,0] neg_hi:[1,0,0]
	v_pk_fma_f32 v[8:9], v[42:43], v[12:13], v[50:51] op_sel_hi:[1,0,1] neg_lo:[1,0,0] neg_hi:[1,0,0]
	ds_read_b128 v[110:113], v10 offset:48384
	ds_read_b128 v[106:109], v10 offset:48128
	ds_read_b128 v[118:121], v10 offset:48896
	ds_read_b128 v[114:117], v10 offset:48640
	ds_read_b128 v[66:69], v11 offset:3072
	s_waitcnt lgkmcnt(5)
	v_fma_mix_f32 v12, v6, v88, v180 op_sel_hi:[0,1,0]
	v_fma_mix_f32 v12, v7, v88, v12 op_sel:[0,1,0] op_sel_hi:[0,1,0]
	v_fma_mix_f32 v12, v8, v89, v12 op_sel_hi:[0,1,0]
	v_fma_mix_f32 v12, v9, v89, v12 op_sel:[0,1,0] op_sel_hi:[0,1,0]
	v_fma_mix_f32 v104, v6, v38, v180 op_sel_hi:[0,1,0]
	v_fma_mix_f32 v104, v7, v38, v104 op_sel:[0,1,0] op_sel_hi:[0,1,0]
	v_add_f32_dpp v12, v12, v12 row_ror:1 row_mask:0xf bank_mask:0xf bound_ctrl:1
	v_fma_mix_f32 v104, v8, v39, v104 op_sel_hi:[0,1,0]
	v_fma_mix_f32 v104, v9, v39, v104 op_sel:[0,1,0] op_sel_hi:[0,1,0]
	v_add_f32_dpp v12, v12, v12 row_ror:2 row_mask:0xf bank_mask:0xf bound_ctrl:1
	v_pk_fma_f32 v[48:49], v[96:97], v[72:73], v[6:7] op_sel_hi:[1,0,1]
	v_pk_fma_f32 v[50:51], v[98:99], v[72:73], v[8:9] op_sel_hi:[1,0,1]
	v_add_f32_dpp v12, v12, v12 row_ror:4 row_mask:0xf bank_mask:0xf bound_ctrl:1
	s_nop 1
	v_add_f32_dpp v12, v12, v12 row_ror:8 row_mask:0xf bank_mask:0xf bound_ctrl:1
	v_pk_fma_f32 v[6:7], v[92:93], v[12:13], v[48:49] op_sel_hi:[1,0,1] neg_lo:[1,0,0] neg_hi:[1,0,0]
	v_pk_fma_f32 v[8:9], v[94:95], v[12:13], v[50:51] op_sel_hi:[1,0,1] neg_lo:[1,0,0] neg_hi:[1,0,0]
	ds_read_b128 v[20:23], v10 offset:49408
	ds_read_b128 v[28:31], v10 offset:49920
	ds_read_b128 v[24:27], v10 offset:49664
	s_waitcnt lgkmcnt(4)
	v_fma_mix_f32 v12, v6, v110, v180 op_sel_hi:[0,1,0]
	v_fma_mix_f32 v12, v7, v110, v12 op_sel:[0,1,0] op_sel_hi:[0,1,0]
	v_fma_mix_f32 v12, v8, v111, v12 op_sel_hi:[0,1,0]
	v_fma_mix_f32 v12, v9, v111, v12 op_sel:[0,1,0] op_sel_hi:[0,1,0]
	v_fma_mix_f32 v105, v6, v90, v180 op_sel_hi:[0,1,0]
	v_fma_mix_f32 v105, v7, v90, v105 op_sel:[0,1,0] op_sel_hi:[0,1,0]
	v_add_f32_dpp v12, v12, v12 row_ror:1 row_mask:0xf bank_mask:0xf bound_ctrl:1
	v_fma_mix_f32 v105, v8, v91, v105 op_sel_hi:[0,1,0]
	v_fma_mix_f32 v105, v9, v91, v105 op_sel:[0,1,0] op_sel_hi:[0,1,0]
	v_add_f32_dpp v12, v12, v12 row_ror:2 row_mask:0xf bank_mask:0xf bound_ctrl:1
	v_pk_fma_f32 v[48:49], v[118:119], v[72:73], v[6:7] op_sel:[0,1,0]
	v_pk_fma_f32 v[50:51], v[120:121], v[72:73], v[8:9] op_sel:[0,1,0]
	v_add_f32_dpp v12, v12, v12 row_ror:4 row_mask:0xf bank_mask:0xf bound_ctrl:1
	s_nop 1
	v_add_f32_dpp v12, v12, v12 row_ror:8 row_mask:0xf bank_mask:0xf bound_ctrl:1
	v_pk_fma_f32 v[6:7], v[114:115], v[12:13], v[48:49] op_sel_hi:[1,0,1] neg_lo:[1,0,0] neg_hi:[1,0,0]
	v_pk_fma_f32 v[8:9], v[116:117], v[12:13], v[50:51] op_sel_hi:[1,0,1] neg_lo:[1,0,0] neg_hi:[1,0,0]
	v_pk_mul_f32 v[6:7], v[6:7], v[106:107]
	v_pk_mul_f32 v[8:9], v[8:9], v[108:109]
	ds_read_b128 v[36:39], v10 offset:50432
	ds_read_b128 v[44:47], v10 offset:50944
	ds_read_b128 v[40:43], v10 offset:50688
	s_waitcnt lgkmcnt(3)
	v_fma_mix_f32 v12, v6, v20, v180 op_sel_hi:[0,1,0]
	v_fma_mix_f32 v12, v7, v20, v12 op_sel:[0,1,0] op_sel_hi:[0,1,0]
	v_fma_mix_f32 v12, v8, v21, v12 op_sel_hi:[0,1,0]
	v_fma_mix_f32 v12, v9, v21, v12 op_sel:[0,1,0] op_sel_hi:[0,1,0]
	v_fma_mix_f32 v61, v6, v112, v180 op_sel_hi:[0,1,0]
	v_fma_mix_f32 v61, v7, v112, v61 op_sel:[0,1,0] op_sel_hi:[0,1,0]
	v_add_f32_dpp v12, v12, v12 row_ror:1 row_mask:0xf bank_mask:0xf bound_ctrl:1
	v_fma_mix_f32 v61, v8, v113, v61 op_sel_hi:[0,1,0]
	v_fma_mix_f32 v61, v9, v113, v61 op_sel:[0,1,0] op_sel_hi:[0,1,0]
	v_add_f32_dpp v12, v12, v12 row_ror:2 row_mask:0xf bank_mask:0xf bound_ctrl:1
	v_pk_fma_f32 v[48:49], v[28:29], v[66:67], v[6:7] op_sel_hi:[1,0,1]
	v_pk_fma_f32 v[50:51], v[30:31], v[66:67], v[8:9] op_sel_hi:[1,0,1]
	v_add_f32_dpp v12, v12, v12 row_ror:4 row_mask:0xf bank_mask:0xf bound_ctrl:1
	s_nop 1
	v_add_f32_dpp v12, v12, v12 row_ror:8 row_mask:0xf bank_mask:0xf bound_ctrl:1
	v_pk_fma_f32 v[6:7], v[24:25], v[12:13], v[48:49] op_sel_hi:[1,0,1] neg_lo:[1,0,0] neg_hi:[1,0,0]
	v_pk_fma_f32 v[8:9], v[26:27], v[12:13], v[50:51] op_sel_hi:[1,0,1] neg_lo:[1,0,0] neg_hi:[1,0,0]
	ds_read_b128 v[88:91], v10 offset:51456
	ds_read_b128 v[96:99], v10 offset:51968
	ds_read_b128 v[92:95], v10 offset:51712
	v_add_f32_dpp v83, v83, v83 row_ror:8 row_mask:0xf bank_mask:0xc
	v_add_f32_dpp v83, v52, v52 row_ror:8 row_mask:0xf bank_mask:0x3
	v_add_f32_dpp v100, v100, v100 row_ror:8 row_mask:0xf bank_mask:0xc
	v_add_f32_dpp v100, v53, v53 row_ror:8 row_mask:0xf bank_mask:0x3
	v_add_f32_dpp v101, v101, v101 row_ror:8 row_mask:0xf bank_mask:0xc
	v_add_f32_dpp v101, v54, v54 row_ror:8 row_mask:0xf bank_mask:0x3
	v_add_f32_dpp v102, v102, v102 row_ror:8 row_mask:0xf bank_mask:0xc
	v_add_f32_dpp v102, v55, v55 row_ror:8 row_mask:0xf bank_mask:0x3
	v_add_f32_dpp v103, v103, v103 row_ror:8 row_mask:0xf bank_mask:0xc
	v_add_f32_dpp v103, v56, v56 row_ror:8 row_mask:0xf bank_mask:0x3
	v_add_f32_dpp v104, v104, v104 row_ror:8 row_mask:0xf bank_mask:0xc
	v_add_f32_dpp v104, v57, v57 row_ror:8 row_mask:0xf bank_mask:0x3
	v_add_f32_dpp v105, v105, v105 row_ror:8 row_mask:0xf bank_mask:0xc
	v_add_f32_dpp v105, v81, v81 row_ror:8 row_mask:0xf bank_mask:0x3
	v_add_f32_dpp v61, v61, v61 row_ror:8 row_mask:0xf bank_mask:0xc
	v_add_f32_dpp v61, v82, v82 row_ror:8 row_mask:0xf bank_mask:0x3
	v_add_f32_dpp v103, v103, v103 row_ror:4 row_mask:0xf bank_mask:0xa
	v_add_f32_dpp v103, v83, v83 row_ror:12 row_mask:0xf bank_mask:0x5
	v_add_f32_dpp v104, v104, v104 row_ror:4 row_mask:0xf bank_mask:0xa
	v_add_f32_dpp v104, v100, v100 row_ror:12 row_mask:0xf bank_mask:0x5
	v_add_f32_dpp v105, v105, v105 row_ror:4 row_mask:0xf bank_mask:0xa
	v_add_f32_dpp v105, v101, v101 row_ror:12 row_mask:0xf bank_mask:0x5
	v_add_f32_dpp v61, v61, v61 row_ror:4 row_mask:0xf bank_mask:0xa
	v_add_f32_dpp v61, v102, v102 row_ror:12 row_mask:0xf bank_mask:0x5
	v_cndmask_b32_e64 v62, v105, v103, s[38:39]
	v_cndmask_b32_e64 v63, v103, v105, s[38:39]
	v_cndmask_b32_e64 v64, v61, v104, s[38:39]
	v_cndmask_b32_e64 v65, v104, v61, s[38:39]
	v_add_f32_dpp v62, v63, v62 quad_perm:[2,3,0,1] row_mask:0xf bank_mask:0xf bound_ctrl:1
	s_nop 0
	v_add_f32_dpp v63, v65, v64 quad_perm:[2,3,0,1] row_mask:0xf bank_mask:0xf bound_ctrl:1
	v_cndmask_b32_e64 v65, v63, v62, s[40:41]
	v_cndmask_b32_e64 v62, v62, v63, s[40:41]
	s_nop 1
	v_add_f32_dpp v62, v62, v65 quad_perm:[1,0,3,2] row_mask:0xf bank_mask:0xf bound_ctrl:1
	v_cvt_pk_bf16_f32 v62, v62, v62
	global_store_short v[2:3], v62, off
	v_lshl_add_u64 v[2:3], v[2:3], 0, s[84:85]
	s_waitcnt lgkmcnt(3)
	v_fma_mix_f32 v12, v6, v36, v180 op_sel_hi:[0,1,0]
	v_fma_mix_f32 v12, v7, v36, v12 op_sel:[0,1,0] op_sel_hi:[0,1,0]
	v_fma_mix_f32 v12, v8, v37, v12 op_sel_hi:[0,1,0]
	v_fma_mix_f32 v12, v9, v37, v12 op_sel:[0,1,0] op_sel_hi:[0,1,0]
	v_fma_mix_f32 v52, v6, v22, v180 op_sel_hi:[0,1,0]
	v_fma_mix_f32 v52, v7, v22, v52 op_sel:[0,1,0] op_sel_hi:[0,1,0]
	v_add_f32_dpp v12, v12, v12 row_ror:1 row_mask:0xf bank_mask:0xf bound_ctrl:1
	v_fma_mix_f32 v52, v8, v23, v52 op_sel_hi:[0,1,0]
	v_fma_mix_f32 v52, v9, v23, v52 op_sel:[0,1,0] op_sel_hi:[0,1,0]
	v_add_f32_dpp v12, v12, v12 row_ror:2 row_mask:0xf bank_mask:0xf bound_ctrl:1
	v_pk_fma_f32 v[48:49], v[44:45], v[66:67], v[6:7] op_sel:[0,1,0]
	v_pk_fma_f32 v[50:51], v[46:47], v[66:67], v[8:9] op_sel:[0,1,0]
	v_add_f32_dpp v12, v12, v12 row_ror:4 row_mask:0xf bank_mask:0xf bound_ctrl:1
	s_nop 1
	v_add_f32_dpp v12, v12, v12 row_ror:8 row_mask:0xf bank_mask:0xf bound_ctrl:1
	v_pk_fma_f32 v[6:7], v[40:41], v[12:13], v[48:49] op_sel_hi:[1,0,1] neg_lo:[1,0,0] neg_hi:[1,0,0]
	v_pk_fma_f32 v[8:9], v[42:43], v[12:13], v[50:51] op_sel_hi:[1,0,1] neg_lo:[1,0,0] neg_hi:[1,0,0]
	ds_read_b128 v[110:113], v10 offset:52480
	ds_read_b128 v[106:109], v10 offset:52224
	ds_read_b128 v[118:121], v10 offset:52992
	ds_read_b128 v[114:117], v10 offset:52736
	ds_read_b128 v[70:73], v11 offset:3328
	s_waitcnt lgkmcnt(5)
	v_fma_mix_f32 v12, v6, v88, v180 op_sel_hi:[0,1,0]
	v_fma_mix_f32 v12, v7, v88, v12 op_sel:[0,1,0] op_sel_hi:[0,1,0]
	v_fma_mix_f32 v12, v8, v89, v12 op_sel_hi:[0,1,0]
	v_fma_mix_f32 v12, v9, v89, v12 op_sel:[0,1,0] op_sel_hi:[0,1,0]
	v_fma_mix_f32 v53, v6, v38, v180 op_sel_hi:[0,1,0]
	v_fma_mix_f32 v53, v7, v38, v53 op_sel:[0,1,0] op_sel_hi:[0,1,0]
	v_add_f32_dpp v12, v12, v12 row_ror:1 row_mask:0xf bank_mask:0xf bound_ctrl:1
	v_fma_mix_f32 v53, v8, v39, v53 op_sel_hi:[0,1,0]
	v_fma_mix_f32 v53, v9, v39, v53 op_sel:[0,1,0] op_sel_hi:[0,1,0]
	v_add_f32_dpp v12, v12, v12 row_ror:2 row_mask:0xf bank_mask:0xf bound_ctrl:1
	v_pk_fma_f32 v[48:49], v[96:97], v[68:69], v[6:7] op_sel_hi:[1,0,1]
	v_pk_fma_f32 v[50:51], v[98:99], v[68:69], v[8:9] op_sel_hi:[1,0,1]
	v_add_f32_dpp v12, v12, v12 row_ror:4 row_mask:0xf bank_mask:0xf bound_ctrl:1
	s_nop 1
	v_add_f32_dpp v12, v12, v12 row_ror:8 row_mask:0xf bank_mask:0xf bound_ctrl:1
	v_pk_fma_f32 v[6:7], v[92:93], v[12:13], v[48:49] op_sel_hi:[1,0,1] neg_lo:[1,0,0] neg_hi:[1,0,0]
	v_pk_fma_f32 v[8:9], v[94:95], v[12:13], v[50:51] op_sel_hi:[1,0,1] neg_lo:[1,0,0] neg_hi:[1,0,0]
	ds_read_b128 v[20:23], v10 offset:53504
	ds_read_b128 v[28:31], v10 offset:54016
	ds_read_b128 v[24:27], v10 offset:53760
	s_waitcnt lgkmcnt(4)
	v_fma_mix_f32 v12, v6, v110, v180 op_sel_hi:[0,1,0]
	v_fma_mix_f32 v12, v7, v110, v12 op_sel:[0,1,0] op_sel_hi:[0,1,0]
	v_fma_mix_f32 v12, v8, v111, v12 op_sel_hi:[0,1,0]
	v_fma_mix_f32 v12, v9, v111, v12 op_sel:[0,1,0] op_sel_hi:[0,1,0]
	v_fma_mix_f32 v54, v6, v90, v180 op_sel_hi:[0,1,0]
	v_fma_mix_f32 v54, v7, v90, v54 op_sel:[0,1,0] op_sel_hi:[0,1,0]
	v_add_f32_dpp v12, v12, v12 row_ror:1 row_mask:0xf bank_mask:0xf bound_ctrl:1
	v_fma_mix_f32 v54, v8, v91, v54 op_sel_hi:[0,1,0]
	v_fma_mix_f32 v54, v9, v91, v54 op_sel:[0,1,0] op_sel_hi:[0,1,0]
	v_add_f32_dpp v12, v12, v12 row_ror:2 row_mask:0xf bank_mask:0xf bound_ctrl:1
	v_pk_fma_f32 v[48:49], v[118:119], v[68:69], v[6:7] op_sel:[0,1,0]
	v_pk_fma_f32 v[50:51], v[120:121], v[68:69], v[8:9] op_sel:[0,1,0]
	v_add_f32_dpp v12, v12, v12 row_ror:4 row_mask:0xf bank_mask:0xf bound_ctrl:1
	s_nop 1
	v_add_f32_dpp v12, v12, v12 row_ror:8 row_mask:0xf bank_mask:0xf bound_ctrl:1
	v_pk_fma_f32 v[6:7], v[114:115], v[12:13], v[48:49] op_sel_hi:[1,0,1] neg_lo:[1,0,0] neg_hi:[1,0,0]
	v_pk_fma_f32 v[8:9], v[116:117], v[12:13], v[50:51] op_sel_hi:[1,0,1] neg_lo:[1,0,0] neg_hi:[1,0,0]
	v_pk_mul_f32 v[6:7], v[6:7], v[106:107]
	v_pk_mul_f32 v[8:9], v[8:9], v[108:109]
	ds_read_b128 v[36:39], v10 offset:54528
	ds_read_b128 v[44:47], v10 offset:55040
	ds_read_b128 v[40:43], v10 offset:54784
	s_waitcnt lgkmcnt(3)
	v_fma_mix_f32 v12, v6, v20, v180 op_sel_hi:[0,1,0]
	v_fma_mix_f32 v12, v7, v20, v12 op_sel:[0,1,0] op_sel_hi:[0,1,0]
	v_fma_mix_f32 v12, v8, v21, v12 op_sel_hi:[0,1,0]
	v_fma_mix_f32 v12, v9, v21, v12 op_sel:[0,1,0] op_sel_hi:[0,1,0]
	v_fma_mix_f32 v55, v6, v112, v180 op_sel_hi:[0,1,0]
	v_fma_mix_f32 v55, v7, v112, v55 op_sel:[0,1,0] op_sel_hi:[0,1,0]
	v_add_f32_dpp v12, v12, v12 row_ror:1 row_mask:0xf bank_mask:0xf bound_ctrl:1
	v_fma_mix_f32 v55, v8, v113, v55 op_sel_hi:[0,1,0]
	v_fma_mix_f32 v55, v9, v113, v55 op_sel:[0,1,0] op_sel_hi:[0,1,0]
	v_add_f32_dpp v12, v12, v12 row_ror:2 row_mask:0xf bank_mask:0xf bound_ctrl:1
	v_pk_fma_f32 v[48:49], v[28:29], v[70:71], v[6:7] op_sel_hi:[1,0,1]
	v_pk_fma_f32 v[50:51], v[30:31], v[70:71], v[8:9] op_sel_hi:[1,0,1]
	v_add_f32_dpp v12, v12, v12 row_ror:4 row_mask:0xf bank_mask:0xf bound_ctrl:1
	s_nop 1
	v_add_f32_dpp v12, v12, v12 row_ror:8 row_mask:0xf bank_mask:0xf bound_ctrl:1
	v_pk_fma_f32 v[6:7], v[24:25], v[12:13], v[48:49] op_sel_hi:[1,0,1] neg_lo:[1,0,0] neg_hi:[1,0,0]
	v_pk_fma_f32 v[8:9], v[26:27], v[12:13], v[50:51] op_sel_hi:[1,0,1] neg_lo:[1,0,0] neg_hi:[1,0,0]
	ds_read_b128 v[88:91], v10 offset:55552
	ds_read_b128 v[96:99], v10 offset:56064
	ds_read_b128 v[92:95], v10 offset:55808
	s_waitcnt lgkmcnt(3)
	v_fma_mix_f32 v12, v6, v36, v180 op_sel_hi:[0,1,0]
	v_fma_mix_f32 v12, v7, v36, v12 op_sel:[0,1,0] op_sel_hi:[0,1,0]
	v_fma_mix_f32 v12, v8, v37, v12 op_sel_hi:[0,1,0]
	v_fma_mix_f32 v12, v9, v37, v12 op_sel:[0,1,0] op_sel_hi:[0,1,0]
	v_fma_mix_f32 v56, v6, v22, v180 op_sel_hi:[0,1,0]
	v_fma_mix_f32 v56, v7, v22, v56 op_sel:[0,1,0] op_sel_hi:[0,1,0]
	v_add_f32_dpp v12, v12, v12 row_ror:1 row_mask:0xf bank_mask:0xf bound_ctrl:1
	v_fma_mix_f32 v56, v8, v23, v56 op_sel_hi:[0,1,0]
	v_fma_mix_f32 v56, v9, v23, v56 op_sel:[0,1,0] op_sel_hi:[0,1,0]
	v_add_f32_dpp v12, v12, v12 row_ror:2 row_mask:0xf bank_mask:0xf bound_ctrl:1
	v_pk_fma_f32 v[48:49], v[44:45], v[70:71], v[6:7] op_sel:[0,1,0]
	v_pk_fma_f32 v[50:51], v[46:47], v[70:71], v[8:9] op_sel:[0,1,0]
	v_add_f32_dpp v12, v12, v12 row_ror:4 row_mask:0xf bank_mask:0xf bound_ctrl:1
	s_nop 1
	v_add_f32_dpp v12, v12, v12 row_ror:8 row_mask:0xf bank_mask:0xf bound_ctrl:1
	v_pk_fma_f32 v[6:7], v[40:41], v[12:13], v[48:49] op_sel_hi:[1,0,1] neg_lo:[1,0,0] neg_hi:[1,0,0]
	v_pk_fma_f32 v[8:9], v[42:43], v[12:13], v[50:51] op_sel_hi:[1,0,1] neg_lo:[1,0,0] neg_hi:[1,0,0]
	ds_read_b128 v[110:113], v10 offset:56576
	ds_read_b128 v[106:109], v10 offset:56320
	ds_read_b128 v[118:121], v10 offset:57088
	ds_read_b128 v[114:117], v10 offset:56832
	ds_read_b128 v[66:69], v11 offset:3584
	s_waitcnt lgkmcnt(5)
	v_fma_mix_f32 v12, v6, v88, v180 op_sel_hi:[0,1,0]
	v_fma_mix_f32 v12, v7, v88, v12 op_sel:[0,1,0] op_sel_hi:[0,1,0]
	v_fma_mix_f32 v12, v8, v89, v12 op_sel_hi:[0,1,0]
	v_fma_mix_f32 v12, v9, v89, v12 op_sel:[0,1,0] op_sel_hi:[0,1,0]
	v_fma_mix_f32 v57, v6, v38, v180 op_sel_hi:[0,1,0]
	v_fma_mix_f32 v57, v7, v38, v57 op_sel:[0,1,0] op_sel_hi:[0,1,0]
	v_add_f32_dpp v12, v12, v12 row_ror:1 row_mask:0xf bank_mask:0xf bound_ctrl:1
	v_fma_mix_f32 v57, v8, v39, v57 op_sel_hi:[0,1,0]
	v_fma_mix_f32 v57, v9, v39, v57 op_sel:[0,1,0] op_sel_hi:[0,1,0]
	v_add_f32_dpp v12, v12, v12 row_ror:2 row_mask:0xf bank_mask:0xf bound_ctrl:1
	v_pk_fma_f32 v[48:49], v[96:97], v[72:73], v[6:7] op_sel_hi:[1,0,1]
	v_pk_fma_f32 v[50:51], v[98:99], v[72:73], v[8:9] op_sel_hi:[1,0,1]
	v_add_f32_dpp v12, v12, v12 row_ror:4 row_mask:0xf bank_mask:0xf bound_ctrl:1
	s_nop 1
	v_add_f32_dpp v12, v12, v12 row_ror:8 row_mask:0xf bank_mask:0xf bound_ctrl:1
	v_pk_fma_f32 v[6:7], v[92:93], v[12:13], v[48:49] op_sel_hi:[1,0,1] neg_lo:[1,0,0] neg_hi:[1,0,0]
	v_pk_fma_f32 v[8:9], v[94:95], v[12:13], v[50:51] op_sel_hi:[1,0,1] neg_lo:[1,0,0] neg_hi:[1,0,0]
	ds_read_b128 v[20:23], v10 offset:57600
	ds_read_b128 v[28:31], v10 offset:58112
	ds_read_b128 v[24:27], v10 offset:57856
	s_waitcnt lgkmcnt(4)
	v_fma_mix_f32 v12, v6, v110, v180 op_sel_hi:[0,1,0]
	v_fma_mix_f32 v12, v7, v110, v12 op_sel:[0,1,0] op_sel_hi:[0,1,0]
	v_fma_mix_f32 v12, v8, v111, v12 op_sel_hi:[0,1,0]
	v_fma_mix_f32 v12, v9, v111, v12 op_sel:[0,1,0] op_sel_hi:[0,1,0]
	v_fma_mix_f32 v81, v6, v90, v180 op_sel_hi:[0,1,0]
	v_fma_mix_f32 v81, v7, v90, v81 op_sel:[0,1,0] op_sel_hi:[0,1,0]
	v_add_f32_dpp v12, v12, v12 row_ror:1 row_mask:0xf bank_mask:0xf bound_ctrl:1
	v_fma_mix_f32 v81, v8, v91, v81 op_sel_hi:[0,1,0]
	v_fma_mix_f32 v81, v9, v91, v81 op_sel:[0,1,0] op_sel_hi:[0,1,0]
	v_add_f32_dpp v12, v12, v12 row_ror:2 row_mask:0xf bank_mask:0xf bound_ctrl:1
	v_pk_fma_f32 v[48:49], v[118:119], v[72:73], v[6:7] op_sel:[0,1,0]
	v_pk_fma_f32 v[50:51], v[120:121], v[72:73], v[8:9] op_sel:[0,1,0]
	v_add_f32_dpp v12, v12, v12 row_ror:4 row_mask:0xf bank_mask:0xf bound_ctrl:1
	s_nop 1
	v_add_f32_dpp v12, v12, v12 row_ror:8 row_mask:0xf bank_mask:0xf bound_ctrl:1
	v_pk_fma_f32 v[6:7], v[114:115], v[12:13], v[48:49] op_sel_hi:[1,0,1] neg_lo:[1,0,0] neg_hi:[1,0,0]
	v_pk_fma_f32 v[8:9], v[116:117], v[12:13], v[50:51] op_sel_hi:[1,0,1] neg_lo:[1,0,0] neg_hi:[1,0,0]
	v_pk_mul_f32 v[6:7], v[6:7], v[106:107]
	v_pk_mul_f32 v[8:9], v[8:9], v[108:109]
	ds_read_b128 v[36:39], v10 offset:58624
	ds_read_b128 v[44:47], v10 offset:59136
	ds_read_b128 v[40:43], v10 offset:58880
	s_waitcnt lgkmcnt(3)
	v_fma_mix_f32 v12, v6, v20, v180 op_sel_hi:[0,1,0]
	v_fma_mix_f32 v12, v7, v20, v12 op_sel:[0,1,0] op_sel_hi:[0,1,0]
	v_fma_mix_f32 v12, v8, v21, v12 op_sel_hi:[0,1,0]
	v_fma_mix_f32 v12, v9, v21, v12 op_sel:[0,1,0] op_sel_hi:[0,1,0]
	v_fma_mix_f32 v82, v6, v112, v180 op_sel_hi:[0,1,0]
	v_fma_mix_f32 v82, v7, v112, v82 op_sel:[0,1,0] op_sel_hi:[0,1,0]
	v_add_f32_dpp v12, v12, v12 row_ror:1 row_mask:0xf bank_mask:0xf bound_ctrl:1
	v_fma_mix_f32 v82, v8, v113, v82 op_sel_hi:[0,1,0]
	v_fma_mix_f32 v82, v9, v113, v82 op_sel:[0,1,0] op_sel_hi:[0,1,0]
	v_add_f32_dpp v12, v12, v12 row_ror:2 row_mask:0xf bank_mask:0xf bound_ctrl:1
	v_pk_fma_f32 v[48:49], v[28:29], v[66:67], v[6:7] op_sel_hi:[1,0,1]
	v_pk_fma_f32 v[50:51], v[30:31], v[66:67], v[8:9] op_sel_hi:[1,0,1]
	v_add_f32_dpp v12, v12, v12 row_ror:4 row_mask:0xf bank_mask:0xf bound_ctrl:1
	s_nop 1
	v_add_f32_dpp v12, v12, v12 row_ror:8 row_mask:0xf bank_mask:0xf bound_ctrl:1
	v_pk_fma_f32 v[6:7], v[24:25], v[12:13], v[48:49] op_sel_hi:[1,0,1] neg_lo:[1,0,0] neg_hi:[1,0,0]
	v_pk_fma_f32 v[8:9], v[26:27], v[12:13], v[50:51] op_sel_hi:[1,0,1] neg_lo:[1,0,0] neg_hi:[1,0,0]
	ds_read_b128 v[88:91], v10 offset:59648
	ds_read_b128 v[96:99], v10 offset:60160
	ds_read_b128 v[92:95], v10 offset:59904
	s_waitcnt lgkmcnt(3)
	v_fma_mix_f32 v12, v6, v36, v180 op_sel_hi:[0,1,0]
	v_fma_mix_f32 v12, v7, v36, v12 op_sel:[0,1,0] op_sel_hi:[0,1,0]
	v_fma_mix_f32 v12, v8, v37, v12 op_sel_hi:[0,1,0]
	v_fma_mix_f32 v12, v9, v37, v12 op_sel:[0,1,0] op_sel_hi:[0,1,0]
	v_fma_mix_f32 v83, v6, v22, v180 op_sel_hi:[0,1,0]
	v_fma_mix_f32 v83, v7, v22, v83 op_sel:[0,1,0] op_sel_hi:[0,1,0]
	v_add_f32_dpp v12, v12, v12 row_ror:1 row_mask:0xf bank_mask:0xf bound_ctrl:1
	v_fma_mix_f32 v83, v8, v23, v83 op_sel_hi:[0,1,0]
	v_fma_mix_f32 v83, v9, v23, v83 op_sel:[0,1,0] op_sel_hi:[0,1,0]
	v_add_f32_dpp v12, v12, v12 row_ror:2 row_mask:0xf bank_mask:0xf bound_ctrl:1
	v_pk_fma_f32 v[48:49], v[44:45], v[66:67], v[6:7] op_sel:[0,1,0]
	v_pk_fma_f32 v[50:51], v[46:47], v[66:67], v[8:9] op_sel:[0,1,0]
	v_add_f32_dpp v12, v12, v12 row_ror:4 row_mask:0xf bank_mask:0xf bound_ctrl:1
	s_nop 1
	v_add_f32_dpp v12, v12, v12 row_ror:8 row_mask:0xf bank_mask:0xf bound_ctrl:1
	v_pk_fma_f32 v[6:7], v[40:41], v[12:13], v[48:49] op_sel_hi:[1,0,1] neg_lo:[1,0,0] neg_hi:[1,0,0]
	v_pk_fma_f32 v[8:9], v[42:43], v[12:13], v[50:51] op_sel_hi:[1,0,1] neg_lo:[1,0,0] neg_hi:[1,0,0]
	ds_read_b128 v[110:113], v10 offset:60672
	ds_read_b128 v[106:109], v10 offset:60416
	ds_read_b128 v[118:121], v10 offset:61184
	ds_read_b128 v[114:117], v10 offset:60928
	ds_read_b128 v[70:73], v11 offset:3840
	s_waitcnt lgkmcnt(5)
	v_fma_mix_f32 v12, v6, v88, v180 op_sel_hi:[0,1,0]
	v_fma_mix_f32 v12, v7, v88, v12 op_sel:[0,1,0] op_sel_hi:[0,1,0]
	v_fma_mix_f32 v12, v8, v89, v12 op_sel_hi:[0,1,0]
	v_fma_mix_f32 v12, v9, v89, v12 op_sel:[0,1,0] op_sel_hi:[0,1,0]
	v_fma_mix_f32 v100, v6, v38, v180 op_sel_hi:[0,1,0]
	v_fma_mix_f32 v100, v7, v38, v100 op_sel:[0,1,0] op_sel_hi:[0,1,0]
	v_add_f32_dpp v12, v12, v12 row_ror:1 row_mask:0xf bank_mask:0xf bound_ctrl:1
	v_fma_mix_f32 v100, v8, v39, v100 op_sel_hi:[0,1,0]
	v_fma_mix_f32 v100, v9, v39, v100 op_sel:[0,1,0] op_sel_hi:[0,1,0]
	v_add_f32_dpp v12, v12, v12 row_ror:2 row_mask:0xf bank_mask:0xf bound_ctrl:1
	v_pk_fma_f32 v[48:49], v[96:97], v[68:69], v[6:7] op_sel_hi:[1,0,1]
	v_pk_fma_f32 v[50:51], v[98:99], v[68:69], v[8:9] op_sel_hi:[1,0,1]
	v_add_f32_dpp v12, v12, v12 row_ror:4 row_mask:0xf bank_mask:0xf bound_ctrl:1
	s_nop 1
	v_add_f32_dpp v12, v12, v12 row_ror:8 row_mask:0xf bank_mask:0xf bound_ctrl:1
	v_pk_fma_f32 v[6:7], v[92:93], v[12:13], v[48:49] op_sel_hi:[1,0,1] neg_lo:[1,0,0] neg_hi:[1,0,0]
	v_pk_fma_f32 v[8:9], v[94:95], v[12:13], v[50:51] op_sel_hi:[1,0,1] neg_lo:[1,0,0] neg_hi:[1,0,0]
	ds_read_b128 v[20:23], v10 offset:61696
	ds_read_b128 v[28:31], v10 offset:62208
	ds_read_b128 v[24:27], v10 offset:61952
	s_waitcnt lgkmcnt(4)
	v_fma_mix_f32 v12, v6, v110, v180 op_sel_hi:[0,1,0]
	v_fma_mix_f32 v12, v7, v110, v12 op_sel:[0,1,0] op_sel_hi:[0,1,0]
	v_fma_mix_f32 v12, v8, v111, v12 op_sel_hi:[0,1,0]
	v_fma_mix_f32 v12, v9, v111, v12 op_sel:[0,1,0] op_sel_hi:[0,1,0]
	v_fma_mix_f32 v101, v6, v90, v180 op_sel_hi:[0,1,0]
	v_fma_mix_f32 v101, v7, v90, v101 op_sel:[0,1,0] op_sel_hi:[0,1,0]
	v_add_f32_dpp v12, v12, v12 row_ror:1 row_mask:0xf bank_mask:0xf bound_ctrl:1
	v_fma_mix_f32 v101, v8, v91, v101 op_sel_hi:[0,1,0]
	v_fma_mix_f32 v101, v9, v91, v101 op_sel:[0,1,0] op_sel_hi:[0,1,0]
	v_add_f32_dpp v12, v12, v12 row_ror:2 row_mask:0xf bank_mask:0xf bound_ctrl:1
	v_pk_fma_f32 v[48:49], v[118:119], v[68:69], v[6:7] op_sel:[0,1,0]
	v_pk_fma_f32 v[50:51], v[120:121], v[68:69], v[8:9] op_sel:[0,1,0]
	v_add_f32_dpp v12, v12, v12 row_ror:4 row_mask:0xf bank_mask:0xf bound_ctrl:1
	s_nop 1
	v_add_f32_dpp v12, v12, v12 row_ror:8 row_mask:0xf bank_mask:0xf bound_ctrl:1
	v_pk_fma_f32 v[6:7], v[114:115], v[12:13], v[48:49] op_sel_hi:[1,0,1] neg_lo:[1,0,0] neg_hi:[1,0,0]
	v_pk_fma_f32 v[8:9], v[116:117], v[12:13], v[50:51] op_sel_hi:[1,0,1] neg_lo:[1,0,0] neg_hi:[1,0,0]
	v_pk_mul_f32 v[6:7], v[6:7], v[106:107]
	v_pk_mul_f32 v[8:9], v[8:9], v[108:109]
	ds_read_b128 v[36:39], v10 offset:62720
	ds_read_b128 v[44:47], v10 offset:63232
	ds_read_b128 v[40:43], v10 offset:62976
	s_waitcnt lgkmcnt(3)
	v_fma_mix_f32 v12, v6, v20, v180 op_sel_hi:[0,1,0]
	v_fma_mix_f32 v12, v7, v20, v12 op_sel:[0,1,0] op_sel_hi:[0,1,0]
	v_fma_mix_f32 v12, v8, v21, v12 op_sel_hi:[0,1,0]
	v_fma_mix_f32 v12, v9, v21, v12 op_sel:[0,1,0] op_sel_hi:[0,1,0]
	v_fma_mix_f32 v102, v6, v112, v180 op_sel_hi:[0,1,0]
	v_fma_mix_f32 v102, v7, v112, v102 op_sel:[0,1,0] op_sel_hi:[0,1,0]
	v_add_f32_dpp v12, v12, v12 row_ror:1 row_mask:0xf bank_mask:0xf bound_ctrl:1
	v_fma_mix_f32 v102, v8, v113, v102 op_sel_hi:[0,1,0]
	v_fma_mix_f32 v102, v9, v113, v102 op_sel:[0,1,0] op_sel_hi:[0,1,0]
	v_add_f32_dpp v12, v12, v12 row_ror:2 row_mask:0xf bank_mask:0xf bound_ctrl:1
	v_pk_fma_f32 v[48:49], v[28:29], v[70:71], v[6:7] op_sel_hi:[1,0,1]
	v_pk_fma_f32 v[50:51], v[30:31], v[70:71], v[8:9] op_sel_hi:[1,0,1]
	v_add_f32_dpp v12, v12, v12 row_ror:4 row_mask:0xf bank_mask:0xf bound_ctrl:1
	s_nop 1
	v_add_f32_dpp v12, v12, v12 row_ror:8 row_mask:0xf bank_mask:0xf bound_ctrl:1
	v_pk_fma_f32 v[6:7], v[24:25], v[12:13], v[48:49] op_sel_hi:[1,0,1] neg_lo:[1,0,0] neg_hi:[1,0,0]
	v_pk_fma_f32 v[8:9], v[26:27], v[12:13], v[50:51] op_sel_hi:[1,0,1] neg_lo:[1,0,0] neg_hi:[1,0,0]
	ds_read_b128 v[88:91], v10 offset:63744
	ds_read_b128 v[96:99], v10 offset:64256
	ds_read_b128 v[92:95], v10 offset:64000
	s_waitcnt lgkmcnt(3)
	v_fma_mix_f32 v12, v6, v36, v180 op_sel_hi:[0,1,0]
	v_fma_mix_f32 v12, v7, v36, v12 op_sel:[0,1,0] op_sel_hi:[0,1,0]
	v_fma_mix_f32 v12, v8, v37, v12 op_sel_hi:[0,1,0]
	v_fma_mix_f32 v12, v9, v37, v12 op_sel:[0,1,0] op_sel_hi:[0,1,0]
	v_fma_mix_f32 v103, v6, v22, v180 op_sel_hi:[0,1,0]
	v_fma_mix_f32 v103, v7, v22, v103 op_sel:[0,1,0] op_sel_hi:[0,1,0]
	v_add_f32_dpp v12, v12, v12 row_ror:1 row_mask:0xf bank_mask:0xf bound_ctrl:1
	v_fma_mix_f32 v103, v8, v23, v103 op_sel_hi:[0,1,0]
	v_fma_mix_f32 v103, v9, v23, v103 op_sel:[0,1,0] op_sel_hi:[0,1,0]
	v_add_f32_dpp v12, v12, v12 row_ror:2 row_mask:0xf bank_mask:0xf bound_ctrl:1
	v_pk_fma_f32 v[48:49], v[44:45], v[70:71], v[6:7] op_sel:[0,1,0]
	v_pk_fma_f32 v[50:51], v[46:47], v[70:71], v[8:9] op_sel:[0,1,0]
	v_add_f32_dpp v12, v12, v12 row_ror:4 row_mask:0xf bank_mask:0xf bound_ctrl:1
	s_nop 1
	v_add_f32_dpp v12, v12, v12 row_ror:8 row_mask:0xf bank_mask:0xf bound_ctrl:1
	v_pk_fma_f32 v[6:7], v[40:41], v[12:13], v[48:49] op_sel_hi:[1,0,1] neg_lo:[1,0,0] neg_hi:[1,0,0]
	v_pk_fma_f32 v[8:9], v[42:43], v[12:13], v[50:51] op_sel_hi:[1,0,1] neg_lo:[1,0,0] neg_hi:[1,0,0]
	ds_read_b128 v[110:113], v10 offset:64768
	ds_read_b128 v[106:109], v10 offset:64512
	ds_read_b128 v[118:121], v10 offset:65280
	ds_read_b128 v[114:117], v10 offset:65024
	s_waitcnt lgkmcnt(4)
	v_fma_mix_f32 v12, v6, v88, v180 op_sel_hi:[0,1,0]
	v_fma_mix_f32 v12, v7, v88, v12 op_sel:[0,1,0] op_sel_hi:[0,1,0]
	v_fma_mix_f32 v12, v8, v89, v12 op_sel_hi:[0,1,0]
	v_fma_mix_f32 v12, v9, v89, v12 op_sel:[0,1,0] op_sel_hi:[0,1,0]
	v_fma_mix_f32 v104, v6, v38, v180 op_sel_hi:[0,1,0]
	v_fma_mix_f32 v104, v7, v38, v104 op_sel:[0,1,0] op_sel_hi:[0,1,0]
	v_add_f32_dpp v12, v12, v12 row_ror:1 row_mask:0xf bank_mask:0xf bound_ctrl:1
	v_fma_mix_f32 v104, v8, v39, v104 op_sel_hi:[0,1,0]
	v_fma_mix_f32 v104, v9, v39, v104 op_sel:[0,1,0] op_sel_hi:[0,1,0]
	v_add_f32_dpp v12, v12, v12 row_ror:2 row_mask:0xf bank_mask:0xf bound_ctrl:1
	v_pk_fma_f32 v[48:49], v[96:97], v[72:73], v[6:7] op_sel_hi:[1,0,1]
	v_pk_fma_f32 v[50:51], v[98:99], v[72:73], v[8:9] op_sel_hi:[1,0,1]
	v_add_f32_dpp v12, v12, v12 row_ror:4 row_mask:0xf bank_mask:0xf bound_ctrl:1
	s_nop 1
	v_add_f32_dpp v12, v12, v12 row_ror:8 row_mask:0xf bank_mask:0xf bound_ctrl:1
	v_pk_fma_f32 v[6:7], v[92:93], v[12:13], v[48:49] op_sel_hi:[1,0,1] neg_lo:[1,0,0] neg_hi:[1,0,0]
	v_pk_fma_f32 v[8:9], v[94:95], v[12:13], v[50:51] op_sel_hi:[1,0,1] neg_lo:[1,0,0] neg_hi:[1,0,0]
	s_waitcnt lgkmcnt(0)
	s_barrier
	v_xor_b32_e32 v10, 0x10000, v10
	v_xor_b32_e32 v11, 0x1000, v11
	ds_read_b128 v[66:69], v11 offset:0
	ds_read_b128 v[20:23], v10 offset:256
	ds_read_b128 v[28:31], v10 offset:768
	ds_read_b128 v[24:27], v10 offset:512
	ds_read_b128 v[36:39], v10 offset:1280
	ds_read_b128 v[44:47], v10 offset:1792
	ds_read_b128 v[40:43], v10 offset:1536
	v_fma_mix_f32 v12, v6, v110, v180 op_sel_hi:[0,1,0]
	v_fma_mix_f32 v12, v7, v110, v12 op_sel:[0,1,0] op_sel_hi:[0,1,0]
	v_fma_mix_f32 v12, v8, v111, v12 op_sel_hi:[0,1,0]
	v_fma_mix_f32 v12, v9, v111, v12 op_sel:[0,1,0] op_sel_hi:[0,1,0]
	v_fma_mix_f32 v105, v6, v90, v180 op_sel_hi:[0,1,0]
	v_fma_mix_f32 v105, v7, v90, v105 op_sel:[0,1,0] op_sel_hi:[0,1,0]
	v_add_f32_dpp v12, v12, v12 row_ror:1 row_mask:0xf bank_mask:0xf bound_ctrl:1
	v_fma_mix_f32 v105, v8, v91, v105 op_sel_hi:[0,1,0]
	v_fma_mix_f32 v105, v9, v91, v105 op_sel:[0,1,0] op_sel_hi:[0,1,0]
	v_add_f32_dpp v12, v12, v12 row_ror:2 row_mask:0xf bank_mask:0xf bound_ctrl:1
	v_pk_fma_f32 v[48:49], v[118:119], v[72:73], v[6:7] op_sel:[0,1,0]
	v_pk_fma_f32 v[50:51], v[120:121], v[72:73], v[8:9] op_sel:[0,1,0]
	v_add_f32_dpp v12, v12, v12 row_ror:4 row_mask:0xf bank_mask:0xf bound_ctrl:1
	s_nop 1
	v_add_f32_dpp v12, v12, v12 row_ror:8 row_mask:0xf bank_mask:0xf bound_ctrl:1
	v_pk_fma_f32 v[6:7], v[114:115], v[12:13], v[48:49] op_sel_hi:[1,0,1] neg_lo:[1,0,0] neg_hi:[1,0,0]
	v_pk_fma_f32 v[8:9], v[116:117], v[12:13], v[50:51] op_sel_hi:[1,0,1] neg_lo:[1,0,0] neg_hi:[1,0,0]
	v_pk_mul_f32 v[6:7], v[6:7], v[106:107]
	v_pk_mul_f32 v[8:9], v[8:9], v[108:109]
	v_fma_mix_f32 v61, v6, v112, v180 op_sel_hi:[0,1,0]
	v_fma_mix_f32 v61, v7, v112, v61 op_sel:[0,1,0] op_sel_hi:[0,1,0]
	v_fma_mix_f32 v61, v8, v113, v61 op_sel_hi:[0,1,0]
	v_fma_mix_f32 v61, v9, v113, v61 op_sel:[0,1,0] op_sel_hi:[0,1,0]
	v_add_f32_dpp v83, v83, v83 row_ror:8 row_mask:0xf bank_mask:0xc
	v_add_f32_dpp v83, v52, v52 row_ror:8 row_mask:0xf bank_mask:0x3
	v_add_f32_dpp v100, v100, v100 row_ror:8 row_mask:0xf bank_mask:0xc
	v_add_f32_dpp v100, v53, v53 row_ror:8 row_mask:0xf bank_mask:0x3
	v_add_f32_dpp v101, v101, v101 row_ror:8 row_mask:0xf bank_mask:0xc
	v_add_f32_dpp v101, v54, v54 row_ror:8 row_mask:0xf bank_mask:0x3
	v_add_f32_dpp v102, v102, v102 row_ror:8 row_mask:0xf bank_mask:0xc
	v_add_f32_dpp v102, v55, v55 row_ror:8 row_mask:0xf bank_mask:0x3
	v_add_f32_dpp v103, v103, v103 row_ror:8 row_mask:0xf bank_mask:0xc
	v_add_f32_dpp v103, v56, v56 row_ror:8 row_mask:0xf bank_mask:0x3
	v_add_f32_dpp v104, v104, v104 row_ror:8 row_mask:0xf bank_mask:0xc
	v_add_f32_dpp v104, v57, v57 row_ror:8 row_mask:0xf bank_mask:0x3
	v_add_f32_dpp v105, v105, v105 row_ror:8 row_mask:0xf bank_mask:0xc
	v_add_f32_dpp v105, v81, v81 row_ror:8 row_mask:0xf bank_mask:0x3
	v_add_f32_dpp v61, v61, v61 row_ror:8 row_mask:0xf bank_mask:0xc
	v_add_f32_dpp v61, v82, v82 row_ror:8 row_mask:0xf bank_mask:0x3
	v_add_f32_dpp v103, v103, v103 row_ror:4 row_mask:0xf bank_mask:0xa
	v_add_f32_dpp v103, v83, v83 row_ror:12 row_mask:0xf bank_mask:0x5
	v_add_f32_dpp v104, v104, v104 row_ror:4 row_mask:0xf bank_mask:0xa
	v_add_f32_dpp v104, v100, v100 row_ror:12 row_mask:0xf bank_mask:0x5
	v_add_f32_dpp v105, v105, v105 row_ror:4 row_mask:0xf bank_mask:0xa
	v_add_f32_dpp v105, v101, v101 row_ror:12 row_mask:0xf bank_mask:0x5
	v_add_f32_dpp v61, v61, v61 row_ror:4 row_mask:0xf bank_mask:0xa
	v_add_f32_dpp v61, v102, v102 row_ror:12 row_mask:0xf bank_mask:0x5
	v_cndmask_b32_e64 v62, v105, v103, s[38:39]
	v_cndmask_b32_e64 v63, v103, v105, s[38:39]
	v_cndmask_b32_e64 v64, v61, v104, s[38:39]
	v_cndmask_b32_e64 v65, v104, v61, s[38:39]
	v_add_f32_dpp v62, v63, v62 quad_perm:[2,3,0,1] row_mask:0xf bank_mask:0xf bound_ctrl:1
	s_nop 0
	v_add_f32_dpp v63, v65, v64 quad_perm:[2,3,0,1] row_mask:0xf bank_mask:0xf bound_ctrl:1
	v_cndmask_b32_e64 v65, v63, v62, s[40:41]
	v_cndmask_b32_e64 v62, v62, v63, s[40:41]
	s_nop 1
	v_add_f32_dpp v62, v62, v65 quad_perm:[1,0,3,2] row_mask:0xf bank_mask:0xf bound_ctrl:1
	v_cvt_pk_bf16_f32 v62, v62, v62
	global_store_short v[2:3], v62, off
	s_cmp_lg_u32 s28, 0x800000
	s_cbranch_scc1 .Lscan_cons_chunk
	s_branch .LBB0_53
.LBB0_59:
	v_readlane_b32 s10, v241, 22
	v_readlane_b32 s11, v241, 23
	v_or_b32_e32 v66, s37, v14
	v_lshlrev_b32_e32 v66, 2, v66
	s_and_b64 s[16:17], s[42:43], exec
	s_mov_b32 s12, 0x10000
	s_cselect_b32 s12, s12, 0xffff0000
	s_movk_i32 s13, 0x400
	s_cselect_b32 s13, s13, 0xfffffc00
	s_cselect_b32 s4, 0, 0x2000000
	s_add_u32 s28, s30, 0xaaf0000
	s_addc_u32 s29, s31, 0
	s_add_u32 s28, s28, s4
	s_addc_u32 s29, s29, 0
	s_add_u32 s34, s28, 0x4000000
	s_addc_u32 s35, s29, 0
	s_add_u32 s8, s30, 0x19af0000
	s_addc_u32 s9, s31, 0
	s_add_u32 s14, s30, 0x17af0000
	s_addc_u32 s15, s31, 0
	global_load_dwordx4 v[106:109], v66, s[10:11]
	v_lshlrev_b32_e32 v67, 2, v61
	v_sub_u32_e32 v68, 0x1fff, v67
	v_cndmask_b32_e64 v67, v68, v67, s[42:43]
	v_add_u32_e32 v67, s80, v67
	v_lshlrev_b32_e32 v67, 10, v67
	v_or_b32_e32 v68, s37, v14
	v_lshl_add_u32 v110, v68, 1, v67
	s_lshl_b32 s5, s64, 4
	s_add_i32 s5, s5, s37
	v_add_u32_e32 v68, s5, v15
	v_lshl_add_u32 v114, v68, 1, v67
	v_add_u32_e32 v111, s13, v110
	v_add_u32_e32 v115, s13, v114
	v_add_u32_e32 v112, s13, v111
	v_add_u32_e32 v116, s13, v115
	v_add_u32_e32 v113, s13, v112
	v_add_u32_e32 v117, s13, v116
	v_lshlrev_b32_e32 v119, 12, v61
	v_lshl_or_b32 v119, v15, 4, v119
	v_lshlrev_b32_e32 v123, 8, v61
	v_lshl_or_b32 v123, v15, 4, v123
	v_add_u32_e32 v123, 0x22000, v123
	global_load_dwordx2 v[16:17], v110, s[44:45]
	global_load_dwordx2 v[18:19], v110, s[46:47]
	global_load_dwordx2 v[20:21], v110, s[8:9]
	global_load_dwordx2 v[22:23], v110, s[34:35]
	global_load_dwordx2 v[24:25], v110, s[28:29]
	global_load_ushort v26, v114, s[14:15]
	global_load_dwordx2 v[28:29], v111, s[44:45]
	global_load_dwordx2 v[30:31], v111, s[46:47]
	global_load_dwordx2 v[32:33], v111, s[8:9]
	global_load_dwordx2 v[34:35], v111, s[34:35]
	global_load_dwordx2 v[36:37], v111, s[28:29]
	global_load_ushort v38, v115, s[14:15]
	global_load_dwordx2 v[40:41], v112, s[44:45]
	global_load_dwordx2 v[42:43], v112, s[46:47]
	global_load_dwordx2 v[44:45], v112, s[8:9]
	global_load_dwordx2 v[46:47], v112, s[34:35]
	global_load_dwordx2 v[48:49], v112, s[28:29]
	global_load_ushort v50, v116, s[14:15]
	global_load_dwordx2 v[52:53], v113, s[44:45]
	global_load_dwordx2 v[54:55], v113, s[46:47]
	global_load_dwordx2 v[56:57], v113, s[8:9]
	global_load_dwordx2 v[58:59], v113, s[34:35]
	global_load_dwordx2 v[60:61], v113, s[28:29]
	global_load_ushort v62, v117, s[14:15]
	v_add_u32_e32 v110, s12, v110
	v_add_u32_e32 v114, s12, v114
	v_add_u32_e32 v111, s12, v111
	v_add_u32_e32 v115, s12, v115
	v_add_u32_e32 v112, s12, v112
	v_add_u32_e32 v116, s12, v116
	v_add_u32_e32 v113, s12, v113
	v_add_u32_e32 v117, s12, v117
	s_waitcnt vmcnt(0)
	v_cvt_f32_f16_e32 v124, v24
	v_cvt_f32_f16_sdwa v125, v24 dst_sel:DWORD dst_unused:UNUSED_PAD src0_sel:WORD_1
	v_cvt_f32_f16_e32 v126, v25
	v_cvt_f32_f16_sdwa v127, v25 dst_sel:DWORD dst_unused:UNUSED_PAD src0_sel:WORD_1
	v_cvt_f32_f16_e32 v128, v36
	v_cvt_f32_f16_sdwa v129, v36 dst_sel:DWORD dst_unused:UNUSED_PAD src0_sel:WORD_1
	v_cvt_f32_f16_e32 v130, v37
	v_cvt_f32_f16_sdwa v131, v37 dst_sel:DWORD dst_unused:UNUSED_PAD src0_sel:WORD_1
	v_cvt_f32_f16_e32 v132, v48
	v_cvt_f32_f16_sdwa v133, v48 dst_sel:DWORD dst_unused:UNUSED_PAD src0_sel:WORD_1
	v_cvt_f32_f16_e32 v134, v49
	v_cvt_f32_f16_sdwa v135, v49 dst_sel:DWORD dst_unused:UNUSED_PAD src0_sel:WORD_1
	v_cvt_f32_f16_e32 v136, v60
	v_cvt_f32_f16_sdwa v137, v60 dst_sel:DWORD dst_unused:UNUSED_PAD src0_sel:WORD_1
	v_cvt_f32_f16_e32 v138, v61
	v_cvt_f32_f16_sdwa v139, v61 dst_sel:DWORD dst_unused:UNUSED_PAD src0_sel:WORD_1
	v_pk_add_f32 v[128:129], v[128:129], v[124:125]
	v_pk_add_f32 v[130:131], v[130:131], v[126:127]
	v_pk_add_f32 v[132:133], v[132:133], v[128:129]
	v_pk_add_f32 v[134:135], v[134:135], v[130:131]
	v_pk_add_f32 v[136:137], v[136:137], v[132:133]
	v_pk_add_f32 v[138:139], v[138:139], v[134:135]
	v_exp_f32_e64 v140, -v124
	v_exp_f32_e64 v141, -v125
	v_exp_f32_e64 v142, -v126
	v_exp_f32_e64 v143, -v127
	v_exp_f32_e64 v144, -v128
	v_exp_f32_e64 v145, -v129
	v_exp_f32_e64 v146, -v130
	v_exp_f32_e64 v147, -v131
	v_exp_f32_e64 v148, -v132
	v_exp_f32_e64 v149, -v133
	v_exp_f32_e64 v150, -v134
	v_exp_f32_e64 v151, -v135
	v_exp_f32_e64 v152, -v136
	v_exp_f32_e64 v153, -v137
	v_exp_f32_e64 v154, -v138
	v_exp_f32_e64 v155, -v139
	v_exp_f32_e32 v156, v124
	v_exp_f32_e32 v157, v125
	v_exp_f32_e32 v158, v126
	v_exp_f32_e32 v159, v127
	v_exp_f32_e32 v160, v128
	v_exp_f32_e32 v161, v129
	v_exp_f32_e32 v162, v130
	v_exp_f32_e32 v163, v131
	v_exp_f32_e32 v164, v132
	v_exp_f32_e32 v165, v133
	v_exp_f32_e32 v166, v134
	v_exp_f32_e32 v167, v135
	v_exp_f32_e32 v168, v136
	v_exp_f32_e32 v169, v137
	v_exp_f32_e32 v170, v138
	v_exp_f32_e32 v171, v139
	v_cvt_f32_f16_e32 v68, v22
	v_cvt_f32_f16_sdwa v69, v22 dst_sel:DWORD dst_unused:UNUSED_PAD src0_sel:WORD_1
	v_cvt_f32_f16_e32 v70, v23
	v_cvt_f32_f16_sdwa v71, v23 dst_sel:DWORD dst_unused:UNUSED_PAD src0_sel:WORD_1
	v_lshlrev_b32_e32 v72, 16, v20
	v_and_b32_e32 v73, 0xffff0000, v20
	v_lshlrev_b32_e32 v74, 16, v21
	v_and_b32_e32 v75, 0xffff0000, v21
	v_lshlrev_b32_e32 v76, 16, v18
	v_and_b32_e32 v77, 0xffff0000, v18
	v_lshlrev_b32_e32 v78, 16, v19
	v_and_b32_e32 v79, 0xffff0000, v19
	v_lshlrev_b32_e32 v80, 16, v16
	v_and_b32_e32 v81, 0xffff0000, v16
	v_lshlrev_b32_e32 v82, 16, v17
	v_and_b32_e32 v83, 0xffff0000, v17
	v_pk_mul_f32 v[84:85], v[72:73], v[68:69]
	v_pk_mul_f32 v[86:87], v[74:75], v[70:71]
	v_pk_add_f32 v[88:89], v[68:69], -1.0 op_sel_hi:[1,0]
	v_pk_add_f32 v[90:91], v[70:71], -1.0 op_sel_hi:[1,0]
	v_pk_fma_f32 v[88:89], v[106:107], v[88:89], 1.0 op_sel_hi:[1,1,0]
	v_pk_fma_f32 v[90:91], v[108:109], v[90:91], 1.0 op_sel_hi:[1,1,0]
	v_pk_mul_f32 v[84:85], v[84:85], v[156:157]
	v_pk_mul_f32 v[86:87], v[86:87], v[158:159]
	v_pk_mul_f32 v[88:89], v[88:89], v[76:77]
	v_pk_mul_f32 v[90:91], v[90:91], v[78:79]
	ds_write_b128 v119, v[84:87] offset:512
	v_pk_mul_f32 v[88:89], v[88:89], v[156:157]
	v_pk_mul_f32 v[90:91], v[90:91], v[158:159]
	v_pk_mul_f32 v[80:81], v[80:81], v[140:141]
	v_pk_mul_f32 v[82:83], v[82:83], v[142:143]
	ds_write_b128 v119, v[88:91] offset:768
	v_lshlrev_b32_e32 v96, 16, v26
	v_cvt_pk_f16_f32 v92, v72, v73
	v_cvt_pk_f16_f32 v93, v74, v75
	v_cvt_pk_f16_f32 v94, v80, v81
	v_cvt_pk_f16_f32 v95, v82, v83
	ds_write_b128 v119, v[92:95] offset:256
	v_cvt_f32_f16_e32 v68, v34
	v_cvt_f32_f16_sdwa v69, v34 dst_sel:DWORD dst_unused:UNUSED_PAD src0_sel:WORD_1
	v_cvt_f32_f16_e32 v70, v35
	v_cvt_f32_f16_sdwa v71, v35 dst_sel:DWORD dst_unused:UNUSED_PAD src0_sel:WORD_1
	v_lshlrev_b32_e32 v72, 16, v32
	v_and_b32_e32 v73, 0xffff0000, v32
	v_lshlrev_b32_e32 v74, 16, v33
	v_and_b32_e32 v75, 0xffff0000, v33
	v_lshlrev_b32_e32 v76, 16, v30
	v_and_b32_e32 v77, 0xffff0000, v30
	v_lshlrev_b32_e32 v78, 16, v31
	v_and_b32_e32 v79, 0xffff0000, v31
	v_lshlrev_b32_e32 v80, 16, v28
	v_and_b32_e32 v81, 0xffff0000, v28
	v_lshlrev_b32_e32 v82, 16, v29
	v_and_b32_e32 v83, 0xffff0000, v29
	v_pk_mul_f32 v[84:85], v[72:73], v[68:69]
	v_pk_mul_f32 v[86:87], v[74:75], v[70:71]
	v_pk_add_f32 v[88:89], v[68:69], -1.0 op_sel_hi:[1,0]
	v_pk_add_f32 v[90:91], v[70:71], -1.0 op_sel_hi:[1,0]
	v_pk_fma_f32 v[88:89], v[106:107], v[88:89], 1.0 op_sel_hi:[1,1,0]
	v_pk_fma_f32 v[90:91], v[108:109], v[90:91], 1.0 op_sel_hi:[1,1,0]
	v_pk_mul_f32 v[84:85], v[84:85], v[160:161]
	v_pk_mul_f32 v[86:87], v[86:87], v[162:163]
	v_pk_mul_f32 v[88:89], v[88:89], v[76:77]
	v_pk_mul_f32 v[90:91], v[90:91], v[78:79]
	ds_write_b128 v119, v[84:87] offset:1536
	v_pk_mul_f32 v[88:89], v[88:89], v[160:161]
	v_pk_mul_f32 v[90:91], v[90:91], v[162:163]
	v_pk_mul_f32 v[72:73], v[72:73], v[140:141]
	v_pk_mul_f32 v[74:75], v[74:75], v[142:143]
	v_pk_mul_f32 v[80:81], v[80:81], v[144:145]
	v_pk_mul_f32 v[82:83], v[82:83], v[146:147]
	ds_write_b128 v119, v[88:91] offset:1792
	v_lshlrev_b32_e32 v97, 16, v38
	v_cvt_pk_f16_f32 v92, v72, v73
	v_cvt_pk_f16_f32 v93, v74, v75
	v_cvt_pk_f16_f32 v94, v80, v81
	v_cvt_pk_f16_f32 v95, v82, v83
	ds_write_b128 v119, v[92:95] offset:1280
	v_cvt_f32_f16_e32 v68, v46
	v_cvt_f32_f16_sdwa v69, v46 dst_sel:DWORD dst_unused:UNUSED_PAD src0_sel:WORD_1
	v_cvt_f32_f16_e32 v70, v47
	v_cvt_f32_f16_sdwa v71, v47 dst_sel:DWORD dst_unused:UNUSED_PAD src0_sel:WORD_1
	v_lshlrev_b32_e32 v72, 16, v44
	v_and_b32_e32 v73, 0xffff0000, v44
	v_lshlrev_b32_e32 v74, 16, v45
	v_and_b32_e32 v75, 0xffff0000, v45
	v_lshlrev_b32_e32 v76, 16, v42
	v_and_b32_e32 v77, 0xffff0000, v42
	v_lshlrev_b32_e32 v78, 16, v43
	v_and_b32_e32 v79, 0xffff0000, v43
	v_lshlrev_b32_e32 v80, 16, v40
	v_and_b32_e32 v81, 0xffff0000, v40
	v_lshlrev_b32_e32 v82, 16, v41
	v_and_b32_e32 v83, 0xffff0000, v41
	v_pk_mul_f32 v[84:85], v[72:73], v[68:69]
	v_pk_mul_f32 v[86:87], v[74:75], v[70:71]
	v_pk_add_f32 v[88:89], v[68:69], -1.0 op_sel_hi:[1,0]
	v_pk_add_f32 v[90:91], v[70:71], -1.0 op_sel_hi:[1,0]
	v_pk_fma_f32 v[88:89], v[106:107], v[88:89], 1.0 op_sel_hi:[1,1,0]
	v_pk_fma_f32 v[90:91], v[108:109], v[90:91], 1.0 op_sel_hi:[1,1,0]
	v_pk_mul_f32 v[84:85], v[84:85], v[164:165]
	v_pk_mul_f32 v[86:87], v[86:87], v[166:167]
	v_pk_mul_f32 v[88:89], v[88:89], v[76:77]
	v_pk_mul_f32 v[90:91], v[90:91], v[78:79]
	ds_write_b128 v119, v[84:87] offset:2560
	v_pk_mul_f32 v[88:89], v[88:89], v[164:165]
	v_pk_mul_f32 v[90:91], v[90:91], v[166:167]
	v_pk_mul_f32 v[72:73], v[72:73], v[144:145]
	v_pk_mul_f32 v[74:75], v[74:75], v[146:147]
	v_pk_mul_f32 v[80:81], v[80:81], v[148:149]
	v_pk_mul_f32 v[82:83], v[82:83], v[150:151]
	ds_write_b128 v119, v[88:91] offset:2816
	v_lshlrev_b32_e32 v98, 16, v50
	v_cvt_pk_f16_f32 v92, v72, v73
	v_cvt_pk_f16_f32 v93, v74, v75
	v_cvt_pk_f16_f32 v94, v80, v81
	v_cvt_pk_f16_f32 v95, v82, v83
	ds_write_b128 v119, v[92:95] offset:2304
	v_cvt_f32_f16_e32 v68, v58
	v_cvt_f32_f16_sdwa v69, v58 dst_sel:DWORD dst_unused:UNUSED_PAD src0_sel:WORD_1
	v_cvt_f32_f16_e32 v70, v59
	v_cvt_f32_f16_sdwa v71, v59 dst_sel:DWORD dst_unused:UNUSED_PAD src0_sel:WORD_1
	v_lshlrev_b32_e32 v72, 16, v56
	v_and_b32_e32 v73, 0xffff0000, v56
	v_lshlrev_b32_e32 v74, 16, v57
	v_and_b32_e32 v75, 0xffff0000, v57
	v_lshlrev_b32_e32 v76, 16, v54
	v_and_b32_e32 v77, 0xffff0000, v54
	v_lshlrev_b32_e32 v78, 16, v55
	v_and_b32_e32 v79, 0xffff0000, v55
	v_lshlrev_b32_e32 v80, 16, v52
	v_and_b32_e32 v81, 0xffff0000, v52
	v_lshlrev_b32_e32 v82, 16, v53
	v_and_b32_e32 v83, 0xffff0000, v53
	v_pk_mul_f32 v[84:85], v[72:73], v[68:69]
	v_pk_mul_f32 v[86:87], v[74:75], v[70:71]
	v_pk_add_f32 v[88:89], v[68:69], -1.0 op_sel_hi:[1,0]
	v_pk_add_f32 v[90:91], v[70:71], -1.0 op_sel_hi:[1,0]
	v_pk_fma_f32 v[88:89], v[106:107], v[88:89], 1.0 op_sel_hi:[1,1,0]
	v_pk_fma_f32 v[90:91], v[108:109], v[90:91], 1.0 op_sel_hi:[1,1,0]
	v_pk_mul_f32 v[84:85], v[84:85], v[168:169]
	v_pk_mul_f32 v[86:87], v[86:87], v[170:171]
	v_pk_mul_f32 v[88:89], v[88:89], v[76:77]
	v_pk_mul_f32 v[90:91], v[90:91], v[78:79]
	ds_write_b128 v119, v[84:87] offset:3584
	v_pk_mul_f32 v[88:89], v[88:89], v[168:169]
	v_pk_mul_f32 v[90:91], v[90:91], v[170:171]
	v_pk_mul_f32 v[72:73], v[72:73], v[148:149]
	v_pk_mul_f32 v[74:75], v[74:75], v[150:151]
	ds_write_b128 v119, v[88:91] offset:3840
	v_lshlrev_b32_e32 v99, 16, v62
	v_cvt_pk_f16_f32 v92, v72, v73
	v_cvt_pk_f16_f32 v93, v74, v75
	v_cvt_pk_f16_f32 v94, v80, v81
	v_cvt_pk_f16_f32 v95, v82, v83
	ds_write_b128 v119, v[92:95] offset:3328
	ds_write_b128 v119, v[152:155] offset:3072
	ds_write_b128 v123, v[96:99]
	global_load_dwordx2 v[16:17], v110, s[44:45]
	global_load_dwordx2 v[18:19], v110, s[46:47]
	global_load_dwordx2 v[20:21], v110, s[8:9]
	global_load_dwordx2 v[22:23], v110, s[34:35]
	global_load_dwordx2 v[24:25], v110, s[28:29]
	global_load_ushort v26, v114, s[14:15]
	global_load_dwordx2 v[28:29], v111, s[44:45]
	global_load_dwordx2 v[30:31], v111, s[46:47]
	global_load_dwordx2 v[32:33], v111, s[8:9]
	global_load_dwordx2 v[34:35], v111, s[34:35]
	global_load_dwordx2 v[36:37], v111, s[28:29]
	global_load_ushort v38, v115, s[14:15]
	global_load_dwordx2 v[40:41], v112, s[44:45]
	global_load_dwordx2 v[42:43], v112, s[46:47]
	global_load_dwordx2 v[44:45], v112, s[8:9]
	global_load_dwordx2 v[46:47], v112, s[34:35]
	global_load_dwordx2 v[48:49], v112, s[28:29]
	global_load_ushort v50, v116, s[14:15]
	global_load_dwordx2 v[52:53], v113, s[44:45]
	global_load_dwordx2 v[54:55], v113, s[46:47]
	global_load_dwordx2 v[56:57], v113, s[8:9]
	global_load_dwordx2 v[58:59], v113, s[34:35]
	global_load_dwordx2 v[60:61], v113, s[28:29]
	global_load_ushort v62, v117, s[14:15]
	v_add_u32_e32 v110, s12, v110
	v_add_u32_e32 v114, s12, v114
	v_add_u32_e32 v111, s12, v111
	v_add_u32_e32 v115, s12, v115
	v_add_u32_e32 v112, s12, v112
	v_add_u32_e32 v116, s12, v116
	v_add_u32_e32 v113, s12, v113
	v_add_u32_e32 v117, s12, v117
	s_waitcnt lgkmcnt(0)
	s_barrier
	s_mov_b32 s6, 0
.Lprod_loop:
	s_cmp_eq_u32 s6, 0x7f
	s_cbranch_scc1 .Lprod_bar
	v_xor_b32_e32 v119, 0x10000, v119
	v_xor_b32_e32 v123, 0x1000, v123
	s_waitcnt vmcnt(0)
	v_cvt_f32_f16_e32 v124, v24
	v_cvt_f32_f16_sdwa v125, v24 dst_sel:DWORD dst_unused:UNUSED_PAD src0_sel:WORD_1
	v_cvt_f32_f16_e32 v126, v25
	v_cvt_f32_f16_sdwa v127, v25 dst_sel:DWORD dst_unused:UNUSED_PAD src0_sel:WORD_1
	v_cvt_f32_f16_e32 v128, v36
	v_cvt_f32_f16_sdwa v129, v36 dst_sel:DWORD dst_unused:UNUSED_PAD src0_sel:WORD_1
	v_cvt_f32_f16_e32 v130, v37
	v_cvt_f32_f16_sdwa v131, v37 dst_sel:DWORD dst_unused:UNUSED_PAD src0_sel:WORD_1
	v_cvt_f32_f16_e32 v132, v48
	v_cvt_f32_f16_sdwa v133, v48 dst_sel:DWORD dst_unused:UNUSED_PAD src0_sel:WORD_1
	v_cvt_f32_f16_e32 v134, v49
	v_cvt_f32_f16_sdwa v135, v49 dst_sel:DWORD dst_unused:UNUSED_PAD src0_sel:WORD_1
	v_cvt_f32_f16_e32 v136, v60
	v_cvt_f32_f16_sdwa v137, v60 dst_sel:DWORD dst_unused:UNUSED_PAD src0_sel:WORD_1
	v_cvt_f32_f16_e32 v138, v61
	v_cvt_f32_f16_sdwa v139, v61 dst_sel:DWORD dst_unused:UNUSED_PAD src0_sel:WORD_1
	v_pk_add_f32 v[128:129], v[128:129], v[124:125]
	v_pk_add_f32 v[130:131], v[130:131], v[126:127]
	v_pk_add_f32 v[132:133], v[132:133], v[128:129]
	v_pk_add_f32 v[134:135], v[134:135], v[130:131]
	v_pk_add_f32 v[136:137], v[136:137], v[132:133]
	v_pk_add_f32 v[138:139], v[138:139], v[134:135]
	v_exp_f32_e64 v140, -v124
	v_exp_f32_e64 v141, -v125
	v_exp_f32_e64 v142, -v126
	v_exp_f32_e64 v143, -v127
	v_exp_f32_e64 v144, -v128
	v_exp_f32_e64 v145, -v129
	v_exp_f32_e64 v146, -v130
	v_exp_f32_e64 v147, -v131
	v_exp_f32_e64 v148, -v132
	v_exp_f32_e64 v149, -v133
	v_exp_f32_e64 v150, -v134
	v_exp_f32_e64 v151, -v135
	v_exp_f32_e64 v152, -v136
	v_exp_f32_e64 v153, -v137
	v_exp_f32_e64 v154, -v138
	v_exp_f32_e64 v155, -v139
	v_exp_f32_e32 v156, v124
	v_exp_f32_e32 v157, v125
	v_exp_f32_e32 v158, v126
	v_exp_f32_e32 v159, v127
	v_exp_f32_e32 v160, v128
	v_exp_f32_e32 v161, v129
	v_exp_f32_e32 v162, v130
	v_exp_f32_e32 v163, v131
	v_exp_f32_e32 v164, v132
	v_exp_f32_e32 v165, v133
	v_exp_f32_e32 v166, v134
	v_exp_f32_e32 v167, v135
	v_exp_f32_e32 v168, v136
	v_exp_f32_e32 v169, v137
	v_exp_f32_e32 v170, v138
	v_exp_f32_e32 v171, v139
	v_cvt_f32_f16_e32 v68, v22
	v_cvt_f32_f16_sdwa v69, v22 dst_sel:DWORD dst_unused:UNUSED_PAD src0_sel:WORD_1
	v_cvt_f32_f16_e32 v70, v23
	v_cvt_f32_f16_sdwa v71, v23 dst_sel:DWORD dst_unused:UNUSED_PAD src0_sel:WORD_1
	v_lshlrev_b32_e32 v72, 16, v20
	v_and_b32_e32 v73, 0xffff0000, v20
	v_lshlrev_b32_e32 v74, 16, v21
	v_and_b32_e32 v75, 0xffff0000, v21
	v_lshlrev_b32_e32 v76, 16, v18
	v_and_b32_e32 v77, 0xffff0000, v18
	v_lshlrev_b32_e32 v78, 16, v19
	v_and_b32_e32 v79, 0xffff0000, v19
	v_lshlrev_b32_e32 v80, 16, v16
	v_and_b32_e32 v81, 0xffff0000, v16
	v_lshlrev_b32_e32 v82, 16, v17
	v_and_b32_e32 v83, 0xffff0000, v17
	v_pk_mul_f32 v[84:85], v[72:73], v[68:69]
	v_pk_mul_f32 v[86:87], v[74:75], v[70:71]
	v_pk_add_f32 v[88:89], v[68:69], -1.0 op_sel_hi:[1,0]
	v_pk_add_f32 v[90:91], v[70:71], -1.0 op_sel_hi:[1,0]
	v_pk_fma_f32 v[88:89], v[106:107], v[88:89], 1.0 op_sel_hi:[1,1,0]
	v_pk_fma_f32 v[90:91], v[108:109], v[90:91], 1.0 op_sel_hi:[1,1,0]
	v_pk_mul_f32 v[84:85], v[84:85], v[156:157]
	v_pk_mul_f32 v[86:87], v[86:87], v[158:159]
	v_pk_mul_f32 v[88:89], v[88:89], v[76:77]
	v_pk_mul_f32 v[90:91], v[90:91], v[78:79]
	ds_write_b128 v119, v[84:87] offset:512
	v_pk_mul_f32 v[88:89], v[88:89], v[156:157]
	v_pk_mul_f32 v[90:91], v[90:91], v[158:159]
	v_pk_mul_f32 v[80:81], v[80:81], v[140:141]
	v_pk_mul_f32 v[82:83], v[82:83], v[142:143]
	ds_write_b128 v119, v[88:91] offset:768
	v_lshlrev_b32_e32 v96, 16, v26
	v_cvt_pk_f16_f32 v92, v72, v73
	v_cvt_pk_f16_f32 v93, v74, v75
	v_cvt_pk_f16_f32 v94, v80, v81
	v_cvt_pk_f16_f32 v95, v82, v83
	ds_write_b128 v119, v[92:95] offset:256
	v_cvt_f32_f16_e32 v68, v34
	v_cvt_f32_f16_sdwa v69, v34 dst_sel:DWORD dst_unused:UNUSED_PAD src0_sel:WORD_1
	v_cvt_f32_f16_e32 v70, v35
	v_cvt_f32_f16_sdwa v71, v35 dst_sel:DWORD dst_unused:UNUSED_PAD src0_sel:WORD_1
	v_lshlrev_b32_e32 v72, 16, v32
	v_and_b32_e32 v73, 0xffff0000, v32
	v_lshlrev_b32_e32 v74, 16, v33
	v_and_b32_e32 v75, 0xffff0000, v33
	v_lshlrev_b32_e32 v76, 16, v30
	v_and_b32_e32 v77, 0xffff0000, v30
	v_lshlrev_b32_e32 v78, 16, v31
	v_and_b32_e32 v79, 0xffff0000, v31
	v_lshlrev_b32_e32 v80, 16, v28
	v_and_b32_e32 v81, 0xffff0000, v28
	v_lshlrev_b32_e32 v82, 16, v29
	v_and_b32_e32 v83, 0xffff0000, v29
	v_pk_mul_f32 v[84:85], v[72:73], v[68:69]
	v_pk_mul_f32 v[86:87], v[74:75], v[70:71]
	v_pk_add_f32 v[88:89], v[68:69], -1.0 op_sel_hi:[1,0]
	v_pk_add_f32 v[90:91], v[70:71], -1.0 op_sel_hi:[1,0]
	v_pk_fma_f32 v[88:89], v[106:107], v[88:89], 1.0 op_sel_hi:[1,1,0]
	v_pk_fma_f32 v[90:91], v[108:109], v[90:91], 1.0 op_sel_hi:[1,1,0]
	v_pk_mul_f32 v[84:85], v[84:85], v[160:161]
	v_pk_mul_f32 v[86:87], v[86:87], v[162:163]
	v_pk_mul_f32 v[88:89], v[88:89], v[76:77]
	v_pk_mul_f32 v[90:91], v[90:91], v[78:79]
	ds_write_b128 v119, v[84:87] offset:1536
	v_pk_mul_f32 v[88:89], v[88:89], v[160:161]
	v_pk_mul_f32 v[90:91], v[90:91], v[162:163]
	v_pk_mul_f32 v[72:73], v[72:73], v[140:141]
	v_pk_mul_f32 v[74:75], v[74:75], v[142:143]
	v_pk_mul_f32 v[80:81], v[80:81], v[144:145]
	v_pk_mul_f32 v[82:83], v[82:83], v[146:147]
	ds_write_b128 v119, v[88:91] offset:1792
	v_lshlrev_b32_e32 v97, 16, v38
	v_cvt_pk_f16_f32 v92, v72, v73
	v_cvt_pk_f16_f32 v93, v74, v75
	v_cvt_pk_f16_f32 v94, v80, v81
	v_cvt_pk_f16_f32 v95, v82, v83
	ds_write_b128 v119, v[92:95] offset:1280
	v_cvt_f32_f16_e32 v68, v46
	v_cvt_f32_f16_sdwa v69, v46 dst_sel:DWORD dst_unused:UNUSED_PAD src0_sel:WORD_1
	v_cvt_f32_f16_e32 v70, v47
	v_cvt_f32_f16_sdwa v71, v47 dst_sel:DWORD dst_unused:UNUSED_PAD src0_sel:WORD_1
	v_lshlrev_b32_e32 v72, 16, v44
	v_and_b32_e32 v73, 0xffff0000, v44
	v_lshlrev_b32_e32 v74, 16, v45
	v_and_b32_e32 v75, 0xffff0000, v45
	v_lshlrev_b32_e32 v76, 16, v42
	v_and_b32_e32 v77, 0xffff0000, v42
	v_lshlrev_b32_e32 v78, 16, v43
	v_and_b32_e32 v79, 0xffff0000, v43
	v_lshlrev_b32_e32 v80, 16, v40
	v_and_b32_e32 v81, 0xffff0000, v40
	v_lshlrev_b32_e32 v82, 16, v41
	v_and_b32_e32 v83, 0xffff0000, v41
	v_pk_mul_f32 v[84:85], v[72:73], v[68:69]
	v_pk_mul_f32 v[86:87], v[74:75], v[70:71]
	v_pk_add_f32 v[88:89], v[68:69], -1.0 op_sel_hi:[1,0]
	v_pk_add_f32 v[90:91], v[70:71], -1.0 op_sel_hi:[1,0]
	v_pk_fma_f32 v[88:89], v[106:107], v[88:89], 1.0 op_sel_hi:[1,1,0]
	v_pk_fma_f32 v[90:91], v[108:109], v[90:91], 1.0 op_sel_hi:[1,1,0]
	v_pk_mul_f32 v[84:85], v[84:85], v[164:165]
	v_pk_mul_f32 v[86:87], v[86:87], v[166:167]
	v_pk_mul_f32 v[88:89], v[88:89], v[76:77]
	v_pk_mul_f32 v[90:91], v[90:91], v[78:79]
	ds_write_b128 v119, v[84:87] offset:2560
	v_pk_mul_f32 v[88:89], v[88:89], v[164:165]
	v_pk_mul_f32 v[90:91], v[90:91], v[166:167]
	v_pk_mul_f32 v[72:73], v[72:73], v[144:145]
	v_pk_mul_f32 v[74:75], v[74:75], v[146:147]
	v_pk_mul_f32 v[80:81], v[80:81], v[148:149]
	v_pk_mul_f32 v[82:83], v[82:83], v[150:151]
	ds_write_b128 v119, v[88:91] offset:2816
	v_lshlrev_b32_e32 v98, 16, v50
	v_cvt_pk_f16_f32 v92, v72, v73
	v_cvt_pk_f16_f32 v93, v74, v75
	v_cvt_pk_f16_f32 v94, v80, v81
	v_cvt_pk_f16_f32 v95, v82, v83
	ds_write_b128 v119, v[92:95] offset:2304
	v_cvt_f32_f16_e32 v68, v58
	v_cvt_f32_f16_sdwa v69, v58 dst_sel:DWORD dst_unused:UNUSED_PAD src0_sel:WORD_1
	v_cvt_f32_f16_e32 v70, v59
	v_cvt_f32_f16_sdwa v71, v59 dst_sel:DWORD dst_unused:UNUSED_PAD src0_sel:WORD_1
	v_lshlrev_b32_e32 v72, 16, v56
	v_and_b32_e32 v73, 0xffff0000, v56
	v_lshlrev_b32_e32 v74, 16, v57
	v_and_b32_e32 v75, 0xffff0000, v57
	v_lshlrev_b32_e32 v76, 16, v54
	v_and_b32_e32 v77, 0xffff0000, v54
	v_lshlrev_b32_e32 v78, 16, v55
	v_and_b32_e32 v79, 0xffff0000, v55
	v_lshlrev_b32_e32 v80, 16, v52
	v_and_b32_e32 v81, 0xffff0000, v52
	v_lshlrev_b32_e32 v82, 16, v53
	v_and_b32_e32 v83, 0xffff0000, v53
	v_pk_mul_f32 v[84:85], v[72:73], v[68:69]
	v_pk_mul_f32 v[86:87], v[74:75], v[70:71]
	v_pk_add_f32 v[88:89], v[68:69], -1.0 op_sel_hi:[1,0]
	v_pk_add_f32 v[90:91], v[70:71], -1.0 op_sel_hi:[1,0]
	v_pk_fma_f32 v[88:89], v[106:107], v[88:89], 1.0 op_sel_hi:[1,1,0]
	v_pk_fma_f32 v[90:91], v[108:109], v[90:91], 1.0 op_sel_hi:[1,1,0]
	v_pk_mul_f32 v[84:85], v[84:85], v[168:169]
	v_pk_mul_f32 v[86:87], v[86:87], v[170:171]
	v_pk_mul_f32 v[88:89], v[88:89], v[76:77]
	v_pk_mul_f32 v[90:91], v[90:91], v[78:79]
	ds_write_b128 v119, v[84:87] offset:3584
	v_pk_mul_f32 v[88:89], v[88:89], v[168:169]
	v_pk_mul_f32 v[90:91], v[90:91], v[170:171]
	v_pk_mul_f32 v[72:73], v[72:73], v[148:149]
	v_pk_mul_f32 v[74:75], v[74:75], v[150:151]
	ds_write_b128 v119, v[88:91] offset:3840
	v_lshlrev_b32_e32 v99, 16, v62
	v_cvt_pk_f16_f32 v92, v72, v73
	v_cvt_pk_f16_f32 v93, v74, v75
	v_cvt_pk_f16_f32 v94, v80, v81
	v_cvt_pk_f16_f32 v95, v82, v83
	ds_write_b128 v119, v[92:95] offset:3328
	ds_write_b128 v119, v[152:155] offset:3072
	ds_write_b128 v123, v[96:99]
	s_cmp_ge_u32 s6, 0x7e
	s_cbranch_scc1 .Lprod_bar
	global_load_dwordx2 v[16:17], v110, s[44:45]
	global_load_dwordx2 v[18:19], v110, s[46:47]
	global_load_dwordx2 v[20:21], v110, s[8:9]
	global_load_dwordx2 v[22:23], v110, s[34:35]
	global_load_dwordx2 v[24:25], v110, s[28:29]
	global_load_ushort v26, v114, s[14:15]
	global_load_dwordx2 v[28:29], v111, s[44:45]
	global_load_dwordx2 v[30:31], v111, s[46:47]
	global_load_dwordx2 v[32:33], v111, s[8:9]
	global_load_dwordx2 v[34:35], v111, s[34:35]
	global_load_dwordx2 v[36:37], v111, s[28:29]
	global_load_ushort v38, v115, s[14:15]
	global_load_dwordx2 v[40:41], v112, s[44:45]
	global_load_dwordx2 v[42:43], v112, s[46:47]
	global_load_dwordx2 v[44:45], v112, s[8:9]
	global_load_dwordx2 v[46:47], v112, s[34:35]
	global_load_dwordx2 v[48:49], v112, s[28:29]
	global_load_ushort v50, v116, s[14:15]
	global_load_dwordx2 v[52:53], v113, s[44:45]
	global_load_dwordx2 v[54:55], v113, s[46:47]
	global_load_dwordx2 v[56:57], v113, s[8:9]
	global_load_dwordx2 v[58:59], v113, s[34:35]
	global_load_dwordx2 v[60:61], v113, s[28:29]
	global_load_ushort v62, v117, s[14:15]
	v_add_u32_e32 v110, s12, v110
	v_add_u32_e32 v114, s12, v114
	v_add_u32_e32 v111, s12, v111
	v_add_u32_e32 v115, s12, v115
	v_add_u32_e32 v112, s12, v112
	v_add_u32_e32 v116, s12, v116
	v_add_u32_e32 v113, s12, v113
	v_add_u32_e32 v117, s12, v117
.Lprod_bar:
	s_waitcnt lgkmcnt(0)
	s_barrier
	s_add_i32 s6, s6, 1
	s_cmp_lt_u32 s6, 0x80
	s_cbranch_scc1 .Lprod_loop
	s_branch .LBB0_52

	.amdhsa_kernel _Z10fwd_kernel6Params
		.amdhsa_group_segment_fixed_size 16384
		.amdhsa_private_segment_fixed_size 0
		.amdhsa_kernarg_size 536
		.amdhsa_user_sgpr_count 2
		.amdhsa_user_sgpr_dispatch_ptr 0
		.amdhsa_user_sgpr_queue_ptr 0
		.amdhsa_user_sgpr_kernarg_segment_ptr 1
		.amdhsa_user_sgpr_dispatch_id 0
		.amdhsa_user_sgpr_kernarg_preload_length 0
		.amdhsa_user_sgpr_kernarg_preload_offset 0
		.amdhsa_user_sgpr_private_segment_size 0
		.amdhsa_uses_dynamic_stack 0
		.amdhsa_enable_private_segment 0
		.amdhsa_system_sgpr_workgroup_id_x 1
		.amdhsa_system_sgpr_workgroup_id_y 0
		.amdhsa_system_sgpr_workgroup_id_z 0
		.amdhsa_system_sgpr_workgroup_info 0
		.amdhsa_system_vgpr_workitem_id 2
		.amdhsa_next_free_vgpr 244
		.amdhsa_next_free_sgpr 102
		.amdhsa_accum_offset 244
		.amdhsa_reserve_vcc 1
		.amdhsa_float_round_mode_32 0
		.amdhsa_float_round_mode_16_64 0
		.amdhsa_float_denorm_mode_32 3
		.amdhsa_float_denorm_mode_16_64 3
		.amdhsa_dx10_clamp 1
		.amdhsa_ieee_mode 1
		.amdhsa_fp16_overflow 0
		.amdhsa_tg_split 0
		.amdhsa_exception_fp_ieee_invalid_op 0
		.amdhsa_exception_fp_denorm_src 0
		.amdhsa_exception_fp_ieee_div_zero 0
		.amdhsa_exception_fp_ieee_overflow 0
		.amdhsa_exception_fp_ieee_underflow 0
		.amdhsa_exception_fp_ieee_inexact 0
		.amdhsa_exception_int_div_zero 0
	.end_amdhsa_kernel

amdhsa.kernels:
  - .agpr_count:     0
    .args:
      - .offset:         0
        .size:           280
        .value_kind:     by_value
      - .offset:         280
        .size:           4
        .value_kind:     hidden_block_count_x
      - .offset:         284
        .size:           4
        .value_kind:     hidden_block_count_y
      - .offset:         288
        .size:           4
        .value_kind:     hidden_block_count_z
      - .offset:         292
        .size:           2
        .value_kind:     hidden_group_size_x
      - .offset:         294
        .size:           2
        .value_kind:     hidden_group_size_y
      - .offset:         296
        .size:           2
        .value_kind:     hidden_group_size_z
      - .offset:         298
        .size:           2
        .value_kind:     hidden_remainder_x
      - .offset:         300
        .size:           2
        .value_kind:     hidden_remainder_y
      - .offset:         302
        .size:           2
        .value_kind:     hidden_remainder_z
      - .offset:         320
        .size:           8
        .value_kind:     hidden_global_offset_x
      - .offset:         328
        .size:           8
        .value_kind:     hidden_global_offset_y
      - .offset:         336
        .size:           8
        .value_kind:     hidden_global_offset_z
      - .offset:         344
        .size:           2
        .value_kind:     hidden_grid_dims
      - .offset:         368
        .size:           8
        .value_kind:     hidden_multigrid_sync_arg
      - .offset:         400
        .size:           4
        .value_kind:     hidden_dynamic_lds_size
    .group_segment_fixed_size: 16384
    .kernarg_segment_align: 8
    .kernarg_segment_size: 536
    .language:       OpenCL C
    .language_version:
      - 2
      - 0
    .max_flat_workgroup_size: 512
    .name:           _Z10fwd_kernel6Params
    .private_segment_fixed_size: 0
    .sgpr_count:     106
    .sgpr_spill_count: 205
    .symbol:         _Z10fwd_kernel6Params.kd
    .uniform_work_group_size: 1
    .uses_dynamic_stack: false
    .vgpr_count:     244
    .vgpr_spill_count: 0
    .wavefront_size: 64
